# GEMM epilogue stores write-through AND non-temporal (sc0 sc1 nt) so output tiles do not displace the re-read A/B operand tiles in L2
# baseline (speedup 1.0000x reference)
.Lg16_proj_k:
	s_add_i32 s3, s1, 2
	s_lshl_b32 s96, s3, 13
	s_add_i32 m0, vcc_lo, 16384
	v_lshl_add_u64 v[160:161], v[188:189], 0, s[96:97]
	global_load_lds_dwordx4 v[160:161], off
	global_load_lds_dwordx4 v[160:161], off offset:1024
	ds_read_b128 v[236:239], v196 offset:0
	ds_read_b128 v[240:243], v162 offset:0
	ds_read_b128 v[244:247], v196 offset:2048
	ds_read_b128 v[248:251], v162 offset:2048
	s_add_i32 s3, s1, 2
	s_lshl_b32 s96, s3, 11
	v_lshl_add_u64 v[198:199], v[184:185], 0, s[96:97]
	v_lshl_add_u64 v[200:201], v[186:187], 0, s[96:97]
	s_waitcnt vmcnt(8) lgkmcnt(3)
	v_mfma_f32_16x16x32_bf16 v[16:19], v[236:239], v[128:131], v[16:19]
	v_mfma_f32_16x16x32_bf16 v[24:27], v[236:239], v[132:135], v[24:27]
	v_mfma_f32_16x16x32_bf16 v[0:3], v[236:239], v[136:139], v[0:3]
	v_mfma_f32_16x16x32_bf16 v[8:11], v[236:239], v[140:143], v[8:11]
	ds_read_b128 v[236:239], v196 offset:4096
	s_waitcnt lgkmcnt(3)
	v_mfma_f32_16x16x32_bf16 v[20:23], v[240:243], v[128:131], v[20:23]
	v_mfma_f32_16x16x32_bf16 v[28:31], v[240:243], v[132:135], v[28:31]
	v_mfma_f32_16x16x32_bf16 v[4:7], v[240:243], v[136:139], v[4:7]
	v_mfma_f32_16x16x32_bf16 v[12:15], v[240:243], v[140:143], v[12:15]
	ds_read_b128 v[240:243], v162 offset:4096
	s_waitcnt lgkmcnt(3)
	v_mfma_f32_16x16x32_bf16 v[112:115], v[244:247], v[128:131], v[112:115]
	v_mfma_f32_16x16x32_bf16 v[120:123], v[244:247], v[132:135], v[120:123]
	v_mfma_f32_16x16x32_bf16 v[96:99], v[244:247], v[136:139], v[96:99]
	v_mfma_f32_16x16x32_bf16 v[104:107], v[244:247], v[140:143], v[104:107]
	ds_read_b128 v[244:247], v196 offset:6144
	s_waitcnt lgkmcnt(3)
	v_mfma_f32_16x16x32_bf16 v[116:119], v[248:251], v[128:131], v[116:119]
	v_mfma_f32_16x16x32_bf16 v[124:127], v[248:251], v[132:135], v[124:127]
	v_mfma_f32_16x16x32_bf16 v[100:103], v[248:251], v[136:139], v[100:103]
	v_mfma_f32_16x16x32_bf16 v[108:111], v[248:251], v[140:143], v[108:111]
	ds_read_b128 v[248:251], v162 offset:6144
	s_waitcnt lgkmcnt(3)
	v_mfma_f32_16x16x32_bf16 v[80:83], v[236:239], v[128:131], v[80:83]
	v_mfma_f32_16x16x32_bf16 v[88:91], v[236:239], v[132:135], v[88:91]
	v_mfma_f32_16x16x32_bf16 v[48:51], v[236:239], v[136:139], v[48:51]
	v_mfma_f32_16x16x32_bf16 v[56:59], v[236:239], v[140:143], v[56:59]
	s_waitcnt lgkmcnt(2)
	v_mfma_f32_16x16x32_bf16 v[84:87], v[240:243], v[128:131], v[84:87]
	v_mfma_f32_16x16x32_bf16 v[92:95], v[240:243], v[132:135], v[92:95]
	v_mfma_f32_16x16x32_bf16 v[52:55], v[240:243], v[136:139], v[52:55]
	v_mfma_f32_16x16x32_bf16 v[60:63], v[240:243], v[140:143], v[60:63]
	s_waitcnt lgkmcnt(1)
	v_mfma_f32_16x16x32_bf16 v[64:67], v[244:247], v[128:131], v[64:67]
	v_mfma_f32_16x16x32_bf16 v[72:75], v[244:247], v[132:135], v[72:75]
	v_mfma_f32_16x16x32_bf16 v[32:35], v[244:247], v[136:139], v[32:35]
	v_mfma_f32_16x16x32_bf16 v[40:43], v[244:247], v[140:143], v[40:43]
	s_waitcnt lgkmcnt(0)
	v_mfma_f32_16x16x32_bf16 v[68:71], v[248:251], v[128:131], v[68:71]
	v_mfma_f32_16x16x32_bf16 v[76:79], v[248:251], v[132:135], v[76:79]
	v_mfma_f32_16x16x32_bf16 v[36:39], v[248:251], v[136:139], v[36:39]
	v_mfma_f32_16x16x32_bf16 v[44:47], v[248:251], v[140:143], v[44:47]
	global_load_dwordx4 v[128:131], v[198:199], off
	global_load_dwordx4 v[132:135], v[198:199], off offset:256
	global_load_dwordx4 v[136:139], v[200:201], off
	global_load_dwordx4 v[140:143], v[200:201], off offset:256
	s_waitcnt vmcnt(10)
	s_barrier
	s_add_i32 s3, s1, 3
	s_lshl_b32 s96, s3, 13
	s_mov_b32 m0, vcc_lo
	v_lshl_add_u64 v[160:161], v[188:189], 0, s[96:97]
	global_load_lds_dwordx4 v[160:161], off
	global_load_lds_dwordx4 v[160:161], off offset:1024
	ds_read_b128 v[236:239], v196 offset:8192
	ds_read_b128 v[240:243], v162 offset:8192
	ds_read_b128 v[244:247], v196 offset:10240
	ds_read_b128 v[248:251], v162 offset:10240
	s_add_i32 s3, s1, 3
	s_lshl_b32 s96, s3, 11
	v_lshl_add_u64 v[198:199], v[184:185], 0, s[96:97]
	v_lshl_add_u64 v[200:201], v[186:187], 0, s[96:97]
	s_waitcnt vmcnt(8) lgkmcnt(3)
	v_mfma_f32_16x16x32_bf16 v[16:19], v[236:239], v[144:147], v[16:19]
	v_mfma_f32_16x16x32_bf16 v[24:27], v[236:239], v[148:151], v[24:27]
	v_mfma_f32_16x16x32_bf16 v[0:3], v[236:239], v[152:155], v[0:3]
	v_mfma_f32_16x16x32_bf16 v[8:11], v[236:239], v[156:159], v[8:11]
	ds_read_b128 v[236:239], v196 offset:12288
	s_waitcnt lgkmcnt(3)
	v_mfma_f32_16x16x32_bf16 v[20:23], v[240:243], v[144:147], v[20:23]
	v_mfma_f32_16x16x32_bf16 v[28:31], v[240:243], v[148:151], v[28:31]
	v_mfma_f32_16x16x32_bf16 v[4:7], v[240:243], v[152:155], v[4:7]
	v_mfma_f32_16x16x32_bf16 v[12:15], v[240:243], v[156:159], v[12:15]
	ds_read_b128 v[240:243], v162 offset:12288
	s_waitcnt lgkmcnt(3)
	v_mfma_f32_16x16x32_bf16 v[112:115], v[244:247], v[144:147], v[112:115]
	v_mfma_f32_16x16x32_bf16 v[120:123], v[244:247], v[148:151], v[120:123]
	v_mfma_f32_16x16x32_bf16 v[96:99], v[244:247], v[152:155], v[96:99]
	v_mfma_f32_16x16x32_bf16 v[104:107], v[244:247], v[156:159], v[104:107]
	ds_read_b128 v[244:247], v196 offset:14336
	s_waitcnt lgkmcnt(3)
	v_mfma_f32_16x16x32_bf16 v[116:119], v[248:251], v[144:147], v[116:119]
	v_mfma_f32_16x16x32_bf16 v[124:127], v[248:251], v[148:151], v[124:127]
	v_mfma_f32_16x16x32_bf16 v[100:103], v[248:251], v[152:155], v[100:103]
	v_mfma_f32_16x16x32_bf16 v[108:111], v[248:251], v[156:159], v[108:111]
	ds_read_b128 v[248:251], v162 offset:14336
	s_waitcnt lgkmcnt(3)
	v_mfma_f32_16x16x32_bf16 v[80:83], v[236:239], v[144:147], v[80:83]
	v_mfma_f32_16x16x32_bf16 v[88:91], v[236:239], v[148:151], v[88:91]
	v_mfma_f32_16x16x32_bf16 v[48:51], v[236:239], v[152:155], v[48:51]
	v_mfma_f32_16x16x32_bf16 v[56:59], v[236:239], v[156:159], v[56:59]
	s_waitcnt lgkmcnt(2)
	v_mfma_f32_16x16x32_bf16 v[84:87], v[240:243], v[144:147], v[84:87]
	v_mfma_f32_16x16x32_bf16 v[92:95], v[240:243], v[148:151], v[92:95]
	v_mfma_f32_16x16x32_bf16 v[52:55], v[240:243], v[152:155], v[52:55]
	v_mfma_f32_16x16x32_bf16 v[60:63], v[240:243], v[156:159], v[60:63]
	s_waitcnt lgkmcnt(1)
	v_mfma_f32_16x16x32_bf16 v[64:67], v[244:247], v[144:147], v[64:67]
	v_mfma_f32_16x16x32_bf16 v[72:75], v[244:247], v[148:151], v[72:75]
	v_mfma_f32_16x16x32_bf16 v[32:35], v[244:247], v[152:155], v[32:35]
	v_mfma_f32_16x16x32_bf16 v[40:43], v[244:247], v[156:159], v[40:43]
	s_waitcnt lgkmcnt(0)
	v_mfma_f32_16x16x32_bf16 v[68:71], v[248:251], v[144:147], v[68:71]
	v_mfma_f32_16x16x32_bf16 v[76:79], v[248:251], v[148:151], v[76:79]
	v_mfma_f32_16x16x32_bf16 v[36:39], v[248:251], v[152:155], v[36:39]
	v_mfma_f32_16x16x32_bf16 v[44:47], v[248:251], v[156:159], v[44:47]
	global_load_dwordx4 v[144:147], v[198:199], off
	global_load_dwordx4 v[148:151], v[198:199], off offset:256
	global_load_dwordx4 v[152:155], v[200:201], off
	global_load_dwordx4 v[156:159], v[200:201], off offset:256
	s_waitcnt vmcnt(10)
	s_barrier
	s_add_i32 s3, s1, 4
	s_lshl_b32 s96, s3, 13
	s_add_i32 m0, vcc_lo, 8192
	v_lshl_add_u64 v[160:161], v[188:189], 0, s[96:97]
	global_load_lds_dwordx4 v[160:161], off
	global_load_lds_dwordx4 v[160:161], off offset:1024
	ds_read_b128 v[236:239], v196 offset:16384
	ds_read_b128 v[240:243], v162 offset:16384
	ds_read_b128 v[244:247], v196 offset:18432
	ds_read_b128 v[248:251], v162 offset:18432
	s_add_i32 s3, s1, 4
	s_lshl_b32 s96, s3, 11
	v_lshl_add_u64 v[198:199], v[184:185], 0, s[96:97]
	v_lshl_add_u64 v[200:201], v[186:187], 0, s[96:97]
	s_waitcnt vmcnt(8) lgkmcnt(3)
	v_mfma_f32_16x16x32_bf16 v[16:19], v[236:239], v[128:131], v[16:19]
	v_mfma_f32_16x16x32_bf16 v[24:27], v[236:239], v[132:135], v[24:27]
	v_mfma_f32_16x16x32_bf16 v[0:3], v[236:239], v[136:139], v[0:3]
	v_mfma_f32_16x16x32_bf16 v[8:11], v[236:239], v[140:143], v[8:11]
	ds_read_b128 v[236:239], v196 offset:20480
	s_waitcnt lgkmcnt(3)
	v_mfma_f32_16x16x32_bf16 v[20:23], v[240:243], v[128:131], v[20:23]
	v_mfma_f32_16x16x32_bf16 v[28:31], v[240:243], v[132:135], v[28:31]
	v_mfma_f32_16x16x32_bf16 v[4:7], v[240:243], v[136:139], v[4:7]
	v_mfma_f32_16x16x32_bf16 v[12:15], v[240:243], v[140:143], v[12:15]
	ds_read_b128 v[240:243], v162 offset:20480
	s_waitcnt lgkmcnt(3)
	v_mfma_f32_16x16x32_bf16 v[112:115], v[244:247], v[128:131], v[112:115]
	v_mfma_f32_16x16x32_bf16 v[120:123], v[244:247], v[132:135], v[120:123]
	v_mfma_f32_16x16x32_bf16 v[96:99], v[244:247], v[136:139], v[96:99]
	v_mfma_f32_16x16x32_bf16 v[104:107], v[244:247], v[140:143], v[104:107]
	ds_read_b128 v[244:247], v196 offset:22528
	s_waitcnt lgkmcnt(3)
	v_mfma_f32_16x16x32_bf16 v[116:119], v[248:251], v[128:131], v[116:119]
	v_mfma_f32_16x16x32_bf16 v[124:127], v[248:251], v[132:135], v[124:127]
	v_mfma_f32_16x16x32_bf16 v[100:103], v[248:251], v[136:139], v[100:103]
	v_mfma_f32_16x16x32_bf16 v[108:111], v[248:251], v[140:143], v[108:111]
	ds_read_b128 v[248:251], v162 offset:22528
	s_waitcnt lgkmcnt(3)
	v_mfma_f32_16x16x32_bf16 v[80:83], v[236:239], v[128:131], v[80:83]
	v_mfma_f32_16x16x32_bf16 v[88:91], v[236:239], v[132:135], v[88:91]
	v_mfma_f32_16x16x32_bf16 v[48:51], v[236:239], v[136:139], v[48:51]
	v_mfma_f32_16x16x32_bf16 v[56:59], v[236:239], v[140:143], v[56:59]
	s_waitcnt lgkmcnt(2)
	v_mfma_f32_16x16x32_bf16 v[84:87], v[240:243], v[128:131], v[84:87]
	v_mfma_f32_16x16x32_bf16 v[92:95], v[240:243], v[132:135], v[92:95]
	v_mfma_f32_16x16x32_bf16 v[52:55], v[240:243], v[136:139], v[52:55]
	v_mfma_f32_16x16x32_bf16 v[60:63], v[240:243], v[140:143], v[60:63]
	s_waitcnt lgkmcnt(1)
	v_mfma_f32_16x16x32_bf16 v[64:67], v[244:247], v[128:131], v[64:67]
	v_mfma_f32_16x16x32_bf16 v[72:75], v[244:247], v[132:135], v[72:75]
	v_mfma_f32_16x16x32_bf16 v[32:35], v[244:247], v[136:139], v[32:35]
	v_mfma_f32_16x16x32_bf16 v[40:43], v[244:247], v[140:143], v[40:43]
	s_waitcnt lgkmcnt(0)
	v_mfma_f32_16x16x32_bf16 v[68:71], v[248:251], v[128:131], v[68:71]
	v_mfma_f32_16x16x32_bf16 v[76:79], v[248:251], v[132:135], v[76:79]
	v_mfma_f32_16x16x32_bf16 v[36:39], v[248:251], v[136:139], v[36:39]
	v_mfma_f32_16x16x32_bf16 v[44:47], v[248:251], v[140:143], v[44:47]
	global_load_dwordx4 v[128:131], v[198:199], off
	global_load_dwordx4 v[132:135], v[198:199], off offset:256
	global_load_dwordx4 v[136:139], v[200:201], off
	global_load_dwordx4 v[140:143], v[200:201], off offset:256
	s_waitcnt vmcnt(10)
	s_barrier
	s_add_i32 s3, s1, 5
	s_lshl_b32 s96, s3, 13
	s_add_i32 m0, vcc_lo, 16384
	v_lshl_add_u64 v[160:161], v[188:189], 0, s[96:97]
	global_load_lds_dwordx4 v[160:161], off
	global_load_lds_dwordx4 v[160:161], off offset:1024
	ds_read_b128 v[236:239], v196 offset:0
	ds_read_b128 v[240:243], v162 offset:0
	ds_read_b128 v[244:247], v196 offset:2048
	ds_read_b128 v[248:251], v162 offset:2048
	s_add_i32 s3, s1, 5
	s_lshl_b32 s96, s3, 11
	v_lshl_add_u64 v[198:199], v[184:185], 0, s[96:97]
	v_lshl_add_u64 v[200:201], v[186:187], 0, s[96:97]
	s_waitcnt vmcnt(8) lgkmcnt(3)
	v_mfma_f32_16x16x32_bf16 v[16:19], v[236:239], v[144:147], v[16:19]
	v_mfma_f32_16x16x32_bf16 v[24:27], v[236:239], v[148:151], v[24:27]
	v_mfma_f32_16x16x32_bf16 v[0:3], v[236:239], v[152:155], v[0:3]
	v_mfma_f32_16x16x32_bf16 v[8:11], v[236:239], v[156:159], v[8:11]
	ds_read_b128 v[236:239], v196 offset:4096
	s_waitcnt lgkmcnt(3)
	v_mfma_f32_16x16x32_bf16 v[20:23], v[240:243], v[144:147], v[20:23]
	v_mfma_f32_16x16x32_bf16 v[28:31], v[240:243], v[148:151], v[28:31]
	v_mfma_f32_16x16x32_bf16 v[4:7], v[240:243], v[152:155], v[4:7]
	v_mfma_f32_16x16x32_bf16 v[12:15], v[240:243], v[156:159], v[12:15]
	ds_read_b128 v[240:243], v162 offset:4096
	s_waitcnt lgkmcnt(3)
	v_mfma_f32_16x16x32_bf16 v[112:115], v[244:247], v[144:147], v[112:115]
	v_mfma_f32_16x16x32_bf16 v[120:123], v[244:247], v[148:151], v[120:123]
	v_mfma_f32_16x16x32_bf16 v[96:99], v[244:247], v[152:155], v[96:99]
	v_mfma_f32_16x16x32_bf16 v[104:107], v[244:247], v[156:159], v[104:107]
	ds_read_b128 v[244:247], v196 offset:6144
	s_waitcnt lgkmcnt(3)
	v_mfma_f32_16x16x32_bf16 v[116:119], v[248:251], v[144:147], v[116:119]
	v_mfma_f32_16x16x32_bf16 v[124:127], v[248:251], v[148:151], v[124:127]
	v_mfma_f32_16x16x32_bf16 v[100:103], v[248:251], v[152:155], v[100:103]
	v_mfma_f32_16x16x32_bf16 v[108:111], v[248:251], v[156:159], v[108:111]
	ds_read_b128 v[248:251], v162 offset:6144
	s_waitcnt lgkmcnt(3)
	v_mfma_f32_16x16x32_bf16 v[80:83], v[236:239], v[144:147], v[80:83]
	v_mfma_f32_16x16x32_bf16 v[88:91], v[236:239], v[148:151], v[88:91]
	v_mfma_f32_16x16x32_bf16 v[48:51], v[236:239], v[152:155], v[48:51]
	v_mfma_f32_16x16x32_bf16 v[56:59], v[236:239], v[156:159], v[56:59]
	s_waitcnt lgkmcnt(2)
	v_mfma_f32_16x16x32_bf16 v[84:87], v[240:243], v[144:147], v[84:87]
	v_mfma_f32_16x16x32_bf16 v[92:95], v[240:243], v[148:151], v[92:95]
	v_mfma_f32_16x16x32_bf16 v[52:55], v[240:243], v[152:155], v[52:55]
	v_mfma_f32_16x16x32_bf16 v[60:63], v[240:243], v[156:159], v[60:63]
	s_waitcnt lgkmcnt(1)
	v_mfma_f32_16x16x32_bf16 v[64:67], v[244:247], v[144:147], v[64:67]
	v_mfma_f32_16x16x32_bf16 v[72:75], v[244:247], v[148:151], v[72:75]
	v_mfma_f32_16x16x32_bf16 v[32:35], v[244:247], v[152:155], v[32:35]
	v_mfma_f32_16x16x32_bf16 v[40:43], v[244:247], v[156:159], v[40:43]
	s_waitcnt lgkmcnt(0)
	v_mfma_f32_16x16x32_bf16 v[68:71], v[248:251], v[144:147], v[68:71]
	v_mfma_f32_16x16x32_bf16 v[76:79], v[248:251], v[148:151], v[76:79]
	v_mfma_f32_16x16x32_bf16 v[36:39], v[248:251], v[152:155], v[36:39]
	v_mfma_f32_16x16x32_bf16 v[44:47], v[248:251], v[156:159], v[44:47]
	global_load_dwordx4 v[144:147], v[198:199], off
	global_load_dwordx4 v[148:151], v[198:199], off offset:256
	global_load_dwordx4 v[152:155], v[200:201], off
	global_load_dwordx4 v[156:159], v[200:201], off offset:256
	s_waitcnt vmcnt(10)
	s_barrier
	s_add_i32 s3, s1, 6
	s_lshl_b32 s96, s3, 13
	s_mov_b32 m0, vcc_lo
	v_lshl_add_u64 v[160:161], v[188:189], 0, s[96:97]
	global_load_lds_dwordx4 v[160:161], off
	global_load_lds_dwordx4 v[160:161], off offset:1024
	ds_read_b128 v[236:239], v196 offset:8192
	ds_read_b128 v[240:243], v162 offset:8192
	ds_read_b128 v[244:247], v196 offset:10240
	ds_read_b128 v[248:251], v162 offset:10240
	s_add_i32 s3, s1, 6
	s_lshl_b32 s96, s3, 11
	v_lshl_add_u64 v[198:199], v[184:185], 0, s[96:97]
	v_lshl_add_u64 v[200:201], v[186:187], 0, s[96:97]
	s_waitcnt vmcnt(8) lgkmcnt(3)
	v_mfma_f32_16x16x32_bf16 v[16:19], v[236:239], v[128:131], v[16:19]
	v_mfma_f32_16x16x32_bf16 v[24:27], v[236:239], v[132:135], v[24:27]
	v_mfma_f32_16x16x32_bf16 v[0:3], v[236:239], v[136:139], v[0:3]
	v_mfma_f32_16x16x32_bf16 v[8:11], v[236:239], v[140:143], v[8:11]
	ds_read_b128 v[236:239], v196 offset:12288
	s_waitcnt lgkmcnt(3)
	v_mfma_f32_16x16x32_bf16 v[20:23], v[240:243], v[128:131], v[20:23]
	v_mfma_f32_16x16x32_bf16 v[28:31], v[240:243], v[132:135], v[28:31]
	v_mfma_f32_16x16x32_bf16 v[4:7], v[240:243], v[136:139], v[4:7]
	v_mfma_f32_16x16x32_bf16 v[12:15], v[240:243], v[140:143], v[12:15]
	ds_read_b128 v[240:243], v162 offset:12288
	s_waitcnt lgkmcnt(3)
	v_mfma_f32_16x16x32_bf16 v[112:115], v[244:247], v[128:131], v[112:115]
	v_mfma_f32_16x16x32_bf16 v[120:123], v[244:247], v[132:135], v[120:123]
	v_mfma_f32_16x16x32_bf16 v[96:99], v[244:247], v[136:139], v[96:99]
	v_mfma_f32_16x16x32_bf16 v[104:107], v[244:247], v[140:143], v[104:107]
	ds_read_b128 v[244:247], v196 offset:14336
	s_waitcnt lgkmcnt(3)
	v_mfma_f32_16x16x32_bf16 v[116:119], v[248:251], v[128:131], v[116:119]
	v_mfma_f32_16x16x32_bf16 v[124:127], v[248:251], v[132:135], v[124:127]
	v_mfma_f32_16x16x32_bf16 v[100:103], v[248:251], v[136:139], v[100:103]
	v_mfma_f32_16x16x32_bf16 v[108:111], v[248:251], v[140:143], v[108:111]
	ds_read_b128 v[248:251], v162 offset:14336
	s_waitcnt lgkmcnt(3)
	v_mfma_f32_16x16x32_bf16 v[80:83], v[236:239], v[128:131], v[80:83]
	v_mfma_f32_16x16x32_bf16 v[88:91], v[236:239], v[132:135], v[88:91]
	v_mfma_f32_16x16x32_bf16 v[48:51], v[236:239], v[136:139], v[48:51]
	v_mfma_f32_16x16x32_bf16 v[56:59], v[236:239], v[140:143], v[56:59]
	s_waitcnt lgkmcnt(2)
	v_mfma_f32_16x16x32_bf16 v[84:87], v[240:243], v[128:131], v[84:87]
	v_mfma_f32_16x16x32_bf16 v[92:95], v[240:243], v[132:135], v[92:95]
	v_mfma_f32_16x16x32_bf16 v[52:55], v[240:243], v[136:139], v[52:55]
	v_mfma_f32_16x16x32_bf16 v[60:63], v[240:243], v[140:143], v[60:63]
	s_waitcnt lgkmcnt(1)
	v_mfma_f32_16x16x32_bf16 v[64:67], v[244:247], v[128:131], v[64:67]
	v_mfma_f32_16x16x32_bf16 v[72:75], v[244:247], v[132:135], v[72:75]
	v_mfma_f32_16x16x32_bf16 v[32:35], v[244:247], v[136:139], v[32:35]
	v_mfma_f32_16x16x32_bf16 v[40:43], v[244:247], v[140:143], v[40:43]
	s_waitcnt lgkmcnt(0)
	v_mfma_f32_16x16x32_bf16 v[68:71], v[248:251], v[128:131], v[68:71]
	v_mfma_f32_16x16x32_bf16 v[76:79], v[248:251], v[132:135], v[76:79]
	v_mfma_f32_16x16x32_bf16 v[36:39], v[248:251], v[136:139], v[36:39]
	v_mfma_f32_16x16x32_bf16 v[44:47], v[248:251], v[140:143], v[44:47]
	global_load_dwordx4 v[128:131], v[198:199], off
	global_load_dwordx4 v[132:135], v[198:199], off offset:256
	global_load_dwordx4 v[136:139], v[200:201], off
	global_load_dwordx4 v[140:143], v[200:201], off offset:256
	s_waitcnt vmcnt(10)
	s_barrier
	s_add_i32 s3, s1, 7
	s_lshl_b32 s96, s3, 13
	s_add_i32 m0, vcc_lo, 8192
	v_lshl_add_u64 v[160:161], v[188:189], 0, s[96:97]
	global_load_lds_dwordx4 v[160:161], off
	global_load_lds_dwordx4 v[160:161], off offset:1024
	ds_read_b128 v[236:239], v196 offset:16384
	ds_read_b128 v[240:243], v162 offset:16384
	ds_read_b128 v[244:247], v196 offset:18432
	ds_read_b128 v[248:251], v162 offset:18432
	s_add_i32 s3, s1, 7
	s_lshl_b32 s96, s3, 11
	v_lshl_add_u64 v[198:199], v[184:185], 0, s[96:97]
	v_lshl_add_u64 v[200:201], v[186:187], 0, s[96:97]
	s_waitcnt vmcnt(8) lgkmcnt(3)
	v_mfma_f32_16x16x32_bf16 v[16:19], v[236:239], v[144:147], v[16:19]
	v_mfma_f32_16x16x32_bf16 v[24:27], v[236:239], v[148:151], v[24:27]
	v_mfma_f32_16x16x32_bf16 v[0:3], v[236:239], v[152:155], v[0:3]
	v_mfma_f32_16x16x32_bf16 v[8:11], v[236:239], v[156:159], v[8:11]
	ds_read_b128 v[236:239], v196 offset:20480
	s_waitcnt lgkmcnt(3)
	v_mfma_f32_16x16x32_bf16 v[20:23], v[240:243], v[144:147], v[20:23]
	v_mfma_f32_16x16x32_bf16 v[28:31], v[240:243], v[148:151], v[28:31]
	v_mfma_f32_16x16x32_bf16 v[4:7], v[240:243], v[152:155], v[4:7]
	v_mfma_f32_16x16x32_bf16 v[12:15], v[240:243], v[156:159], v[12:15]
	ds_read_b128 v[240:243], v162 offset:20480
	s_waitcnt lgkmcnt(3)
	v_mfma_f32_16x16x32_bf16 v[112:115], v[244:247], v[144:147], v[112:115]
	v_mfma_f32_16x16x32_bf16 v[120:123], v[244:247], v[148:151], v[120:123]
	v_mfma_f32_16x16x32_bf16 v[96:99], v[244:247], v[152:155], v[96:99]
	v_mfma_f32_16x16x32_bf16 v[104:107], v[244:247], v[156:159], v[104:107]
	ds_read_b128 v[244:247], v196 offset:22528
	s_waitcnt lgkmcnt(3)
	v_mfma_f32_16x16x32_bf16 v[116:119], v[248:251], v[144:147], v[116:119]
	v_mfma_f32_16x16x32_bf16 v[124:127], v[248:251], v[148:151], v[124:127]
	v_mfma_f32_16x16x32_bf16 v[100:103], v[248:251], v[152:155], v[100:103]
	v_mfma_f32_16x16x32_bf16 v[108:111], v[248:251], v[156:159], v[108:111]
	ds_read_b128 v[248:251], v162 offset:22528
	s_waitcnt lgkmcnt(3)
	v_mfma_f32_16x16x32_bf16 v[80:83], v[236:239], v[144:147], v[80:83]
	v_mfma_f32_16x16x32_bf16 v[88:91], v[236:239], v[148:151], v[88:91]
	v_mfma_f32_16x16x32_bf16 v[48:51], v[236:239], v[152:155], v[48:51]
	v_mfma_f32_16x16x32_bf16 v[56:59], v[236:239], v[156:159], v[56:59]
	s_waitcnt lgkmcnt(2)
	v_mfma_f32_16x16x32_bf16 v[84:87], v[240:243], v[144:147], v[84:87]
	v_mfma_f32_16x16x32_bf16 v[92:95], v[240:243], v[148:151], v[92:95]
	v_mfma_f32_16x16x32_bf16 v[52:55], v[240:243], v[152:155], v[52:55]
	v_mfma_f32_16x16x32_bf16 v[60:63], v[240:243], v[156:159], v[60:63]
	s_waitcnt lgkmcnt(1)
	v_mfma_f32_16x16x32_bf16 v[64:67], v[244:247], v[144:147], v[64:67]
	v_mfma_f32_16x16x32_bf16 v[72:75], v[244:247], v[148:151], v[72:75]
	v_mfma_f32_16x16x32_bf16 v[32:35], v[244:247], v[152:155], v[32:35]
	v_mfma_f32_16x16x32_bf16 v[40:43], v[244:247], v[156:159], v[40:43]
	s_waitcnt lgkmcnt(0)
	v_mfma_f32_16x16x32_bf16 v[68:71], v[248:251], v[144:147], v[68:71]
	v_mfma_f32_16x16x32_bf16 v[76:79], v[248:251], v[148:151], v[76:79]
	v_mfma_f32_16x16x32_bf16 v[36:39], v[248:251], v[152:155], v[36:39]
	v_mfma_f32_16x16x32_bf16 v[44:47], v[248:251], v[156:159], v[44:47]
	global_load_dwordx4 v[144:147], v[198:199], off
	global_load_dwordx4 v[148:151], v[198:199], off offset:256
	global_load_dwordx4 v[152:155], v[200:201], off
	global_load_dwordx4 v[156:159], v[200:201], off offset:256
	s_waitcnt vmcnt(10)
	s_barrier
	s_add_i32 s1, s1, 6
	s_cmp_lt_u32 s1, 30
	s_cbranch_scc1 .Lg16_proj_k
	ds_read_b128 v[236:239], v196 offset:0
	ds_read_b128 v[240:243], v162 offset:0
	ds_read_b128 v[244:247], v196 offset:2048
	ds_read_b128 v[248:251], v162 offset:2048
	s_waitcnt vmcnt(6) lgkmcnt(3)
	v_mfma_f32_16x16x32_bf16 v[16:19], v[236:239], v[128:131], v[16:19]
	v_mfma_f32_16x16x32_bf16 v[24:27], v[236:239], v[132:135], v[24:27]
	v_mfma_f32_16x16x32_bf16 v[0:3], v[236:239], v[136:139], v[0:3]
	v_mfma_f32_16x16x32_bf16 v[8:11], v[236:239], v[140:143], v[8:11]
	ds_read_b128 v[236:239], v196 offset:4096
	s_waitcnt lgkmcnt(3)
	v_mfma_f32_16x16x32_bf16 v[20:23], v[240:243], v[128:131], v[20:23]
	v_mfma_f32_16x16x32_bf16 v[28:31], v[240:243], v[132:135], v[28:31]
	v_mfma_f32_16x16x32_bf16 v[4:7], v[240:243], v[136:139], v[4:7]
	v_mfma_f32_16x16x32_bf16 v[12:15], v[240:243], v[140:143], v[12:15]
	ds_read_b128 v[240:243], v162 offset:4096
	s_waitcnt lgkmcnt(3)
	v_mfma_f32_16x16x32_bf16 v[112:115], v[244:247], v[128:131], v[112:115]
	v_mfma_f32_16x16x32_bf16 v[120:123], v[244:247], v[132:135], v[120:123]
	v_mfma_f32_16x16x32_bf16 v[96:99], v[244:247], v[136:139], v[96:99]
	v_mfma_f32_16x16x32_bf16 v[104:107], v[244:247], v[140:143], v[104:107]
	ds_read_b128 v[244:247], v196 offset:6144
	s_waitcnt lgkmcnt(3)
	v_mfma_f32_16x16x32_bf16 v[116:119], v[248:251], v[128:131], v[116:119]
	v_mfma_f32_16x16x32_bf16 v[124:127], v[248:251], v[132:135], v[124:127]
	v_mfma_f32_16x16x32_bf16 v[100:103], v[248:251], v[136:139], v[100:103]
	v_mfma_f32_16x16x32_bf16 v[108:111], v[248:251], v[140:143], v[108:111]
	ds_read_b128 v[248:251], v162 offset:6144
	s_waitcnt lgkmcnt(3)
	v_mfma_f32_16x16x32_bf16 v[80:83], v[236:239], v[128:131], v[80:83]
	v_mfma_f32_16x16x32_bf16 v[88:91], v[236:239], v[132:135], v[88:91]
	v_mfma_f32_16x16x32_bf16 v[48:51], v[236:239], v[136:139], v[48:51]
	v_mfma_f32_16x16x32_bf16 v[56:59], v[236:239], v[140:143], v[56:59]
	s_waitcnt lgkmcnt(2)
	v_mfma_f32_16x16x32_bf16 v[84:87], v[240:243], v[128:131], v[84:87]
	v_mfma_f32_16x16x32_bf16 v[92:95], v[240:243], v[132:135], v[92:95]
	v_mfma_f32_16x16x32_bf16 v[52:55], v[240:243], v[136:139], v[52:55]
	v_mfma_f32_16x16x32_bf16 v[60:63], v[240:243], v[140:143], v[60:63]
	s_waitcnt lgkmcnt(1)
	v_mfma_f32_16x16x32_bf16 v[64:67], v[244:247], v[128:131], v[64:67]
	v_mfma_f32_16x16x32_bf16 v[72:75], v[244:247], v[132:135], v[72:75]
	v_mfma_f32_16x16x32_bf16 v[32:35], v[244:247], v[136:139], v[32:35]
	v_mfma_f32_16x16x32_bf16 v[40:43], v[244:247], v[140:143], v[40:43]
	s_waitcnt lgkmcnt(0)
	v_mfma_f32_16x16x32_bf16 v[68:71], v[248:251], v[128:131], v[68:71]
	v_mfma_f32_16x16x32_bf16 v[76:79], v[248:251], v[132:135], v[76:79]
	v_mfma_f32_16x16x32_bf16 v[36:39], v[248:251], v[136:139], v[36:39]
	v_mfma_f32_16x16x32_bf16 v[44:47], v[248:251], v[140:143], v[44:47]
	s_waitcnt vmcnt(4)
	s_barrier
	ds_read_b128 v[236:239], v196 offset:8192
	ds_read_b128 v[240:243], v162 offset:8192
	ds_read_b128 v[244:247], v196 offset:10240
	ds_read_b128 v[248:251], v162 offset:10240
	s_waitcnt vmcnt(0) lgkmcnt(3)
	v_mfma_f32_16x16x32_bf16 v[16:19], v[236:239], v[144:147], v[16:19]
	v_mfma_f32_16x16x32_bf16 v[24:27], v[236:239], v[148:151], v[24:27]
	v_mfma_f32_16x16x32_bf16 v[0:3], v[236:239], v[152:155], v[0:3]
	v_mfma_f32_16x16x32_bf16 v[8:11], v[236:239], v[156:159], v[8:11]
	ds_read_b128 v[236:239], v196 offset:12288
	s_waitcnt lgkmcnt(3)
	v_mfma_f32_16x16x32_bf16 v[20:23], v[240:243], v[144:147], v[20:23]
	v_mfma_f32_16x16x32_bf16 v[28:31], v[240:243], v[148:151], v[28:31]
	v_mfma_f32_16x16x32_bf16 v[4:7], v[240:243], v[152:155], v[4:7]
	v_mfma_f32_16x16x32_bf16 v[12:15], v[240:243], v[156:159], v[12:15]
	ds_read_b128 v[240:243], v162 offset:12288
	s_waitcnt lgkmcnt(3)
	v_mfma_f32_16x16x32_bf16 v[112:115], v[244:247], v[144:147], v[112:115]
	v_mfma_f32_16x16x32_bf16 v[120:123], v[244:247], v[148:151], v[120:123]
	v_mfma_f32_16x16x32_bf16 v[96:99], v[244:247], v[152:155], v[96:99]
	v_mfma_f32_16x16x32_bf16 v[104:107], v[244:247], v[156:159], v[104:107]
	ds_read_b128 v[244:247], v196 offset:14336
	s_waitcnt lgkmcnt(3)
	v_mfma_f32_16x16x32_bf16 v[116:119], v[248:251], v[144:147], v[116:119]
	v_mfma_f32_16x16x32_bf16 v[124:127], v[248:251], v[148:151], v[124:127]
	v_mfma_f32_16x16x32_bf16 v[100:103], v[248:251], v[152:155], v[100:103]
	v_mfma_f32_16x16x32_bf16 v[108:111], v[248:251], v[156:159], v[108:111]
	ds_read_b128 v[248:251], v162 offset:14336
	s_waitcnt lgkmcnt(3)
	v_mfma_f32_16x16x32_bf16 v[80:83], v[236:239], v[144:147], v[80:83]
	v_mfma_f32_16x16x32_bf16 v[88:91], v[236:239], v[148:151], v[88:91]
	v_mfma_f32_16x16x32_bf16 v[48:51], v[236:239], v[152:155], v[48:51]
	v_mfma_f32_16x16x32_bf16 v[56:59], v[236:239], v[156:159], v[56:59]
	s_waitcnt lgkmcnt(2)
	v_mfma_f32_16x16x32_bf16 v[84:87], v[240:243], v[144:147], v[84:87]
	v_mfma_f32_16x16x32_bf16 v[92:95], v[240:243], v[148:151], v[92:95]
	v_mfma_f32_16x16x32_bf16 v[52:55], v[240:243], v[152:155], v[52:55]
	v_mfma_f32_16x16x32_bf16 v[60:63], v[240:243], v[156:159], v[60:63]
	s_waitcnt lgkmcnt(1)
	v_mfma_f32_16x16x32_bf16 v[64:67], v[244:247], v[144:147], v[64:67]
	v_mfma_f32_16x16x32_bf16 v[72:75], v[244:247], v[148:151], v[72:75]
	v_mfma_f32_16x16x32_bf16 v[32:35], v[244:247], v[152:155], v[32:35]
	v_mfma_f32_16x16x32_bf16 v[40:43], v[244:247], v[156:159], v[40:43]
	s_waitcnt lgkmcnt(0)
	v_mfma_f32_16x16x32_bf16 v[68:71], v[248:251], v[144:147], v[68:71]
	v_mfma_f32_16x16x32_bf16 v[76:79], v[248:251], v[148:151], v[76:79]
	v_mfma_f32_16x16x32_bf16 v[36:39], v[248:251], v[152:155], v[36:39]
	v_mfma_f32_16x16x32_bf16 v[44:47], v[248:251], v[156:159], v[44:47]
	s_barrier
	s_nop 7
	s_nop 1
	s_waitcnt vmcnt(0)
	s_waitcnt vmcnt(0)
	v_and_b32_e32 v128, 63, v179
	v_lshrrev_b32_e32 v129, 6, v179
	s_lshl_b32 s20, s2, 8
	s_cmp_eq_u32 s0, 23
	s_cbranch_scc1 .Lpe_proj_ab
	v_readlane_b32 s14, v254, 15
	v_readlane_b32 s15, v254, 16
	v_readlane_b32 s16, v254, 17
	v_readlane_b32 s17, v254, 18
	s_movk_i32 s22, 0x900
	s_movk_i32 s23, 0x300
	s_cmp_lt_u32 s0, 20
	s_cselect_b32 s14, s14, s16
	s_cselect_b32 s15, s15, s17
	s_cselect_b32 s18, s22, s23
	s_movk_i32 s22, 0xf500
	s_movk_i32 s23, 0xec00
	s_cselect_b32 s19, s22, s23
	s_movk_i32 s22, 0xb00
	s_cmp_lt_u32 s0, 11
	s_cselect_b32 s14, s66, s14
	s_cselect_b32 s15, s67, s15
	s_cselect_b32 s18, s22, s18
	s_cselect_b32 s19, 0, s19
	s_mul_hi_u32 s21, s20, s18
	s_mul_i32 s20, s20, s18
	s_lshl_b32 s22, s0, 8
	s_add_i32 s22, s22, s19
	s_add_u32 s12, s14, s20
	s_addc_u32 s13, s15, s21
	s_add_u32 s12, s12, s22
	s_addc_u32 s13, s13, 0
	v_mul_u32_u24_e32 v188, 0x2400, v129
	v_and_b32_e32 v189, 15, v128
	v_mul_u32_u24_e32 v189, 0x90, v189
	v_add_u32_e32 v130, v188, v189
	v_lshrrev_b32_e32 v189, 4, v128
	v_lshl_add_u32 v130, v189, 4, v130
	v_lshrrev_b32_e32 v189, 3, v128
	v_mul_u32_u24_e32 v132, 0x90, v189
	v_add_u32_e32 v131, v188, v132
	v_and_b32_e32 v188, 7, v128
	v_lshlrev_b32_e32 v188, 4, v188
	v_add_u32_e32 v131, v131, v188
	v_lshl_add_u32 v189, v129, 6, v189
	v_add_u32_e32 v132, 0, v189
	v_add_u32_e32 v133, 8, v189
	v_add_u32_e32 v134, 16, v189
	v_add_u32_e32 v135, 24, v189
	v_add_u32_e32 v136, 32, v189
	v_add_u32_e32 v137, 40, v189
	v_add_u32_e32 v138, 48, v189
	v_add_u32_e32 v139, 56, v189
	v_mul_lo_u32 v132, v132, s18
	v_mul_lo_u32 v133, v133, s18
	v_mul_lo_u32 v134, v134, s18
	v_mul_lo_u32 v135, v135, s18
	v_mul_lo_u32 v136, v136, s18
	v_mul_lo_u32 v137, v137, s18
	v_mul_lo_u32 v138, v138, s18
	v_mul_lo_u32 v139, v139, s18
	v_add_u32_e32 v132, v132, v188
	v_add_u32_e32 v133, v133, v188
	v_add_u32_e32 v134, v134, v188
	v_add_u32_e32 v135, v135, v188
	v_add_u32_e32 v136, v136, v188
	v_add_u32_e32 v137, v137, v188
	v_add_u32_e32 v138, v138, v188
	v_add_u32_e32 v139, v139, v188
	v_cvt_pk_bf16_f32 v140, v16, v17
	v_cvt_pk_bf16_f32 v141, v18, v19
	v_cvt_pk_bf16_f32 v142, v20, v21
	v_cvt_pk_bf16_f32 v143, v22, v23
	ds_write_b128 v130, v[140:143]
	v_cvt_pk_bf16_f32 v144, v112, v113
	v_cvt_pk_bf16_f32 v145, v114, v115
	v_cvt_pk_bf16_f32 v146, v116, v117
	v_cvt_pk_bf16_f32 v147, v118, v119
	ds_write_b128 v130, v[144:147] offset:64
	v_cvt_pk_bf16_f32 v140, v24, v25
	v_cvt_pk_bf16_f32 v141, v26, v27
	v_cvt_pk_bf16_f32 v142, v28, v29
	v_cvt_pk_bf16_f32 v143, v30, v31
	ds_write_b128 v130, v[140:143] offset:2304
	v_cvt_pk_bf16_f32 v144, v120, v121
	v_cvt_pk_bf16_f32 v145, v122, v123
	v_cvt_pk_bf16_f32 v146, v124, v125
	v_cvt_pk_bf16_f32 v147, v126, v127
	ds_write_b128 v130, v[144:147] offset:2368
	v_cvt_pk_bf16_f32 v140, v0, v1
	v_cvt_pk_bf16_f32 v141, v2, v3
	v_cvt_pk_bf16_f32 v142, v4, v5
	v_cvt_pk_bf16_f32 v143, v6, v7
	ds_write_b128 v130, v[140:143] offset:4608
	v_cvt_pk_bf16_f32 v144, v96, v97
	v_cvt_pk_bf16_f32 v145, v98, v99
	v_cvt_pk_bf16_f32 v146, v100, v101
	v_cvt_pk_bf16_f32 v147, v102, v103
	ds_write_b128 v130, v[144:147] offset:4672
	v_cvt_pk_bf16_f32 v140, v8, v9
	v_cvt_pk_bf16_f32 v141, v10, v11
	v_cvt_pk_bf16_f32 v142, v12, v13
	v_cvt_pk_bf16_f32 v143, v14, v15
	ds_write_b128 v130, v[140:143] offset:6912
	v_cvt_pk_bf16_f32 v144, v104, v105
	v_cvt_pk_bf16_f32 v145, v106, v107
	v_cvt_pk_bf16_f32 v146, v108, v109
	v_cvt_pk_bf16_f32 v147, v110, v111
	ds_write_b128 v130, v[144:147] offset:6976
	s_waitcnt lgkmcnt(0)
	ds_read_b128 v[148:151], v131
	ds_read_b128 v[152:155], v131 offset:1152
	ds_read_b128 v[156:159], v131 offset:2304
	ds_read_b128 v[160:163], v131 offset:3456
	ds_read_b128 v[164:167], v131 offset:4608
	ds_read_b128 v[168:171], v131 offset:5760
	ds_read_b128 v[172:175], v131 offset:6912
	ds_read_b128 v[184:187], v131 offset:8064
	s_waitcnt lgkmcnt(7)
	global_store_dwordx4 v132, v[148:151], s[12:13] sc0 sc1 nt
	s_waitcnt lgkmcnt(6)
	global_store_dwordx4 v133, v[152:155], s[12:13] sc0 sc1 nt
	s_waitcnt lgkmcnt(5)
	global_store_dwordx4 v134, v[156:159], s[12:13] sc0 sc1 nt
	s_waitcnt lgkmcnt(4)
	global_store_dwordx4 v135, v[160:163], s[12:13] sc0 sc1 nt
	s_waitcnt lgkmcnt(3)
	global_store_dwordx4 v136, v[164:167], s[12:13] sc0 sc1 nt
	s_waitcnt lgkmcnt(2)
	global_store_dwordx4 v137, v[168:171], s[12:13] sc0 sc1 nt
	s_waitcnt lgkmcnt(1)
	global_store_dwordx4 v138, v[172:175], s[12:13] sc0 sc1 nt
	s_waitcnt lgkmcnt(0)
	global_store_dwordx4 v139, v[184:187], s[12:13] sc0 sc1 nt
	v_cvt_pk_bf16_f32 v140, v80, v81
	v_cvt_pk_bf16_f32 v141, v82, v83
	v_cvt_pk_bf16_f32 v142, v84, v85
	v_cvt_pk_bf16_f32 v143, v86, v87
	ds_write_b128 v130, v[140:143]
	v_cvt_pk_bf16_f32 v144, v64, v65
	v_cvt_pk_bf16_f32 v145, v66, v67
	v_cvt_pk_bf16_f32 v146, v68, v69
	v_cvt_pk_bf16_f32 v147, v70, v71
	ds_write_b128 v130, v[144:147] offset:64
	v_cvt_pk_bf16_f32 v140, v88, v89
	v_cvt_pk_bf16_f32 v141, v90, v91
	v_cvt_pk_bf16_f32 v142, v92, v93
	v_cvt_pk_bf16_f32 v143, v94, v95
	ds_write_b128 v130, v[140:143] offset:2304
	v_cvt_pk_bf16_f32 v144, v72, v73
	v_cvt_pk_bf16_f32 v145, v74, v75
	v_cvt_pk_bf16_f32 v146, v76, v77
	v_cvt_pk_bf16_f32 v147, v78, v79
	ds_write_b128 v130, v[144:147] offset:2368
	v_cvt_pk_bf16_f32 v140, v48, v49
	v_cvt_pk_bf16_f32 v141, v50, v51
	v_cvt_pk_bf16_f32 v142, v52, v53
	v_cvt_pk_bf16_f32 v143, v54, v55
	ds_write_b128 v130, v[140:143] offset:4608
	v_cvt_pk_bf16_f32 v144, v32, v33
	v_cvt_pk_bf16_f32 v145, v34, v35
	v_cvt_pk_bf16_f32 v146, v36, v37
	v_cvt_pk_bf16_f32 v147, v38, v39
	ds_write_b128 v130, v[144:147] offset:4672
	v_cvt_pk_bf16_f32 v140, v56, v57
	v_cvt_pk_bf16_f32 v141, v58, v59
	v_cvt_pk_bf16_f32 v142, v60, v61
	v_cvt_pk_bf16_f32 v143, v62, v63
	ds_write_b128 v130, v[140:143] offset:6912
	v_cvt_pk_bf16_f32 v144, v40, v41
	v_cvt_pk_bf16_f32 v145, v42, v43
	v_cvt_pk_bf16_f32 v146, v44, v45
	v_cvt_pk_bf16_f32 v147, v46, v47
	ds_write_b128 v130, v[144:147] offset:6976
	s_waitcnt lgkmcnt(0)
	ds_read_b128 v[148:151], v131
	ds_read_b128 v[152:155], v131 offset:1152
	ds_read_b128 v[156:159], v131 offset:2304
	ds_read_b128 v[160:163], v131 offset:3456
	ds_read_b128 v[164:167], v131 offset:4608
	ds_read_b128 v[168:171], v131 offset:5760
	ds_read_b128 v[172:175], v131 offset:6912
	ds_read_b128 v[184:187], v131 offset:8064
	s_waitcnt lgkmcnt(7)
	global_store_dwordx4 v132, v[148:151], s[12:13] offset:128 sc0 sc1 nt
	s_waitcnt lgkmcnt(6)
	global_store_dwordx4 v133, v[152:155], s[12:13] offset:128 sc0 sc1 nt
	s_waitcnt lgkmcnt(5)
	global_store_dwordx4 v134, v[156:159], s[12:13] offset:128 sc0 sc1 nt
	s_waitcnt lgkmcnt(4)
	global_store_dwordx4 v135, v[160:163], s[12:13] offset:128 sc0 sc1 nt
	s_waitcnt lgkmcnt(3)
	global_store_dwordx4 v136, v[164:167], s[12:13] offset:128 sc0 sc1 nt
	s_waitcnt lgkmcnt(2)
	global_store_dwordx4 v137, v[168:171], s[12:13] offset:128 sc0 sc1 nt
	s_waitcnt lgkmcnt(1)
	global_store_dwordx4 v138, v[172:175], s[12:13] offset:128 sc0 sc1 nt
	s_waitcnt lgkmcnt(0)
	global_store_dwordx4 v139, v[184:187], s[12:13] offset:128 sc0 sc1 nt
	s_branch .Lpe_proj_end
.Lpe_proj_ab:
	v_readlane_b32 s14, v254, 19
	v_readlane_b32 s15, v254, 20
	s_mul_i32 s20, s20, 0x60
	s_add_u32 s12, s14, s20
	s_addc_u32 s13, s15, 0
	v_and_b32_e32 v189, 15, v128
	v_lshl_add_u32 v189, v129, 6, v189
	v_mul_u32_u24_e32 v189, 0x60, v189
	v_lshrrev_b32_e32 v188, 4, v128
	v_lshl_add_u32 v189, v188, 5, v189
	v_cmp_gt_u32_e32 vcc, 48, v128
	s_and_saveexec_b64 s[14:15], vcc
	global_store_dwordx4 v189, v[16:19], s[12:13] sc0 sc1 nt
	global_store_dwordx4 v189, v[20:23], s[12:13] offset:16 sc0 sc1 nt
	global_store_dwordx4 v189, v[24:27], s[12:13] offset:1536 sc0 sc1 nt
	global_store_dwordx4 v189, v[28:31], s[12:13] offset:1552 sc0 sc1 nt
	s_add_u32 s12, s12, 0xc00
	s_addc_u32 s13, s13, 0
	global_store_dwordx4 v189, v[0:3], s[12:13] sc0 sc1 nt
	global_store_dwordx4 v189, v[4:7], s[12:13] offset:16 sc0 sc1 nt
	global_store_dwordx4 v189, v[8:11], s[12:13] offset:1536 sc0 sc1 nt
	global_store_dwordx4 v189, v[12:15], s[12:13] offset:1552 sc0 sc1 nt
	s_mov_b64 exec, s[14:15]

.Lg16_out_k:
	s_add_i32 s9, s3, 2
	s_lshl_b32 s96, s9, 13
	s_add_i32 m0, vcc_lo, 16384
	v_lshl_add_u64 v[160:161], v[188:189], 0, s[96:97]
	global_load_lds_dwordx4 v[160:161], off
	global_load_lds_dwordx4 v[160:161], off offset:1024
	ds_read_b128 v[196:199], v246 offset:0
	ds_read_b128 v[200:203], v162 offset:0
	ds_read_b128 v[204:207], v246 offset:2048
	ds_read_b128 v[242:245], v162 offset:2048
	s_add_i32 s9, s3, 2
	s_lshl_b32 s96, s9, 11
	v_lshl_add_u64 v[248:249], v[184:185], 0, s[96:97]
	v_lshl_add_u64 v[250:251], v[186:187], 0, s[96:97]
	s_waitcnt vmcnt(8) lgkmcnt(3)
	v_mfma_f32_16x16x32_bf16 v[112:115], v[196:199], v[128:131], v[112:115]
	v_mfma_f32_16x16x32_bf16 v[120:123], v[196:199], v[132:135], v[120:123]
	v_mfma_f32_16x16x32_bf16 v[48:51], v[196:199], v[136:139], v[48:51]
	v_mfma_f32_16x16x32_bf16 v[56:59], v[196:199], v[140:143], v[56:59]
	ds_read_b128 v[196:199], v246 offset:4096
	s_waitcnt lgkmcnt(3)
	v_mfma_f32_16x16x32_bf16 v[116:119], v[200:203], v[128:131], v[116:119]
	v_mfma_f32_16x16x32_bf16 v[124:127], v[200:203], v[132:135], v[124:127]
	v_mfma_f32_16x16x32_bf16 v[52:55], v[200:203], v[136:139], v[52:55]
	v_mfma_f32_16x16x32_bf16 v[60:63], v[200:203], v[140:143], v[60:63]
	ds_read_b128 v[200:203], v162 offset:4096
	s_waitcnt lgkmcnt(3)
	v_mfma_f32_16x16x32_bf16 v[96:99], v[204:207], v[128:131], v[96:99]
	v_mfma_f32_16x16x32_bf16 v[104:107], v[204:207], v[132:135], v[104:107]
	v_mfma_f32_16x16x32_bf16 v[32:35], v[204:207], v[136:139], v[32:35]
	v_mfma_f32_16x16x32_bf16 v[40:43], v[204:207], v[140:143], v[40:43]
	ds_read_b128 v[204:207], v246 offset:6144
	s_waitcnt lgkmcnt(3)
	v_mfma_f32_16x16x32_bf16 v[100:103], v[242:245], v[128:131], v[100:103]
	v_mfma_f32_16x16x32_bf16 v[108:111], v[242:245], v[132:135], v[108:111]
	v_mfma_f32_16x16x32_bf16 v[36:39], v[242:245], v[136:139], v[36:39]
	v_mfma_f32_16x16x32_bf16 v[44:47], v[242:245], v[140:143], v[44:47]
	ds_read_b128 v[242:245], v162 offset:6144
	s_waitcnt lgkmcnt(3)
	v_mfma_f32_16x16x32_bf16 v[80:83], v[196:199], v[128:131], v[80:83]
	v_mfma_f32_16x16x32_bf16 v[88:91], v[196:199], v[132:135], v[88:91]
	v_mfma_f32_16x16x32_bf16 v[16:19], v[196:199], v[136:139], v[16:19]
	v_mfma_f32_16x16x32_bf16 v[24:27], v[196:199], v[140:143], v[24:27]
	s_waitcnt lgkmcnt(2)
	v_mfma_f32_16x16x32_bf16 v[84:87], v[200:203], v[128:131], v[84:87]
	v_mfma_f32_16x16x32_bf16 v[92:95], v[200:203], v[132:135], v[92:95]
	v_mfma_f32_16x16x32_bf16 v[20:23], v[200:203], v[136:139], v[20:23]
	v_mfma_f32_16x16x32_bf16 v[28:31], v[200:203], v[140:143], v[28:31]
	s_waitcnt lgkmcnt(1)
	v_mfma_f32_16x16x32_bf16 v[64:67], v[204:207], v[128:131], v[64:67]
	v_mfma_f32_16x16x32_bf16 v[72:75], v[204:207], v[132:135], v[72:75]
	v_mfma_f32_16x16x32_bf16 v[0:3], v[204:207], v[136:139], v[0:3]
	v_mfma_f32_16x16x32_bf16 v[8:11], v[204:207], v[140:143], v[8:11]
	s_waitcnt lgkmcnt(0)
	v_mfma_f32_16x16x32_bf16 v[68:71], v[242:245], v[128:131], v[68:71]
	v_mfma_f32_16x16x32_bf16 v[76:79], v[242:245], v[132:135], v[76:79]
	v_mfma_f32_16x16x32_bf16 v[4:7], v[242:245], v[136:139], v[4:7]
	v_mfma_f32_16x16x32_bf16 v[12:15], v[242:245], v[140:143], v[12:15]
	global_load_dwordx4 v[128:131], v[248:249], off
	global_load_dwordx4 v[132:135], v[248:249], off offset:256
	global_load_dwordx4 v[136:139], v[250:251], off
	global_load_dwordx4 v[140:143], v[250:251], off offset:256
	s_waitcnt vmcnt(10)
	s_barrier
	s_add_i32 s9, s3, 3
	s_lshl_b32 s96, s9, 13
	s_mov_b32 m0, vcc_lo
	v_lshl_add_u64 v[160:161], v[188:189], 0, s[96:97]
	global_load_lds_dwordx4 v[160:161], off
	global_load_lds_dwordx4 v[160:161], off offset:1024
	ds_read_b128 v[196:199], v246 offset:8192
	ds_read_b128 v[200:203], v162 offset:8192
	ds_read_b128 v[204:207], v246 offset:10240
	ds_read_b128 v[242:245], v162 offset:10240
	s_add_i32 s9, s3, 3
	s_lshl_b32 s96, s9, 11
	v_lshl_add_u64 v[248:249], v[184:185], 0, s[96:97]
	v_lshl_add_u64 v[250:251], v[186:187], 0, s[96:97]
	s_waitcnt vmcnt(8) lgkmcnt(3)
	v_mfma_f32_16x16x32_bf16 v[112:115], v[196:199], v[144:147], v[112:115]
	v_mfma_f32_16x16x32_bf16 v[120:123], v[196:199], v[148:151], v[120:123]
	v_mfma_f32_16x16x32_bf16 v[48:51], v[196:199], v[152:155], v[48:51]
	v_mfma_f32_16x16x32_bf16 v[56:59], v[196:199], v[156:159], v[56:59]
	ds_read_b128 v[196:199], v246 offset:12288
	s_waitcnt lgkmcnt(3)
	v_mfma_f32_16x16x32_bf16 v[116:119], v[200:203], v[144:147], v[116:119]
	v_mfma_f32_16x16x32_bf16 v[124:127], v[200:203], v[148:151], v[124:127]
	v_mfma_f32_16x16x32_bf16 v[52:55], v[200:203], v[152:155], v[52:55]
	v_mfma_f32_16x16x32_bf16 v[60:63], v[200:203], v[156:159], v[60:63]
	ds_read_b128 v[200:203], v162 offset:12288
	s_waitcnt lgkmcnt(3)
	v_mfma_f32_16x16x32_bf16 v[96:99], v[204:207], v[144:147], v[96:99]
	v_mfma_f32_16x16x32_bf16 v[104:107], v[204:207], v[148:151], v[104:107]
	v_mfma_f32_16x16x32_bf16 v[32:35], v[204:207], v[152:155], v[32:35]
	v_mfma_f32_16x16x32_bf16 v[40:43], v[204:207], v[156:159], v[40:43]
	ds_read_b128 v[204:207], v246 offset:14336
	s_waitcnt lgkmcnt(3)
	v_mfma_f32_16x16x32_bf16 v[100:103], v[242:245], v[144:147], v[100:103]
	v_mfma_f32_16x16x32_bf16 v[108:111], v[242:245], v[148:151], v[108:111]
	v_mfma_f32_16x16x32_bf16 v[36:39], v[242:245], v[152:155], v[36:39]
	v_mfma_f32_16x16x32_bf16 v[44:47], v[242:245], v[156:159], v[44:47]
	ds_read_b128 v[242:245], v162 offset:14336
	s_waitcnt lgkmcnt(3)
	v_mfma_f32_16x16x32_bf16 v[80:83], v[196:199], v[144:147], v[80:83]
	v_mfma_f32_16x16x32_bf16 v[88:91], v[196:199], v[148:151], v[88:91]
	v_mfma_f32_16x16x32_bf16 v[16:19], v[196:199], v[152:155], v[16:19]
	v_mfma_f32_16x16x32_bf16 v[24:27], v[196:199], v[156:159], v[24:27]
	s_waitcnt lgkmcnt(2)
	v_mfma_f32_16x16x32_bf16 v[84:87], v[200:203], v[144:147], v[84:87]
	v_mfma_f32_16x16x32_bf16 v[92:95], v[200:203], v[148:151], v[92:95]
	v_mfma_f32_16x16x32_bf16 v[20:23], v[200:203], v[152:155], v[20:23]
	v_mfma_f32_16x16x32_bf16 v[28:31], v[200:203], v[156:159], v[28:31]
	s_waitcnt lgkmcnt(1)
	v_mfma_f32_16x16x32_bf16 v[64:67], v[204:207], v[144:147], v[64:67]
	v_mfma_f32_16x16x32_bf16 v[72:75], v[204:207], v[148:151], v[72:75]
	v_mfma_f32_16x16x32_bf16 v[0:3], v[204:207], v[152:155], v[0:3]
	v_mfma_f32_16x16x32_bf16 v[8:11], v[204:207], v[156:159], v[8:11]
	s_waitcnt lgkmcnt(0)
	v_mfma_f32_16x16x32_bf16 v[68:71], v[242:245], v[144:147], v[68:71]
	v_mfma_f32_16x16x32_bf16 v[76:79], v[242:245], v[148:151], v[76:79]
	v_mfma_f32_16x16x32_bf16 v[4:7], v[242:245], v[152:155], v[4:7]
	v_mfma_f32_16x16x32_bf16 v[12:15], v[242:245], v[156:159], v[12:15]
	global_load_dwordx4 v[144:147], v[248:249], off
	global_load_dwordx4 v[148:151], v[248:249], off offset:256
	global_load_dwordx4 v[152:155], v[250:251], off
	global_load_dwordx4 v[156:159], v[250:251], off offset:256
	s_waitcnt vmcnt(10)
	s_barrier
	s_add_i32 s9, s3, 4
	s_lshl_b32 s96, s9, 13
	s_add_i32 m0, vcc_lo, 8192
	v_lshl_add_u64 v[160:161], v[188:189], 0, s[96:97]
	global_load_lds_dwordx4 v[160:161], off
	global_load_lds_dwordx4 v[160:161], off offset:1024
	ds_read_b128 v[196:199], v246 offset:16384
	ds_read_b128 v[200:203], v162 offset:16384
	ds_read_b128 v[204:207], v246 offset:18432
	ds_read_b128 v[242:245], v162 offset:18432
	s_add_i32 s9, s3, 4
	s_lshl_b32 s96, s9, 11
	v_lshl_add_u64 v[248:249], v[184:185], 0, s[96:97]
	v_lshl_add_u64 v[250:251], v[186:187], 0, s[96:97]
	s_waitcnt vmcnt(8) lgkmcnt(3)
	v_mfma_f32_16x16x32_bf16 v[112:115], v[196:199], v[128:131], v[112:115]
	v_mfma_f32_16x16x32_bf16 v[120:123], v[196:199], v[132:135], v[120:123]
	v_mfma_f32_16x16x32_bf16 v[48:51], v[196:199], v[136:139], v[48:51]
	v_mfma_f32_16x16x32_bf16 v[56:59], v[196:199], v[140:143], v[56:59]
	ds_read_b128 v[196:199], v246 offset:20480
	s_waitcnt lgkmcnt(3)
	v_mfma_f32_16x16x32_bf16 v[116:119], v[200:203], v[128:131], v[116:119]
	v_mfma_f32_16x16x32_bf16 v[124:127], v[200:203], v[132:135], v[124:127]
	v_mfma_f32_16x16x32_bf16 v[52:55], v[200:203], v[136:139], v[52:55]
	v_mfma_f32_16x16x32_bf16 v[60:63], v[200:203], v[140:143], v[60:63]
	ds_read_b128 v[200:203], v162 offset:20480
	s_waitcnt lgkmcnt(3)
	v_mfma_f32_16x16x32_bf16 v[96:99], v[204:207], v[128:131], v[96:99]
	v_mfma_f32_16x16x32_bf16 v[104:107], v[204:207], v[132:135], v[104:107]
	v_mfma_f32_16x16x32_bf16 v[32:35], v[204:207], v[136:139], v[32:35]
	v_mfma_f32_16x16x32_bf16 v[40:43], v[204:207], v[140:143], v[40:43]
	ds_read_b128 v[204:207], v246 offset:22528
	s_waitcnt lgkmcnt(3)
	v_mfma_f32_16x16x32_bf16 v[100:103], v[242:245], v[128:131], v[100:103]
	v_mfma_f32_16x16x32_bf16 v[108:111], v[242:245], v[132:135], v[108:111]
	v_mfma_f32_16x16x32_bf16 v[36:39], v[242:245], v[136:139], v[36:39]
	v_mfma_f32_16x16x32_bf16 v[44:47], v[242:245], v[140:143], v[44:47]
	ds_read_b128 v[242:245], v162 offset:22528
	s_waitcnt lgkmcnt(3)
	v_mfma_f32_16x16x32_bf16 v[80:83], v[196:199], v[128:131], v[80:83]
	v_mfma_f32_16x16x32_bf16 v[88:91], v[196:199], v[132:135], v[88:91]
	v_mfma_f32_16x16x32_bf16 v[16:19], v[196:199], v[136:139], v[16:19]
	v_mfma_f32_16x16x32_bf16 v[24:27], v[196:199], v[140:143], v[24:27]
	s_waitcnt lgkmcnt(2)
	v_mfma_f32_16x16x32_bf16 v[84:87], v[200:203], v[128:131], v[84:87]
	v_mfma_f32_16x16x32_bf16 v[92:95], v[200:203], v[132:135], v[92:95]
	v_mfma_f32_16x16x32_bf16 v[20:23], v[200:203], v[136:139], v[20:23]
	v_mfma_f32_16x16x32_bf16 v[28:31], v[200:203], v[140:143], v[28:31]
	s_waitcnt lgkmcnt(1)
	v_mfma_f32_16x16x32_bf16 v[64:67], v[204:207], v[128:131], v[64:67]
	v_mfma_f32_16x16x32_bf16 v[72:75], v[204:207], v[132:135], v[72:75]
	v_mfma_f32_16x16x32_bf16 v[0:3], v[204:207], v[136:139], v[0:3]
	v_mfma_f32_16x16x32_bf16 v[8:11], v[204:207], v[140:143], v[8:11]
	s_waitcnt lgkmcnt(0)
	v_mfma_f32_16x16x32_bf16 v[68:71], v[242:245], v[128:131], v[68:71]
	v_mfma_f32_16x16x32_bf16 v[76:79], v[242:245], v[132:135], v[76:79]
	v_mfma_f32_16x16x32_bf16 v[4:7], v[242:245], v[136:139], v[4:7]
	v_mfma_f32_16x16x32_bf16 v[12:15], v[242:245], v[140:143], v[12:15]
	global_load_dwordx4 v[128:131], v[248:249], off
	global_load_dwordx4 v[132:135], v[248:249], off offset:256
	global_load_dwordx4 v[136:139], v[250:251], off
	global_load_dwordx4 v[140:143], v[250:251], off offset:256
	s_waitcnt vmcnt(10)
	s_barrier
	s_add_i32 s9, s3, 5
	s_lshl_b32 s96, s9, 13
	s_add_i32 m0, vcc_lo, 16384
	v_lshl_add_u64 v[160:161], v[188:189], 0, s[96:97]
	global_load_lds_dwordx4 v[160:161], off
	global_load_lds_dwordx4 v[160:161], off offset:1024
	ds_read_b128 v[196:199], v246 offset:0
	ds_read_b128 v[200:203], v162 offset:0
	ds_read_b128 v[204:207], v246 offset:2048
	ds_read_b128 v[242:245], v162 offset:2048
	s_add_i32 s9, s3, 5
	s_lshl_b32 s96, s9, 11
	v_lshl_add_u64 v[248:249], v[184:185], 0, s[96:97]
	v_lshl_add_u64 v[250:251], v[186:187], 0, s[96:97]
	s_waitcnt vmcnt(8) lgkmcnt(3)
	v_mfma_f32_16x16x32_bf16 v[112:115], v[196:199], v[144:147], v[112:115]
	v_mfma_f32_16x16x32_bf16 v[120:123], v[196:199], v[148:151], v[120:123]
	v_mfma_f32_16x16x32_bf16 v[48:51], v[196:199], v[152:155], v[48:51]
	v_mfma_f32_16x16x32_bf16 v[56:59], v[196:199], v[156:159], v[56:59]
	ds_read_b128 v[196:199], v246 offset:4096
	s_waitcnt lgkmcnt(3)
	v_mfma_f32_16x16x32_bf16 v[116:119], v[200:203], v[144:147], v[116:119]
	v_mfma_f32_16x16x32_bf16 v[124:127], v[200:203], v[148:151], v[124:127]
	v_mfma_f32_16x16x32_bf16 v[52:55], v[200:203], v[152:155], v[52:55]
	v_mfma_f32_16x16x32_bf16 v[60:63], v[200:203], v[156:159], v[60:63]
	ds_read_b128 v[200:203], v162 offset:4096
	s_waitcnt lgkmcnt(3)
	v_mfma_f32_16x16x32_bf16 v[96:99], v[204:207], v[144:147], v[96:99]
	v_mfma_f32_16x16x32_bf16 v[104:107], v[204:207], v[148:151], v[104:107]
	v_mfma_f32_16x16x32_bf16 v[32:35], v[204:207], v[152:155], v[32:35]
	v_mfma_f32_16x16x32_bf16 v[40:43], v[204:207], v[156:159], v[40:43]
	ds_read_b128 v[204:207], v246 offset:6144
	s_waitcnt lgkmcnt(3)
	v_mfma_f32_16x16x32_bf16 v[100:103], v[242:245], v[144:147], v[100:103]
	v_mfma_f32_16x16x32_bf16 v[108:111], v[242:245], v[148:151], v[108:111]
	v_mfma_f32_16x16x32_bf16 v[36:39], v[242:245], v[152:155], v[36:39]
	v_mfma_f32_16x16x32_bf16 v[44:47], v[242:245], v[156:159], v[44:47]
	ds_read_b128 v[242:245], v162 offset:6144
	s_waitcnt lgkmcnt(3)
	v_mfma_f32_16x16x32_bf16 v[80:83], v[196:199], v[144:147], v[80:83]
	v_mfma_f32_16x16x32_bf16 v[88:91], v[196:199], v[148:151], v[88:91]
	v_mfma_f32_16x16x32_bf16 v[16:19], v[196:199], v[152:155], v[16:19]
	v_mfma_f32_16x16x32_bf16 v[24:27], v[196:199], v[156:159], v[24:27]
	s_waitcnt lgkmcnt(2)
	v_mfma_f32_16x16x32_bf16 v[84:87], v[200:203], v[144:147], v[84:87]
	v_mfma_f32_16x16x32_bf16 v[92:95], v[200:203], v[148:151], v[92:95]
	v_mfma_f32_16x16x32_bf16 v[20:23], v[200:203], v[152:155], v[20:23]
	v_mfma_f32_16x16x32_bf16 v[28:31], v[200:203], v[156:159], v[28:31]
	s_waitcnt lgkmcnt(1)
	v_mfma_f32_16x16x32_bf16 v[64:67], v[204:207], v[144:147], v[64:67]
	v_mfma_f32_16x16x32_bf16 v[72:75], v[204:207], v[148:151], v[72:75]
	v_mfma_f32_16x16x32_bf16 v[0:3], v[204:207], v[152:155], v[0:3]
	v_mfma_f32_16x16x32_bf16 v[8:11], v[204:207], v[156:159], v[8:11]
	s_waitcnt lgkmcnt(0)
	v_mfma_f32_16x16x32_bf16 v[68:71], v[242:245], v[144:147], v[68:71]
	v_mfma_f32_16x16x32_bf16 v[76:79], v[242:245], v[148:151], v[76:79]
	v_mfma_f32_16x16x32_bf16 v[4:7], v[242:245], v[152:155], v[4:7]
	v_mfma_f32_16x16x32_bf16 v[12:15], v[242:245], v[156:159], v[12:15]
	global_load_dwordx4 v[144:147], v[248:249], off
	global_load_dwordx4 v[148:151], v[248:249], off offset:256
	global_load_dwordx4 v[152:155], v[250:251], off
	global_load_dwordx4 v[156:159], v[250:251], off offset:256
	s_waitcnt vmcnt(10)
	s_barrier
	s_add_i32 s9, s3, 6
	s_lshl_b32 s96, s9, 13
	s_mov_b32 m0, vcc_lo
	v_lshl_add_u64 v[160:161], v[188:189], 0, s[96:97]
	global_load_lds_dwordx4 v[160:161], off
	global_load_lds_dwordx4 v[160:161], off offset:1024
	ds_read_b128 v[196:199], v246 offset:8192
	ds_read_b128 v[200:203], v162 offset:8192
	ds_read_b128 v[204:207], v246 offset:10240
	ds_read_b128 v[242:245], v162 offset:10240
	s_add_i32 s9, s3, 6
	s_lshl_b32 s96, s9, 11
	v_lshl_add_u64 v[248:249], v[184:185], 0, s[96:97]
	v_lshl_add_u64 v[250:251], v[186:187], 0, s[96:97]
	s_waitcnt vmcnt(8) lgkmcnt(3)
	v_mfma_f32_16x16x32_bf16 v[112:115], v[196:199], v[128:131], v[112:115]
	v_mfma_f32_16x16x32_bf16 v[120:123], v[196:199], v[132:135], v[120:123]
	v_mfma_f32_16x16x32_bf16 v[48:51], v[196:199], v[136:139], v[48:51]
	v_mfma_f32_16x16x32_bf16 v[56:59], v[196:199], v[140:143], v[56:59]
	ds_read_b128 v[196:199], v246 offset:12288
	s_waitcnt lgkmcnt(3)
	v_mfma_f32_16x16x32_bf16 v[116:119], v[200:203], v[128:131], v[116:119]
	v_mfma_f32_16x16x32_bf16 v[124:127], v[200:203], v[132:135], v[124:127]
	v_mfma_f32_16x16x32_bf16 v[52:55], v[200:203], v[136:139], v[52:55]
	v_mfma_f32_16x16x32_bf16 v[60:63], v[200:203], v[140:143], v[60:63]
	ds_read_b128 v[200:203], v162 offset:12288
	s_waitcnt lgkmcnt(3)
	v_mfma_f32_16x16x32_bf16 v[96:99], v[204:207], v[128:131], v[96:99]
	v_mfma_f32_16x16x32_bf16 v[104:107], v[204:207], v[132:135], v[104:107]
	v_mfma_f32_16x16x32_bf16 v[32:35], v[204:207], v[136:139], v[32:35]
	v_mfma_f32_16x16x32_bf16 v[40:43], v[204:207], v[140:143], v[40:43]
	ds_read_b128 v[204:207], v246 offset:14336
	s_waitcnt lgkmcnt(3)
	v_mfma_f32_16x16x32_bf16 v[100:103], v[242:245], v[128:131], v[100:103]
	v_mfma_f32_16x16x32_bf16 v[108:111], v[242:245], v[132:135], v[108:111]
	v_mfma_f32_16x16x32_bf16 v[36:39], v[242:245], v[136:139], v[36:39]
	v_mfma_f32_16x16x32_bf16 v[44:47], v[242:245], v[140:143], v[44:47]
	ds_read_b128 v[242:245], v162 offset:14336
	s_waitcnt lgkmcnt(3)
	v_mfma_f32_16x16x32_bf16 v[80:83], v[196:199], v[128:131], v[80:83]
	v_mfma_f32_16x16x32_bf16 v[88:91], v[196:199], v[132:135], v[88:91]
	v_mfma_f32_16x16x32_bf16 v[16:19], v[196:199], v[136:139], v[16:19]
	v_mfma_f32_16x16x32_bf16 v[24:27], v[196:199], v[140:143], v[24:27]
	s_waitcnt lgkmcnt(2)
	v_mfma_f32_16x16x32_bf16 v[84:87], v[200:203], v[128:131], v[84:87]
	v_mfma_f32_16x16x32_bf16 v[92:95], v[200:203], v[132:135], v[92:95]
	v_mfma_f32_16x16x32_bf16 v[20:23], v[200:203], v[136:139], v[20:23]
	v_mfma_f32_16x16x32_bf16 v[28:31], v[200:203], v[140:143], v[28:31]
	s_waitcnt lgkmcnt(1)
	v_mfma_f32_16x16x32_bf16 v[64:67], v[204:207], v[128:131], v[64:67]
	v_mfma_f32_16x16x32_bf16 v[72:75], v[204:207], v[132:135], v[72:75]
	v_mfma_f32_16x16x32_bf16 v[0:3], v[204:207], v[136:139], v[0:3]
	v_mfma_f32_16x16x32_bf16 v[8:11], v[204:207], v[140:143], v[8:11]
	s_waitcnt lgkmcnt(0)
	v_mfma_f32_16x16x32_bf16 v[68:71], v[242:245], v[128:131], v[68:71]
	v_mfma_f32_16x16x32_bf16 v[76:79], v[242:245], v[132:135], v[76:79]
	v_mfma_f32_16x16x32_bf16 v[4:7], v[242:245], v[136:139], v[4:7]
	v_mfma_f32_16x16x32_bf16 v[12:15], v[242:245], v[140:143], v[12:15]
	global_load_dwordx4 v[128:131], v[248:249], off
	global_load_dwordx4 v[132:135], v[248:249], off offset:256
	global_load_dwordx4 v[136:139], v[250:251], off
	global_load_dwordx4 v[140:143], v[250:251], off offset:256
	s_waitcnt vmcnt(10)
	s_barrier
	s_add_i32 s9, s3, 7
	s_lshl_b32 s96, s9, 13
	s_add_i32 m0, vcc_lo, 8192
	v_lshl_add_u64 v[160:161], v[188:189], 0, s[96:97]
	global_load_lds_dwordx4 v[160:161], off
	global_load_lds_dwordx4 v[160:161], off offset:1024
	ds_read_b128 v[196:199], v246 offset:16384
	ds_read_b128 v[200:203], v162 offset:16384
	ds_read_b128 v[204:207], v246 offset:18432
	ds_read_b128 v[242:245], v162 offset:18432
	s_add_i32 s9, s3, 7
	s_lshl_b32 s96, s9, 11
	v_lshl_add_u64 v[248:249], v[184:185], 0, s[96:97]
	v_lshl_add_u64 v[250:251], v[186:187], 0, s[96:97]
	s_waitcnt vmcnt(8) lgkmcnt(3)
	v_mfma_f32_16x16x32_bf16 v[112:115], v[196:199], v[144:147], v[112:115]
	v_mfma_f32_16x16x32_bf16 v[120:123], v[196:199], v[148:151], v[120:123]
	v_mfma_f32_16x16x32_bf16 v[48:51], v[196:199], v[152:155], v[48:51]
	v_mfma_f32_16x16x32_bf16 v[56:59], v[196:199], v[156:159], v[56:59]
	ds_read_b128 v[196:199], v246 offset:20480
	s_waitcnt lgkmcnt(3)
	v_mfma_f32_16x16x32_bf16 v[116:119], v[200:203], v[144:147], v[116:119]
	v_mfma_f32_16x16x32_bf16 v[124:127], v[200:203], v[148:151], v[124:127]
	v_mfma_f32_16x16x32_bf16 v[52:55], v[200:203], v[152:155], v[52:55]
	v_mfma_f32_16x16x32_bf16 v[60:63], v[200:203], v[156:159], v[60:63]
	ds_read_b128 v[200:203], v162 offset:20480
	s_waitcnt lgkmcnt(3)
	v_mfma_f32_16x16x32_bf16 v[96:99], v[204:207], v[144:147], v[96:99]
	v_mfma_f32_16x16x32_bf16 v[104:107], v[204:207], v[148:151], v[104:107]
	v_mfma_f32_16x16x32_bf16 v[32:35], v[204:207], v[152:155], v[32:35]
	v_mfma_f32_16x16x32_bf16 v[40:43], v[204:207], v[156:159], v[40:43]
	ds_read_b128 v[204:207], v246 offset:22528
	s_waitcnt lgkmcnt(3)
	v_mfma_f32_16x16x32_bf16 v[100:103], v[242:245], v[144:147], v[100:103]
	v_mfma_f32_16x16x32_bf16 v[108:111], v[242:245], v[148:151], v[108:111]
	v_mfma_f32_16x16x32_bf16 v[36:39], v[242:245], v[152:155], v[36:39]
	v_mfma_f32_16x16x32_bf16 v[44:47], v[242:245], v[156:159], v[44:47]
	ds_read_b128 v[242:245], v162 offset:22528
	s_waitcnt lgkmcnt(3)
	v_mfma_f32_16x16x32_bf16 v[80:83], v[196:199], v[144:147], v[80:83]
	v_mfma_f32_16x16x32_bf16 v[88:91], v[196:199], v[148:151], v[88:91]
	v_mfma_f32_16x16x32_bf16 v[16:19], v[196:199], v[152:155], v[16:19]
	v_mfma_f32_16x16x32_bf16 v[24:27], v[196:199], v[156:159], v[24:27]
	s_waitcnt lgkmcnt(2)
	v_mfma_f32_16x16x32_bf16 v[84:87], v[200:203], v[144:147], v[84:87]
	v_mfma_f32_16x16x32_bf16 v[92:95], v[200:203], v[148:151], v[92:95]
	v_mfma_f32_16x16x32_bf16 v[20:23], v[200:203], v[152:155], v[20:23]
	v_mfma_f32_16x16x32_bf16 v[28:31], v[200:203], v[156:159], v[28:31]
	s_waitcnt lgkmcnt(1)
	v_mfma_f32_16x16x32_bf16 v[64:67], v[204:207], v[144:147], v[64:67]
	v_mfma_f32_16x16x32_bf16 v[72:75], v[204:207], v[148:151], v[72:75]
	v_mfma_f32_16x16x32_bf16 v[0:3], v[204:207], v[152:155], v[0:3]
	v_mfma_f32_16x16x32_bf16 v[8:11], v[204:207], v[156:159], v[8:11]
	s_waitcnt lgkmcnt(0)
	v_mfma_f32_16x16x32_bf16 v[68:71], v[242:245], v[144:147], v[68:71]
	v_mfma_f32_16x16x32_bf16 v[76:79], v[242:245], v[148:151], v[76:79]
	v_mfma_f32_16x16x32_bf16 v[4:7], v[242:245], v[152:155], v[4:7]
	v_mfma_f32_16x16x32_bf16 v[12:15], v[242:245], v[156:159], v[12:15]
	global_load_dwordx4 v[144:147], v[248:249], off
	global_load_dwordx4 v[148:151], v[248:249], off offset:256
	global_load_dwordx4 v[152:155], v[250:251], off
	global_load_dwordx4 v[156:159], v[250:251], off offset:256
	s_waitcnt vmcnt(10)
	s_barrier
	s_add_i32 s3, s3, 6
	s_cmp_lt_u32 s3, 30
	s_cbranch_scc1 .Lg16_out_k
	ds_read_b128 v[196:199], v246 offset:0
	ds_read_b128 v[200:203], v162 offset:0
	ds_read_b128 v[204:207], v246 offset:2048
	ds_read_b128 v[242:245], v162 offset:2048
	s_waitcnt vmcnt(6) lgkmcnt(3)
	v_mfma_f32_16x16x32_bf16 v[112:115], v[196:199], v[128:131], v[112:115]
	v_mfma_f32_16x16x32_bf16 v[120:123], v[196:199], v[132:135], v[120:123]
	v_mfma_f32_16x16x32_bf16 v[48:51], v[196:199], v[136:139], v[48:51]
	v_mfma_f32_16x16x32_bf16 v[56:59], v[196:199], v[140:143], v[56:59]
	ds_read_b128 v[196:199], v246 offset:4096
	s_waitcnt lgkmcnt(3)
	v_mfma_f32_16x16x32_bf16 v[116:119], v[200:203], v[128:131], v[116:119]
	v_mfma_f32_16x16x32_bf16 v[124:127], v[200:203], v[132:135], v[124:127]
	v_mfma_f32_16x16x32_bf16 v[52:55], v[200:203], v[136:139], v[52:55]
	v_mfma_f32_16x16x32_bf16 v[60:63], v[200:203], v[140:143], v[60:63]
	ds_read_b128 v[200:203], v162 offset:4096
	s_waitcnt lgkmcnt(3)
	v_mfma_f32_16x16x32_bf16 v[96:99], v[204:207], v[128:131], v[96:99]
	v_mfma_f32_16x16x32_bf16 v[104:107], v[204:207], v[132:135], v[104:107]
	v_mfma_f32_16x16x32_bf16 v[32:35], v[204:207], v[136:139], v[32:35]
	v_mfma_f32_16x16x32_bf16 v[40:43], v[204:207], v[140:143], v[40:43]
	ds_read_b128 v[204:207], v246 offset:6144
	s_waitcnt lgkmcnt(3)
	v_mfma_f32_16x16x32_bf16 v[100:103], v[242:245], v[128:131], v[100:103]
	v_mfma_f32_16x16x32_bf16 v[108:111], v[242:245], v[132:135], v[108:111]
	v_mfma_f32_16x16x32_bf16 v[36:39], v[242:245], v[136:139], v[36:39]
	v_mfma_f32_16x16x32_bf16 v[44:47], v[242:245], v[140:143], v[44:47]
	ds_read_b128 v[242:245], v162 offset:6144
	s_waitcnt lgkmcnt(3)
	v_mfma_f32_16x16x32_bf16 v[80:83], v[196:199], v[128:131], v[80:83]
	v_mfma_f32_16x16x32_bf16 v[88:91], v[196:199], v[132:135], v[88:91]
	v_mfma_f32_16x16x32_bf16 v[16:19], v[196:199], v[136:139], v[16:19]
	v_mfma_f32_16x16x32_bf16 v[24:27], v[196:199], v[140:143], v[24:27]
	s_waitcnt lgkmcnt(2)
	v_mfma_f32_16x16x32_bf16 v[84:87], v[200:203], v[128:131], v[84:87]
	v_mfma_f32_16x16x32_bf16 v[92:95], v[200:203], v[132:135], v[92:95]
	v_mfma_f32_16x16x32_bf16 v[20:23], v[200:203], v[136:139], v[20:23]
	v_mfma_f32_16x16x32_bf16 v[28:31], v[200:203], v[140:143], v[28:31]
	s_waitcnt lgkmcnt(1)
	v_mfma_f32_16x16x32_bf16 v[64:67], v[204:207], v[128:131], v[64:67]
	v_mfma_f32_16x16x32_bf16 v[72:75], v[204:207], v[132:135], v[72:75]
	v_mfma_f32_16x16x32_bf16 v[0:3], v[204:207], v[136:139], v[0:3]
	v_mfma_f32_16x16x32_bf16 v[8:11], v[204:207], v[140:143], v[8:11]
	s_waitcnt lgkmcnt(0)
	v_mfma_f32_16x16x32_bf16 v[68:71], v[242:245], v[128:131], v[68:71]
	v_mfma_f32_16x16x32_bf16 v[76:79], v[242:245], v[132:135], v[76:79]
	v_mfma_f32_16x16x32_bf16 v[4:7], v[242:245], v[136:139], v[4:7]
	v_mfma_f32_16x16x32_bf16 v[12:15], v[242:245], v[140:143], v[12:15]
	s_waitcnt vmcnt(4)
	s_barrier
	ds_read_b128 v[196:199], v246 offset:8192
	ds_read_b128 v[200:203], v162 offset:8192
	ds_read_b128 v[204:207], v246 offset:10240
	ds_read_b128 v[242:245], v162 offset:10240
	s_waitcnt vmcnt(0) lgkmcnt(3)
	v_mfma_f32_16x16x32_bf16 v[112:115], v[196:199], v[144:147], v[112:115]
	v_mfma_f32_16x16x32_bf16 v[120:123], v[196:199], v[148:151], v[120:123]
	v_mfma_f32_16x16x32_bf16 v[48:51], v[196:199], v[152:155], v[48:51]
	v_mfma_f32_16x16x32_bf16 v[56:59], v[196:199], v[156:159], v[56:59]
	ds_read_b128 v[196:199], v246 offset:12288
	s_waitcnt lgkmcnt(3)
	v_mfma_f32_16x16x32_bf16 v[116:119], v[200:203], v[144:147], v[116:119]
	v_mfma_f32_16x16x32_bf16 v[124:127], v[200:203], v[148:151], v[124:127]
	v_mfma_f32_16x16x32_bf16 v[52:55], v[200:203], v[152:155], v[52:55]
	v_mfma_f32_16x16x32_bf16 v[60:63], v[200:203], v[156:159], v[60:63]
	ds_read_b128 v[200:203], v162 offset:12288
	s_waitcnt lgkmcnt(3)
	v_mfma_f32_16x16x32_bf16 v[96:99], v[204:207], v[144:147], v[96:99]
	v_mfma_f32_16x16x32_bf16 v[104:107], v[204:207], v[148:151], v[104:107]
	v_mfma_f32_16x16x32_bf16 v[32:35], v[204:207], v[152:155], v[32:35]
	v_mfma_f32_16x16x32_bf16 v[40:43], v[204:207], v[156:159], v[40:43]
	ds_read_b128 v[204:207], v246 offset:14336
	s_waitcnt lgkmcnt(3)
	v_mfma_f32_16x16x32_bf16 v[100:103], v[242:245], v[144:147], v[100:103]
	v_mfma_f32_16x16x32_bf16 v[108:111], v[242:245], v[148:151], v[108:111]
	v_mfma_f32_16x16x32_bf16 v[36:39], v[242:245], v[152:155], v[36:39]
	v_mfma_f32_16x16x32_bf16 v[44:47], v[242:245], v[156:159], v[44:47]
	ds_read_b128 v[242:245], v162 offset:14336
	s_waitcnt lgkmcnt(3)
	v_mfma_f32_16x16x32_bf16 v[80:83], v[196:199], v[144:147], v[80:83]
	v_mfma_f32_16x16x32_bf16 v[88:91], v[196:199], v[148:151], v[88:91]
	v_mfma_f32_16x16x32_bf16 v[16:19], v[196:199], v[152:155], v[16:19]
	v_mfma_f32_16x16x32_bf16 v[24:27], v[196:199], v[156:159], v[24:27]
	s_waitcnt lgkmcnt(2)
	v_mfma_f32_16x16x32_bf16 v[84:87], v[200:203], v[144:147], v[84:87]
	v_mfma_f32_16x16x32_bf16 v[92:95], v[200:203], v[148:151], v[92:95]
	v_mfma_f32_16x16x32_bf16 v[20:23], v[200:203], v[152:155], v[20:23]
	v_mfma_f32_16x16x32_bf16 v[28:31], v[200:203], v[156:159], v[28:31]
	s_waitcnt lgkmcnt(1)
	v_mfma_f32_16x16x32_bf16 v[64:67], v[204:207], v[144:147], v[64:67]
	v_mfma_f32_16x16x32_bf16 v[72:75], v[204:207], v[148:151], v[72:75]
	v_mfma_f32_16x16x32_bf16 v[0:3], v[204:207], v[152:155], v[0:3]
	v_mfma_f32_16x16x32_bf16 v[8:11], v[204:207], v[156:159], v[8:11]
	s_waitcnt lgkmcnt(0)
	v_mfma_f32_16x16x32_bf16 v[68:71], v[242:245], v[144:147], v[68:71]
	v_mfma_f32_16x16x32_bf16 v[76:79], v[242:245], v[148:151], v[76:79]
	v_mfma_f32_16x16x32_bf16 v[4:7], v[242:245], v[152:155], v[4:7]
	v_mfma_f32_16x16x32_bf16 v[12:15], v[242:245], v[156:159], v[12:15]
	s_barrier
	s_nop 7
	s_nop 1
	s_waitcnt vmcnt(0)
	s_waitcnt vmcnt(0)
	v_and_b32_e32 v188, 63, v179
	v_lshrrev_b32_e32 v189, 6, v179
	v_mul_u32_u24_e32 v249, 0x2400, v189
	v_mov_b32_e32 v250, v249
	v_and_b32_e32 v251, 15, v188
	v_mul_u32_u24_e32 v251, 0x110, v251
	v_add_u32_e32 v249, v249, v251
	v_lshrrev_b32_e32 v251, 4, v188
	v_lshl_add_u32 v249, v251, 5, v249
	v_lshrrev_b32_e32 v237, 4, v188
	v_mul_u32_u24_e32 v251, 0x110, v237
	v_add_u32_e32 v250, v250, v251
	v_and_b32_e32 v251, 15, v188
	v_lshlrev_b32_e32 v251, 4, v251
	v_add_u32_e32 v250, v250, v251
	v_lshl_add_u32 v237, v189, 6, v237
	v_lshl_add_u32 v237, v237, 12, v251
	v_add_u32_e32 v238, 16384, v237
	v_add_u32_e32 v239, 32768, v237
	v_add_u32_e32 v240, 49152, v237
	v_add_u32_e32 v241, 65536, v237
	v_add_u32_e32 v242, 81920, v237
	v_add_u32_e32 v243, 98304, v237
	v_add_u32_e32 v248, 114688, v237
	s_lshl_b32 s16, s8, 8
	s_lshl_b32 s18, s2, 9
	s_lshr_b32 s19, s8, 4
	v_readlane_b32 s12, v254, 38
	v_readlane_b32 s13, v254, 37
	v_readlane_b32 s14, v253, 46
	v_readlane_b32 s15, v253, 47
	v_readlane_b32 s22, v254, 40
	v_readlane_b32 s23, v254, 39
	s_add_i32 s17, s16, 0xffff8000
	s_cmpk_lt_u32 s8, 0x80
	s_cselect_b32 s12, s12, s22
	s_cselect_b32 s13, s13, s23
	s_cselect_b32 s14, s14, s62
	s_cselect_b32 s15, s15, s63
	s_cselect_b32 s19, s19, 8
	s_cselect_b32 s16, s16, s17
	s_mov_b32 s17, 0
	s_lshl_b64 s[16:17], s[16:17], 12
	s_add_u32 s16, s16, s18
	s_addc_u32 s17, s17, 0
	s_add_u32 s12, s12, s16
	s_addc_u32 s13, s13, s17
	s_add_u32 s14, s14, s16
	s_addc_u32 s15, s15, s17
	s_mul_i32 s19, s19, 0x6000
	s_add_u32 s20, s0, s19
	s_addc_u32 s21, s1, 0
	s_add_u32 s20, s20, s18
	s_addc_u32 s21, s21, 0
	global_load_dwordx4 v[244:247], v251, s[20:21]
	global_load_dwordx4 v[160:163], v237, s[12:13]
	global_load_dwordx4 v[164:167], v238, s[12:13]
	global_load_dwordx4 v[168:171], v239, s[12:13]
	global_load_dwordx4 v[172:175], v240, s[12:13]
	global_load_dwordx4 v[196:199], v241, s[12:13]
	global_load_dwordx4 v[200:203], v242, s[12:13]
	global_load_dwordx4 v[204:207], v243, s[12:13]
	global_load_dwordx4 v[184:187], v248, s[12:13]
	ds_write_b128 v249, v[112:115]
	ds_write_b128 v249, v[116:119] offset:16
	ds_write_b128 v249, v[96:99] offset:128
	ds_write_b128 v249, v[100:103] offset:144
	ds_write_b128 v249, v[120:123] offset:4352
	ds_write_b128 v249, v[124:127] offset:4368
	ds_write_b128 v249, v[104:107] offset:4480
	ds_write_b128 v249, v[108:111] offset:4496
	s_waitcnt lgkmcnt(0)
	ds_read_b128 v[128:131], v250
	ds_read_b128 v[132:135], v250 offset:1088
	ds_read_b128 v[136:139], v250 offset:2176
	ds_read_b128 v[140:143], v250 offset:3264
	ds_read_b128 v[144:147], v250 offset:4352
	ds_read_b128 v[148:151], v250 offset:5440
	ds_read_b128 v[152:155], v250 offset:6528
	ds_read_b128 v[156:159], v250 offset:7616
	s_waitcnt vmcnt(7) lgkmcnt(7)
	v_fma_f32 v128, v244, v128, v160
	v_fma_f32 v129, v245, v129, v161
	v_fma_f32 v130, v246, v130, v162
	v_fma_f32 v131, v247, v131, v163
	global_store_dwordx4 v237, v[128:131], s[14:15] sc0 sc1 nt
	s_waitcnt vmcnt(7) lgkmcnt(6)
	v_fma_f32 v132, v244, v132, v164
	v_fma_f32 v133, v245, v133, v165
	v_fma_f32 v134, v246, v134, v166
	v_fma_f32 v135, v247, v135, v167
	global_store_dwordx4 v238, v[132:135], s[14:15] sc0 sc1 nt
	s_waitcnt vmcnt(7) lgkmcnt(5)
	v_fma_f32 v136, v244, v136, v168
	v_fma_f32 v137, v245, v137, v169
	v_fma_f32 v138, v246, v138, v170
	v_fma_f32 v139, v247, v139, v171
	global_store_dwordx4 v239, v[136:139], s[14:15] sc0 sc1 nt
	s_waitcnt vmcnt(7) lgkmcnt(4)
	v_fma_f32 v140, v244, v140, v172
	v_fma_f32 v141, v245, v141, v173
	v_fma_f32 v142, v246, v142, v174
	v_fma_f32 v143, v247, v143, v175
	global_store_dwordx4 v240, v[140:143], s[14:15] sc0 sc1 nt
	s_waitcnt vmcnt(7) lgkmcnt(3)
	v_fma_f32 v144, v244, v144, v196
	v_fma_f32 v145, v245, v145, v197
	v_fma_f32 v146, v246, v146, v198
	v_fma_f32 v147, v247, v147, v199
	global_store_dwordx4 v241, v[144:147], s[14:15] sc0 sc1 nt
	s_waitcnt vmcnt(7) lgkmcnt(2)
	v_fma_f32 v148, v244, v148, v200
	v_fma_f32 v149, v245, v149, v201
	v_fma_f32 v150, v246, v150, v202
	v_fma_f32 v151, v247, v151, v203
	global_store_dwordx4 v242, v[148:151], s[14:15] sc0 sc1 nt
	s_waitcnt vmcnt(7) lgkmcnt(1)
	v_fma_f32 v152, v244, v152, v204
	v_fma_f32 v153, v245, v153, v205
	v_fma_f32 v154, v246, v154, v206
	v_fma_f32 v155, v247, v155, v207
	global_store_dwordx4 v243, v[152:155], s[14:15] sc0 sc1 nt
	s_waitcnt vmcnt(7) lgkmcnt(0)
	v_fma_f32 v156, v244, v156, v184
	v_fma_f32 v157, v245, v157, v185
	v_fma_f32 v158, v246, v158, v186
	v_fma_f32 v159, v247, v159, v187
	global_store_dwordx4 v248, v[156:159], s[14:15] sc0 sc1 nt
	global_load_dwordx4 v[244:247], v251, s[20:21] offset:256
	global_load_dwordx4 v[160:163], v237, s[12:13] offset:256
	global_load_dwordx4 v[164:167], v238, s[12:13] offset:256
	global_load_dwordx4 v[168:171], v239, s[12:13] offset:256
	global_load_dwordx4 v[172:175], v240, s[12:13] offset:256
	global_load_dwordx4 v[196:199], v241, s[12:13] offset:256
	global_load_dwordx4 v[200:203], v242, s[12:13] offset:256
	global_load_dwordx4 v[204:207], v243, s[12:13] offset:256
	global_load_dwordx4 v[184:187], v248, s[12:13] offset:256
	ds_write_b128 v249, v[80:83]
	ds_write_b128 v249, v[84:87] offset:16
	ds_write_b128 v249, v[64:67] offset:128
	ds_write_b128 v249, v[68:71] offset:144
	ds_write_b128 v249, v[88:91] offset:4352
	ds_write_b128 v249, v[92:95] offset:4368
	ds_write_b128 v249, v[72:75] offset:4480
	ds_write_b128 v249, v[76:79] offset:4496
	s_waitcnt lgkmcnt(0)
	ds_read_b128 v[128:131], v250
	ds_read_b128 v[132:135], v250 offset:1088
	ds_read_b128 v[136:139], v250 offset:2176
	ds_read_b128 v[140:143], v250 offset:3264
	ds_read_b128 v[144:147], v250 offset:4352
	ds_read_b128 v[148:151], v250 offset:5440
	ds_read_b128 v[152:155], v250 offset:6528
	ds_read_b128 v[156:159], v250 offset:7616
	s_waitcnt vmcnt(7) lgkmcnt(7)
	v_fma_f32 v128, v244, v128, v160
	v_fma_f32 v129, v245, v129, v161
	v_fma_f32 v130, v246, v130, v162
	v_fma_f32 v131, v247, v131, v163
	global_store_dwordx4 v237, v[128:131], s[14:15] offset:256 sc0 sc1 nt
	s_waitcnt vmcnt(7) lgkmcnt(6)
	v_fma_f32 v132, v244, v132, v164
	v_fma_f32 v133, v245, v133, v165
	v_fma_f32 v134, v246, v134, v166
	v_fma_f32 v135, v247, v135, v167
	global_store_dwordx4 v238, v[132:135], s[14:15] offset:256 sc0 sc1 nt
	s_waitcnt vmcnt(7) lgkmcnt(5)
	v_fma_f32 v136, v244, v136, v168
	v_fma_f32 v137, v245, v137, v169
	v_fma_f32 v138, v246, v138, v170
	v_fma_f32 v139, v247, v139, v171
	global_store_dwordx4 v239, v[136:139], s[14:15] offset:256 sc0 sc1 nt
	s_waitcnt vmcnt(7) lgkmcnt(4)
	v_fma_f32 v140, v244, v140, v172
	v_fma_f32 v141, v245, v141, v173
	v_fma_f32 v142, v246, v142, v174
	v_fma_f32 v143, v247, v143, v175
	global_store_dwordx4 v240, v[140:143], s[14:15] offset:256 sc0 sc1 nt
	s_waitcnt vmcnt(7) lgkmcnt(3)
	v_fma_f32 v144, v244, v144, v196
	v_fma_f32 v145, v245, v145, v197
	v_fma_f32 v146, v246, v146, v198
	v_fma_f32 v147, v247, v147, v199
	global_store_dwordx4 v241, v[144:147], s[14:15] offset:256 sc0 sc1 nt
	s_waitcnt vmcnt(7) lgkmcnt(2)
	v_fma_f32 v148, v244, v148, v200
	v_fma_f32 v149, v245, v149, v201
	v_fma_f32 v150, v246, v150, v202
	v_fma_f32 v151, v247, v151, v203
	global_store_dwordx4 v242, v[148:151], s[14:15] offset:256 sc0 sc1 nt
	s_waitcnt vmcnt(7) lgkmcnt(1)
	v_fma_f32 v152, v244, v152, v204
	v_fma_f32 v153, v245, v153, v205
	v_fma_f32 v154, v246, v154, v206
	v_fma_f32 v155, v247, v155, v207
	global_store_dwordx4 v243, v[152:155], s[14:15] offset:256 sc0 sc1 nt
	s_waitcnt vmcnt(7) lgkmcnt(0)
	v_fma_f32 v156, v244, v156, v184
	v_fma_f32 v157, v245, v157, v185
	v_fma_f32 v158, v246, v158, v186
	v_fma_f32 v159, v247, v159, v187
	global_store_dwordx4 v248, v[156:159], s[14:15] offset:256 sc0 sc1 nt
	s_add_u32 s12, s12, 0x20000
	s_addc_u32 s13, s13, 0
	s_add_u32 s14, s14, 0x20000
	s_addc_u32 s15, s15, 0
	global_load_dwordx4 v[244:247], v251, s[20:21]
	global_load_dwordx4 v[160:163], v237, s[12:13]
	global_load_dwordx4 v[164:167], v238, s[12:13]
	global_load_dwordx4 v[168:171], v239, s[12:13]
	global_load_dwordx4 v[172:175], v240, s[12:13]
	global_load_dwordx4 v[196:199], v241, s[12:13]
	global_load_dwordx4 v[200:203], v242, s[12:13]
	global_load_dwordx4 v[204:207], v243, s[12:13]
	global_load_dwordx4 v[184:187], v248, s[12:13]
	ds_write_b128 v249, v[48:51]
	ds_write_b128 v249, v[52:55] offset:16
	ds_write_b128 v249, v[32:35] offset:128
	ds_write_b128 v249, v[36:39] offset:144
	ds_write_b128 v249, v[56:59] offset:4352
	ds_write_b128 v249, v[60:63] offset:4368
	ds_write_b128 v249, v[40:43] offset:4480
	ds_write_b128 v249, v[44:47] offset:4496
	s_waitcnt lgkmcnt(0)
	ds_read_b128 v[128:131], v250
	ds_read_b128 v[132:135], v250 offset:1088
	ds_read_b128 v[136:139], v250 offset:2176
	ds_read_b128 v[140:143], v250 offset:3264
	ds_read_b128 v[144:147], v250 offset:4352
	ds_read_b128 v[148:151], v250 offset:5440
	ds_read_b128 v[152:155], v250 offset:6528
	ds_read_b128 v[156:159], v250 offset:7616
	s_waitcnt vmcnt(7) lgkmcnt(7)
	v_fma_f32 v128, v244, v128, v160
	v_fma_f32 v129, v245, v129, v161
	v_fma_f32 v130, v246, v130, v162
	v_fma_f32 v131, v247, v131, v163
	global_store_dwordx4 v237, v[128:131], s[14:15] sc0 sc1 nt
	s_waitcnt vmcnt(7) lgkmcnt(6)
	v_fma_f32 v132, v244, v132, v164
	v_fma_f32 v133, v245, v133, v165
	v_fma_f32 v134, v246, v134, v166
	v_fma_f32 v135, v247, v135, v167
	global_store_dwordx4 v238, v[132:135], s[14:15] sc0 sc1 nt
	s_waitcnt vmcnt(7) lgkmcnt(5)
	v_fma_f32 v136, v244, v136, v168
	v_fma_f32 v137, v245, v137, v169
	v_fma_f32 v138, v246, v138, v170
	v_fma_f32 v139, v247, v139, v171
	global_store_dwordx4 v239, v[136:139], s[14:15] sc0 sc1 nt
	s_waitcnt vmcnt(7) lgkmcnt(4)
	v_fma_f32 v140, v244, v140, v172
	v_fma_f32 v141, v245, v141, v173
	v_fma_f32 v142, v246, v142, v174
	v_fma_f32 v143, v247, v143, v175
	global_store_dwordx4 v240, v[140:143], s[14:15] sc0 sc1 nt
	s_waitcnt vmcnt(7) lgkmcnt(3)
	v_fma_f32 v144, v244, v144, v196
	v_fma_f32 v145, v245, v145, v197
	v_fma_f32 v146, v246, v146, v198
	v_fma_f32 v147, v247, v147, v199
	global_store_dwordx4 v241, v[144:147], s[14:15] sc0 sc1 nt
	s_waitcnt vmcnt(7) lgkmcnt(2)
	v_fma_f32 v148, v244, v148, v200
	v_fma_f32 v149, v245, v149, v201
	v_fma_f32 v150, v246, v150, v202
	v_fma_f32 v151, v247, v151, v203
	global_store_dwordx4 v242, v[148:151], s[14:15] sc0 sc1 nt
	s_waitcnt vmcnt(7) lgkmcnt(1)
	v_fma_f32 v152, v244, v152, v204
	v_fma_f32 v153, v245, v153, v205
	v_fma_f32 v154, v246, v154, v206
	v_fma_f32 v155, v247, v155, v207
	global_store_dwordx4 v243, v[152:155], s[14:15] sc0 sc1 nt
	s_waitcnt vmcnt(7) lgkmcnt(0)
	v_fma_f32 v156, v244, v156, v184
	v_fma_f32 v157, v245, v157, v185
	v_fma_f32 v158, v246, v158, v186
	v_fma_f32 v159, v247, v159, v187
	global_store_dwordx4 v248, v[156:159], s[14:15] sc0 sc1 nt
	global_load_dwordx4 v[244:247], v251, s[20:21] offset:256
	global_load_dwordx4 v[160:163], v237, s[12:13] offset:256
	global_load_dwordx4 v[164:167], v238, s[12:13] offset:256
	global_load_dwordx4 v[168:171], v239, s[12:13] offset:256
	global_load_dwordx4 v[172:175], v240, s[12:13] offset:256
	global_load_dwordx4 v[196:199], v241, s[12:13] offset:256
	global_load_dwordx4 v[200:203], v242, s[12:13] offset:256
	global_load_dwordx4 v[204:207], v243, s[12:13] offset:256
	global_load_dwordx4 v[184:187], v248, s[12:13] offset:256
	ds_write_b128 v249, v[16:19]
	ds_write_b128 v249, v[20:23] offset:16
	ds_write_b128 v249, v[0:3] offset:128
	ds_write_b128 v249, v[4:7] offset:144
	ds_write_b128 v249, v[24:27] offset:4352
	ds_write_b128 v249, v[28:31] offset:4368
	ds_write_b128 v249, v[8:11] offset:4480
	ds_write_b128 v249, v[12:15] offset:4496
	s_waitcnt lgkmcnt(0)
	ds_read_b128 v[128:131], v250
	ds_read_b128 v[132:135], v250 offset:1088
	ds_read_b128 v[136:139], v250 offset:2176
	ds_read_b128 v[140:143], v250 offset:3264
	ds_read_b128 v[144:147], v250 offset:4352
	ds_read_b128 v[148:151], v250 offset:5440
	ds_read_b128 v[152:155], v250 offset:6528
	ds_read_b128 v[156:159], v250 offset:7616
	s_waitcnt vmcnt(7) lgkmcnt(7)
	v_fma_f32 v128, v244, v128, v160
	v_fma_f32 v129, v245, v129, v161
	v_fma_f32 v130, v246, v130, v162
	v_fma_f32 v131, v247, v131, v163
	global_store_dwordx4 v237, v[128:131], s[14:15] offset:256 sc0 sc1 nt
	s_waitcnt vmcnt(7) lgkmcnt(6)
	v_fma_f32 v132, v244, v132, v164
	v_fma_f32 v133, v245, v133, v165
	v_fma_f32 v134, v246, v134, v166
	v_fma_f32 v135, v247, v135, v167
	global_store_dwordx4 v238, v[132:135], s[14:15] offset:256 sc0 sc1 nt
	s_waitcnt vmcnt(7) lgkmcnt(5)
	v_fma_f32 v136, v244, v136, v168
	v_fma_f32 v137, v245, v137, v169
	v_fma_f32 v138, v246, v138, v170
	v_fma_f32 v139, v247, v139, v171
	global_store_dwordx4 v239, v[136:139], s[14:15] offset:256 sc0 sc1 nt
	s_waitcnt vmcnt(7) lgkmcnt(4)
	v_fma_f32 v140, v244, v140, v172
	v_fma_f32 v141, v245, v141, v173
	v_fma_f32 v142, v246, v142, v174
	v_fma_f32 v143, v247, v143, v175
	global_store_dwordx4 v240, v[140:143], s[14:15] offset:256 sc0 sc1 nt
	s_waitcnt vmcnt(7) lgkmcnt(3)
	v_fma_f32 v144, v244, v144, v196
	v_fma_f32 v145, v245, v145, v197
	v_fma_f32 v146, v246, v146, v198
	v_fma_f32 v147, v247, v147, v199
	global_store_dwordx4 v241, v[144:147], s[14:15] offset:256 sc0 sc1 nt
	s_waitcnt vmcnt(7) lgkmcnt(2)
	v_fma_f32 v148, v244, v148, v200
	v_fma_f32 v149, v245, v149, v201
	v_fma_f32 v150, v246, v150, v202
	v_fma_f32 v151, v247, v151, v203
	global_store_dwordx4 v242, v[148:151], s[14:15] offset:256 sc0 sc1 nt
	s_waitcnt vmcnt(7) lgkmcnt(1)
	v_fma_f32 v152, v244, v152, v204
	v_fma_f32 v153, v245, v153, v205
	v_fma_f32 v154, v246, v154, v206
	v_fma_f32 v155, v247, v155, v207
	global_store_dwordx4 v243, v[152:155], s[14:15] offset:256 sc0 sc1 nt
	s_waitcnt vmcnt(7) lgkmcnt(0)
	v_fma_f32 v156, v244, v156, v184
	v_fma_f32 v157, v245, v157, v185
	v_fma_f32 v158, v246, v158, v186
	v_fma_f32 v159, v247, v159, v187
	global_store_dwordx4 v248, v[156:159], s[14:15] offset:256 sc0 sc1 nt
	s_waitcnt lgkmcnt(0)
	v_readlane_b32 s16, v254, 11
	s_andn2_b32 s17, s26, 63
	s_add_i32 s4, s4, s16
	s_cmp_lt_i32 s4, s17
	s_cbranch_scc0 .Lhx_out_left
	s_barrier
	s_branch .LBB0_923

.Lre_outh_h0:
	global_load_dwordx4 v[244:247], v251, s[20:21]
	global_load_dwordx4 v[160:163], v237, s[12:13]
	global_load_dwordx4 v[164:167], v238, s[12:13]
	global_load_dwordx4 v[168:171], v239, s[12:13]
	global_load_dwordx4 v[172:175], v240, s[12:13]
	global_load_dwordx4 v[196:199], v241, s[12:13]
	global_load_dwordx4 v[200:203], v242, s[12:13]
	global_load_dwordx4 v[204:207], v243, s[12:13]
	global_load_dwordx4 v[184:187], v248, s[12:13]
	ds_write_b128 v249, v[112:115]
	ds_write_b128 v249, v[116:119] offset:16
	ds_write_b128 v249, v[96:99] offset:128
	ds_write_b128 v249, v[100:103] offset:144
	ds_write_b128 v249, v[120:123] offset:4352
	ds_write_b128 v249, v[124:127] offset:4368
	ds_write_b128 v249, v[104:107] offset:4480
	ds_write_b128 v249, v[108:111] offset:4496
	s_waitcnt lgkmcnt(0)
	ds_read_b128 v[128:131], v250
	ds_read_b128 v[132:135], v250 offset:1088
	ds_read_b128 v[136:139], v250 offset:2176
	ds_read_b128 v[140:143], v250 offset:3264
	ds_read_b128 v[144:147], v250 offset:4352
	ds_read_b128 v[148:151], v250 offset:5440
	ds_read_b128 v[152:155], v250 offset:6528
	ds_read_b128 v[156:159], v250 offset:7616
	s_waitcnt vmcnt(7) lgkmcnt(7)
	v_fma_f32 v128, v244, v128, v160
	v_fma_f32 v129, v245, v129, v161
	v_fma_f32 v130, v246, v130, v162
	v_fma_f32 v131, v247, v131, v163
	global_store_dwordx4 v237, v[128:131], s[14:15] sc0 sc1 nt
	s_waitcnt vmcnt(7) lgkmcnt(6)
	v_fma_f32 v132, v244, v132, v164
	v_fma_f32 v133, v245, v133, v165
	v_fma_f32 v134, v246, v134, v166
	v_fma_f32 v135, v247, v135, v167
	global_store_dwordx4 v238, v[132:135], s[14:15] sc0 sc1 nt
	s_waitcnt vmcnt(7) lgkmcnt(5)
	v_fma_f32 v136, v244, v136, v168
	v_fma_f32 v137, v245, v137, v169
	v_fma_f32 v138, v246, v138, v170
	v_fma_f32 v139, v247, v139, v171
	global_store_dwordx4 v239, v[136:139], s[14:15] sc0 sc1 nt
	s_waitcnt vmcnt(7) lgkmcnt(4)
	v_fma_f32 v140, v244, v140, v172
	v_fma_f32 v141, v245, v141, v173
	v_fma_f32 v142, v246, v142, v174
	v_fma_f32 v143, v247, v143, v175
	global_store_dwordx4 v240, v[140:143], s[14:15] sc0 sc1 nt
	s_waitcnt vmcnt(7) lgkmcnt(3)
	v_fma_f32 v144, v244, v144, v196
	v_fma_f32 v145, v245, v145, v197
	v_fma_f32 v146, v246, v146, v198
	v_fma_f32 v147, v247, v147, v199
	global_store_dwordx4 v241, v[144:147], s[14:15] sc0 sc1 nt
	s_waitcnt vmcnt(7) lgkmcnt(2)
	v_fma_f32 v148, v244, v148, v200
	v_fma_f32 v149, v245, v149, v201
	v_fma_f32 v150, v246, v150, v202
	v_fma_f32 v151, v247, v151, v203
	global_store_dwordx4 v242, v[148:151], s[14:15] sc0 sc1 nt
	s_waitcnt vmcnt(7) lgkmcnt(1)
	v_fma_f32 v152, v244, v152, v204
	v_fma_f32 v153, v245, v153, v205
	v_fma_f32 v154, v246, v154, v206
	v_fma_f32 v155, v247, v155, v207
	global_store_dwordx4 v243, v[152:155], s[14:15] sc0 sc1 nt
	s_waitcnt vmcnt(7) lgkmcnt(0)
	v_fma_f32 v156, v244, v156, v184
	v_fma_f32 v157, v245, v157, v185
	v_fma_f32 v158, v246, v158, v186
	v_fma_f32 v159, v247, v159, v187
	global_store_dwordx4 v248, v[156:159], s[14:15] sc0 sc1 nt
	global_load_dwordx4 v[244:247], v251, s[20:21] offset:256
	global_load_dwordx4 v[160:163], v237, s[12:13] offset:256
	global_load_dwordx4 v[164:167], v238, s[12:13] offset:256
	global_load_dwordx4 v[168:171], v239, s[12:13] offset:256
	global_load_dwordx4 v[172:175], v240, s[12:13] offset:256
	global_load_dwordx4 v[196:199], v241, s[12:13] offset:256
	global_load_dwordx4 v[200:203], v242, s[12:13] offset:256
	global_load_dwordx4 v[204:207], v243, s[12:13] offset:256
	global_load_dwordx4 v[184:187], v248, s[12:13] offset:256
	ds_write_b128 v249, v[80:83]
	ds_write_b128 v249, v[84:87] offset:16
	ds_write_b128 v249, v[64:67] offset:128
	ds_write_b128 v249, v[68:71] offset:144
	ds_write_b128 v249, v[88:91] offset:4352
	ds_write_b128 v249, v[92:95] offset:4368
	ds_write_b128 v249, v[72:75] offset:4480
	ds_write_b128 v249, v[76:79] offset:4496
	s_waitcnt lgkmcnt(0)
	ds_read_b128 v[128:131], v250
	ds_read_b128 v[132:135], v250 offset:1088
	ds_read_b128 v[136:139], v250 offset:2176
	ds_read_b128 v[140:143], v250 offset:3264
	ds_read_b128 v[144:147], v250 offset:4352
	ds_read_b128 v[148:151], v250 offset:5440
	ds_read_b128 v[152:155], v250 offset:6528
	ds_read_b128 v[156:159], v250 offset:7616
	s_waitcnt vmcnt(7) lgkmcnt(7)
	v_fma_f32 v128, v244, v128, v160
	v_fma_f32 v129, v245, v129, v161
	v_fma_f32 v130, v246, v130, v162
	v_fma_f32 v131, v247, v131, v163
	global_store_dwordx4 v237, v[128:131], s[14:15] offset:256 sc0 sc1 nt
	s_waitcnt vmcnt(7) lgkmcnt(6)
	v_fma_f32 v132, v244, v132, v164
	v_fma_f32 v133, v245, v133, v165
	v_fma_f32 v134, v246, v134, v166
	v_fma_f32 v135, v247, v135, v167
	global_store_dwordx4 v238, v[132:135], s[14:15] offset:256 sc0 sc1 nt
	s_waitcnt vmcnt(7) lgkmcnt(5)
	v_fma_f32 v136, v244, v136, v168
	v_fma_f32 v137, v245, v137, v169
	v_fma_f32 v138, v246, v138, v170
	v_fma_f32 v139, v247, v139, v171
	global_store_dwordx4 v239, v[136:139], s[14:15] offset:256 sc0 sc1 nt
	s_waitcnt vmcnt(7) lgkmcnt(4)
	v_fma_f32 v140, v244, v140, v172
	v_fma_f32 v141, v245, v141, v173
	v_fma_f32 v142, v246, v142, v174
	v_fma_f32 v143, v247, v143, v175
	global_store_dwordx4 v240, v[140:143], s[14:15] offset:256 sc0 sc1 nt
	s_waitcnt vmcnt(7) lgkmcnt(3)
	v_fma_f32 v144, v244, v144, v196
	v_fma_f32 v145, v245, v145, v197
	v_fma_f32 v146, v246, v146, v198
	v_fma_f32 v147, v247, v147, v199
	global_store_dwordx4 v241, v[144:147], s[14:15] offset:256 sc0 sc1 nt
	s_waitcnt vmcnt(7) lgkmcnt(2)
	v_fma_f32 v148, v244, v148, v200
	v_fma_f32 v149, v245, v149, v201
	v_fma_f32 v150, v246, v150, v202
	v_fma_f32 v151, v247, v151, v203
	global_store_dwordx4 v242, v[148:151], s[14:15] offset:256 sc0 sc1 nt
	s_waitcnt vmcnt(7) lgkmcnt(1)
	v_fma_f32 v152, v244, v152, v204
	v_fma_f32 v153, v245, v153, v205
	v_fma_f32 v154, v246, v154, v206
	v_fma_f32 v155, v247, v155, v207
	global_store_dwordx4 v243, v[152:155], s[14:15] offset:256 sc0 sc1 nt
	s_waitcnt vmcnt(7) lgkmcnt(0)
	v_fma_f32 v156, v244, v156, v184
	v_fma_f32 v157, v245, v157, v185
	v_fma_f32 v158, v246, v158, v186
	v_fma_f32 v159, v247, v159, v187
	global_store_dwordx4 v248, v[156:159], s[14:15] offset:256 sc0 sc1 nt
	s_waitcnt lgkmcnt(0)
	s_mov_b32 s100, 0
	s_barrier
	s_branch .LBB0_926

.Lg16_gu_k:
	s_add_i32 s8, s1, 2
	s_lshl_b32 s96, s8, 13
	s_add_i32 m0, vcc_lo, 16384
	v_lshl_add_u64 v[160:161], v[188:189], 0, s[96:97]
	global_load_lds_dwordx4 v[160:161], off
	global_load_lds_dwordx4 v[160:161], off offset:1024
	ds_read_b128 v[196:199], v246 offset:0
	ds_read_b128 v[200:203], v162 offset:0
	ds_read_b128 v[204:207], v246 offset:2048
	ds_read_b128 v[242:245], v162 offset:2048
	s_add_i32 s8, s1, 2
	s_lshl_b32 s96, s8, 11
	v_lshl_add_u64 v[248:249], v[184:185], 0, s[96:97]
	v_lshl_add_u64 v[250:251], v[186:187], 0, s[96:97]
	s_waitcnt vmcnt(8) lgkmcnt(3)
	v_mfma_f32_16x16x32_bf16 v[112:115], v[196:199], v[128:131], v[112:115]
	v_mfma_f32_16x16x32_bf16 v[120:123], v[196:199], v[132:135], v[120:123]
	v_mfma_f32_16x16x32_bf16 v[80:83], v[196:199], v[136:139], v[80:83]
	v_mfma_f32_16x16x32_bf16 v[88:91], v[196:199], v[140:143], v[88:91]
	ds_read_b128 v[196:199], v246 offset:4096
	s_waitcnt lgkmcnt(3)
	v_mfma_f32_16x16x32_bf16 v[116:119], v[200:203], v[128:131], v[116:119]
	v_mfma_f32_16x16x32_bf16 v[124:127], v[200:203], v[132:135], v[124:127]
	v_mfma_f32_16x16x32_bf16 v[84:87], v[200:203], v[136:139], v[84:87]
	v_mfma_f32_16x16x32_bf16 v[92:95], v[200:203], v[140:143], v[92:95]
	ds_read_b128 v[200:203], v162 offset:4096
	s_waitcnt lgkmcnt(3)
	v_mfma_f32_16x16x32_bf16 v[96:99], v[204:207], v[128:131], v[96:99]
	v_mfma_f32_16x16x32_bf16 v[104:107], v[204:207], v[132:135], v[104:107]
	v_mfma_f32_16x16x32_bf16 v[64:67], v[204:207], v[136:139], v[64:67]
	v_mfma_f32_16x16x32_bf16 v[72:75], v[204:207], v[140:143], v[72:75]
	ds_read_b128 v[204:207], v246 offset:6144
	s_waitcnt lgkmcnt(3)
	v_mfma_f32_16x16x32_bf16 v[100:103], v[242:245], v[128:131], v[100:103]
	v_mfma_f32_16x16x32_bf16 v[108:111], v[242:245], v[132:135], v[108:111]
	v_mfma_f32_16x16x32_bf16 v[68:71], v[242:245], v[136:139], v[68:71]
	v_mfma_f32_16x16x32_bf16 v[76:79], v[242:245], v[140:143], v[76:79]
	ds_read_b128 v[242:245], v162 offset:6144
	s_waitcnt lgkmcnt(3)
	v_mfma_f32_16x16x32_bf16 v[48:51], v[196:199], v[128:131], v[48:51]
	v_mfma_f32_16x16x32_bf16 v[56:59], v[196:199], v[132:135], v[56:59]
	v_mfma_f32_16x16x32_bf16 v[16:19], v[196:199], v[136:139], v[16:19]
	v_mfma_f32_16x16x32_bf16 v[24:27], v[196:199], v[140:143], v[24:27]
	s_waitcnt lgkmcnt(2)
	v_mfma_f32_16x16x32_bf16 v[52:55], v[200:203], v[128:131], v[52:55]
	v_mfma_f32_16x16x32_bf16 v[60:63], v[200:203], v[132:135], v[60:63]
	v_mfma_f32_16x16x32_bf16 v[20:23], v[200:203], v[136:139], v[20:23]
	v_mfma_f32_16x16x32_bf16 v[28:31], v[200:203], v[140:143], v[28:31]
	s_waitcnt lgkmcnt(1)
	v_mfma_f32_16x16x32_bf16 v[32:35], v[204:207], v[128:131], v[32:35]
	v_mfma_f32_16x16x32_bf16 v[40:43], v[204:207], v[132:135], v[40:43]
	v_mfma_f32_16x16x32_bf16 v[0:3], v[204:207], v[136:139], v[0:3]
	v_mfma_f32_16x16x32_bf16 v[8:11], v[204:207], v[140:143], v[8:11]
	s_waitcnt lgkmcnt(0)
	v_mfma_f32_16x16x32_bf16 v[36:39], v[242:245], v[128:131], v[36:39]
	v_mfma_f32_16x16x32_bf16 v[44:47], v[242:245], v[132:135], v[44:47]
	v_mfma_f32_16x16x32_bf16 v[4:7], v[242:245], v[136:139], v[4:7]
	v_mfma_f32_16x16x32_bf16 v[12:15], v[242:245], v[140:143], v[12:15]
	global_load_dwordx4 v[128:131], v[248:249], off
	global_load_dwordx4 v[132:135], v[248:249], off offset:256
	global_load_dwordx4 v[136:139], v[250:251], off
	global_load_dwordx4 v[140:143], v[250:251], off offset:256
	s_waitcnt vmcnt(10)
	s_barrier
	s_add_i32 s8, s1, 3
	s_lshl_b32 s96, s8, 13
	s_mov_b32 m0, vcc_lo
	v_lshl_add_u64 v[160:161], v[188:189], 0, s[96:97]
	global_load_lds_dwordx4 v[160:161], off
	global_load_lds_dwordx4 v[160:161], off offset:1024
	ds_read_b128 v[196:199], v246 offset:8192
	ds_read_b128 v[200:203], v162 offset:8192
	ds_read_b128 v[204:207], v246 offset:10240
	ds_read_b128 v[242:245], v162 offset:10240
	s_add_i32 s8, s1, 3
	s_lshl_b32 s96, s8, 11
	v_lshl_add_u64 v[248:249], v[184:185], 0, s[96:97]
	v_lshl_add_u64 v[250:251], v[186:187], 0, s[96:97]
	s_waitcnt vmcnt(8) lgkmcnt(3)
	v_mfma_f32_16x16x32_bf16 v[112:115], v[196:199], v[144:147], v[112:115]
	v_mfma_f32_16x16x32_bf16 v[120:123], v[196:199], v[148:151], v[120:123]
	v_mfma_f32_16x16x32_bf16 v[80:83], v[196:199], v[152:155], v[80:83]
	v_mfma_f32_16x16x32_bf16 v[88:91], v[196:199], v[156:159], v[88:91]
	ds_read_b128 v[196:199], v246 offset:12288
	s_waitcnt lgkmcnt(3)
	v_mfma_f32_16x16x32_bf16 v[116:119], v[200:203], v[144:147], v[116:119]
	v_mfma_f32_16x16x32_bf16 v[124:127], v[200:203], v[148:151], v[124:127]
	v_mfma_f32_16x16x32_bf16 v[84:87], v[200:203], v[152:155], v[84:87]
	v_mfma_f32_16x16x32_bf16 v[92:95], v[200:203], v[156:159], v[92:95]
	ds_read_b128 v[200:203], v162 offset:12288
	s_waitcnt lgkmcnt(3)
	v_mfma_f32_16x16x32_bf16 v[96:99], v[204:207], v[144:147], v[96:99]
	v_mfma_f32_16x16x32_bf16 v[104:107], v[204:207], v[148:151], v[104:107]
	v_mfma_f32_16x16x32_bf16 v[64:67], v[204:207], v[152:155], v[64:67]
	v_mfma_f32_16x16x32_bf16 v[72:75], v[204:207], v[156:159], v[72:75]
	ds_read_b128 v[204:207], v246 offset:14336
	s_waitcnt lgkmcnt(3)
	v_mfma_f32_16x16x32_bf16 v[100:103], v[242:245], v[144:147], v[100:103]
	v_mfma_f32_16x16x32_bf16 v[108:111], v[242:245], v[148:151], v[108:111]
	v_mfma_f32_16x16x32_bf16 v[68:71], v[242:245], v[152:155], v[68:71]
	v_mfma_f32_16x16x32_bf16 v[76:79], v[242:245], v[156:159], v[76:79]
	ds_read_b128 v[242:245], v162 offset:14336
	s_waitcnt lgkmcnt(3)
	v_mfma_f32_16x16x32_bf16 v[48:51], v[196:199], v[144:147], v[48:51]
	v_mfma_f32_16x16x32_bf16 v[56:59], v[196:199], v[148:151], v[56:59]
	v_mfma_f32_16x16x32_bf16 v[16:19], v[196:199], v[152:155], v[16:19]
	v_mfma_f32_16x16x32_bf16 v[24:27], v[196:199], v[156:159], v[24:27]
	s_waitcnt lgkmcnt(2)
	v_mfma_f32_16x16x32_bf16 v[52:55], v[200:203], v[144:147], v[52:55]
	v_mfma_f32_16x16x32_bf16 v[60:63], v[200:203], v[148:151], v[60:63]
	v_mfma_f32_16x16x32_bf16 v[20:23], v[200:203], v[152:155], v[20:23]
	v_mfma_f32_16x16x32_bf16 v[28:31], v[200:203], v[156:159], v[28:31]
	s_waitcnt lgkmcnt(1)
	v_mfma_f32_16x16x32_bf16 v[32:35], v[204:207], v[144:147], v[32:35]
	v_mfma_f32_16x16x32_bf16 v[40:43], v[204:207], v[148:151], v[40:43]
	v_mfma_f32_16x16x32_bf16 v[0:3], v[204:207], v[152:155], v[0:3]
	v_mfma_f32_16x16x32_bf16 v[8:11], v[204:207], v[156:159], v[8:11]
	s_waitcnt lgkmcnt(0)
	v_mfma_f32_16x16x32_bf16 v[36:39], v[242:245], v[144:147], v[36:39]
	v_mfma_f32_16x16x32_bf16 v[44:47], v[242:245], v[148:151], v[44:47]
	v_mfma_f32_16x16x32_bf16 v[4:7], v[242:245], v[152:155], v[4:7]
	v_mfma_f32_16x16x32_bf16 v[12:15], v[242:245], v[156:159], v[12:15]
	global_load_dwordx4 v[144:147], v[248:249], off
	global_load_dwordx4 v[148:151], v[248:249], off offset:256
	global_load_dwordx4 v[152:155], v[250:251], off
	global_load_dwordx4 v[156:159], v[250:251], off offset:256
	s_waitcnt vmcnt(10)
	s_barrier
	s_add_i32 s8, s1, 4
	s_lshl_b32 s96, s8, 13
	s_add_i32 m0, vcc_lo, 8192
	v_lshl_add_u64 v[160:161], v[188:189], 0, s[96:97]
	global_load_lds_dwordx4 v[160:161], off
	global_load_lds_dwordx4 v[160:161], off offset:1024
	ds_read_b128 v[196:199], v246 offset:16384
	ds_read_b128 v[200:203], v162 offset:16384
	ds_read_b128 v[204:207], v246 offset:18432
	ds_read_b128 v[242:245], v162 offset:18432
	s_add_i32 s8, s1, 4
	s_lshl_b32 s96, s8, 11
	v_lshl_add_u64 v[248:249], v[184:185], 0, s[96:97]
	v_lshl_add_u64 v[250:251], v[186:187], 0, s[96:97]
	s_waitcnt vmcnt(8) lgkmcnt(3)
	v_mfma_f32_16x16x32_bf16 v[112:115], v[196:199], v[128:131], v[112:115]
	v_mfma_f32_16x16x32_bf16 v[120:123], v[196:199], v[132:135], v[120:123]
	v_mfma_f32_16x16x32_bf16 v[80:83], v[196:199], v[136:139], v[80:83]
	v_mfma_f32_16x16x32_bf16 v[88:91], v[196:199], v[140:143], v[88:91]
	ds_read_b128 v[196:199], v246 offset:20480
	s_waitcnt lgkmcnt(3)
	v_mfma_f32_16x16x32_bf16 v[116:119], v[200:203], v[128:131], v[116:119]
	v_mfma_f32_16x16x32_bf16 v[124:127], v[200:203], v[132:135], v[124:127]
	v_mfma_f32_16x16x32_bf16 v[84:87], v[200:203], v[136:139], v[84:87]
	v_mfma_f32_16x16x32_bf16 v[92:95], v[200:203], v[140:143], v[92:95]
	ds_read_b128 v[200:203], v162 offset:20480
	s_waitcnt lgkmcnt(3)
	v_mfma_f32_16x16x32_bf16 v[96:99], v[204:207], v[128:131], v[96:99]
	v_mfma_f32_16x16x32_bf16 v[104:107], v[204:207], v[132:135], v[104:107]
	v_mfma_f32_16x16x32_bf16 v[64:67], v[204:207], v[136:139], v[64:67]
	v_mfma_f32_16x16x32_bf16 v[72:75], v[204:207], v[140:143], v[72:75]
	ds_read_b128 v[204:207], v246 offset:22528
	s_waitcnt lgkmcnt(3)
	v_mfma_f32_16x16x32_bf16 v[100:103], v[242:245], v[128:131], v[100:103]
	v_mfma_f32_16x16x32_bf16 v[108:111], v[242:245], v[132:135], v[108:111]
	v_mfma_f32_16x16x32_bf16 v[68:71], v[242:245], v[136:139], v[68:71]
	v_mfma_f32_16x16x32_bf16 v[76:79], v[242:245], v[140:143], v[76:79]
	ds_read_b128 v[242:245], v162 offset:22528
	s_waitcnt lgkmcnt(3)
	v_mfma_f32_16x16x32_bf16 v[48:51], v[196:199], v[128:131], v[48:51]
	v_mfma_f32_16x16x32_bf16 v[56:59], v[196:199], v[132:135], v[56:59]
	v_mfma_f32_16x16x32_bf16 v[16:19], v[196:199], v[136:139], v[16:19]
	v_mfma_f32_16x16x32_bf16 v[24:27], v[196:199], v[140:143], v[24:27]
	s_waitcnt lgkmcnt(2)
	v_mfma_f32_16x16x32_bf16 v[52:55], v[200:203], v[128:131], v[52:55]
	v_mfma_f32_16x16x32_bf16 v[60:63], v[200:203], v[132:135], v[60:63]
	v_mfma_f32_16x16x32_bf16 v[20:23], v[200:203], v[136:139], v[20:23]
	v_mfma_f32_16x16x32_bf16 v[28:31], v[200:203], v[140:143], v[28:31]
	s_waitcnt lgkmcnt(1)
	v_mfma_f32_16x16x32_bf16 v[32:35], v[204:207], v[128:131], v[32:35]
	v_mfma_f32_16x16x32_bf16 v[40:43], v[204:207], v[132:135], v[40:43]
	v_mfma_f32_16x16x32_bf16 v[0:3], v[204:207], v[136:139], v[0:3]
	v_mfma_f32_16x16x32_bf16 v[8:11], v[204:207], v[140:143], v[8:11]
	s_waitcnt lgkmcnt(0)
	v_mfma_f32_16x16x32_bf16 v[36:39], v[242:245], v[128:131], v[36:39]
	v_mfma_f32_16x16x32_bf16 v[44:47], v[242:245], v[132:135], v[44:47]
	v_mfma_f32_16x16x32_bf16 v[4:7], v[242:245], v[136:139], v[4:7]
	v_mfma_f32_16x16x32_bf16 v[12:15], v[242:245], v[140:143], v[12:15]
	global_load_dwordx4 v[128:131], v[248:249], off
	global_load_dwordx4 v[132:135], v[248:249], off offset:256
	global_load_dwordx4 v[136:139], v[250:251], off
	global_load_dwordx4 v[140:143], v[250:251], off offset:256
	s_waitcnt vmcnt(10)
	s_barrier
	s_add_i32 s8, s1, 5
	s_lshl_b32 s96, s8, 13
	s_add_i32 m0, vcc_lo, 16384
	v_lshl_add_u64 v[160:161], v[188:189], 0, s[96:97]
	global_load_lds_dwordx4 v[160:161], off
	global_load_lds_dwordx4 v[160:161], off offset:1024
	ds_read_b128 v[196:199], v246 offset:0
	ds_read_b128 v[200:203], v162 offset:0
	ds_read_b128 v[204:207], v246 offset:2048
	ds_read_b128 v[242:245], v162 offset:2048
	s_add_i32 s8, s1, 5
	s_lshl_b32 s96, s8, 11
	v_lshl_add_u64 v[248:249], v[184:185], 0, s[96:97]
	v_lshl_add_u64 v[250:251], v[186:187], 0, s[96:97]
	s_waitcnt vmcnt(8) lgkmcnt(3)
	v_mfma_f32_16x16x32_bf16 v[112:115], v[196:199], v[144:147], v[112:115]
	v_mfma_f32_16x16x32_bf16 v[120:123], v[196:199], v[148:151], v[120:123]
	v_mfma_f32_16x16x32_bf16 v[80:83], v[196:199], v[152:155], v[80:83]
	v_mfma_f32_16x16x32_bf16 v[88:91], v[196:199], v[156:159], v[88:91]
	ds_read_b128 v[196:199], v246 offset:4096
	s_waitcnt lgkmcnt(3)
	v_mfma_f32_16x16x32_bf16 v[116:119], v[200:203], v[144:147], v[116:119]
	v_mfma_f32_16x16x32_bf16 v[124:127], v[200:203], v[148:151], v[124:127]
	v_mfma_f32_16x16x32_bf16 v[84:87], v[200:203], v[152:155], v[84:87]
	v_mfma_f32_16x16x32_bf16 v[92:95], v[200:203], v[156:159], v[92:95]
	ds_read_b128 v[200:203], v162 offset:4096
	s_waitcnt lgkmcnt(3)
	v_mfma_f32_16x16x32_bf16 v[96:99], v[204:207], v[144:147], v[96:99]
	v_mfma_f32_16x16x32_bf16 v[104:107], v[204:207], v[148:151], v[104:107]
	v_mfma_f32_16x16x32_bf16 v[64:67], v[204:207], v[152:155], v[64:67]
	v_mfma_f32_16x16x32_bf16 v[72:75], v[204:207], v[156:159], v[72:75]
	ds_read_b128 v[204:207], v246 offset:6144
	s_waitcnt lgkmcnt(3)
	v_mfma_f32_16x16x32_bf16 v[100:103], v[242:245], v[144:147], v[100:103]
	v_mfma_f32_16x16x32_bf16 v[108:111], v[242:245], v[148:151], v[108:111]
	v_mfma_f32_16x16x32_bf16 v[68:71], v[242:245], v[152:155], v[68:71]
	v_mfma_f32_16x16x32_bf16 v[76:79], v[242:245], v[156:159], v[76:79]
	ds_read_b128 v[242:245], v162 offset:6144
	s_waitcnt lgkmcnt(3)
	v_mfma_f32_16x16x32_bf16 v[48:51], v[196:199], v[144:147], v[48:51]
	v_mfma_f32_16x16x32_bf16 v[56:59], v[196:199], v[148:151], v[56:59]
	v_mfma_f32_16x16x32_bf16 v[16:19], v[196:199], v[152:155], v[16:19]
	v_mfma_f32_16x16x32_bf16 v[24:27], v[196:199], v[156:159], v[24:27]
	s_waitcnt lgkmcnt(2)
	v_mfma_f32_16x16x32_bf16 v[52:55], v[200:203], v[144:147], v[52:55]
	v_mfma_f32_16x16x32_bf16 v[60:63], v[200:203], v[148:151], v[60:63]
	v_mfma_f32_16x16x32_bf16 v[20:23], v[200:203], v[152:155], v[20:23]
	v_mfma_f32_16x16x32_bf16 v[28:31], v[200:203], v[156:159], v[28:31]
	s_waitcnt lgkmcnt(1)
	v_mfma_f32_16x16x32_bf16 v[32:35], v[204:207], v[144:147], v[32:35]
	v_mfma_f32_16x16x32_bf16 v[40:43], v[204:207], v[148:151], v[40:43]
	v_mfma_f32_16x16x32_bf16 v[0:3], v[204:207], v[152:155], v[0:3]
	v_mfma_f32_16x16x32_bf16 v[8:11], v[204:207], v[156:159], v[8:11]
	s_waitcnt lgkmcnt(0)
	v_mfma_f32_16x16x32_bf16 v[36:39], v[242:245], v[144:147], v[36:39]
	v_mfma_f32_16x16x32_bf16 v[44:47], v[242:245], v[148:151], v[44:47]
	v_mfma_f32_16x16x32_bf16 v[4:7], v[242:245], v[152:155], v[4:7]
	v_mfma_f32_16x16x32_bf16 v[12:15], v[242:245], v[156:159], v[12:15]
	global_load_dwordx4 v[144:147], v[248:249], off
	global_load_dwordx4 v[148:151], v[248:249], off offset:256
	global_load_dwordx4 v[152:155], v[250:251], off
	global_load_dwordx4 v[156:159], v[250:251], off offset:256
	s_waitcnt vmcnt(10)
	s_barrier
	s_add_i32 s8, s1, 6
	s_lshl_b32 s96, s8, 13
	s_mov_b32 m0, vcc_lo
	v_lshl_add_u64 v[160:161], v[188:189], 0, s[96:97]
	global_load_lds_dwordx4 v[160:161], off
	global_load_lds_dwordx4 v[160:161], off offset:1024
	ds_read_b128 v[196:199], v246 offset:8192
	ds_read_b128 v[200:203], v162 offset:8192
	ds_read_b128 v[204:207], v246 offset:10240
	ds_read_b128 v[242:245], v162 offset:10240
	s_add_i32 s8, s1, 6
	s_lshl_b32 s96, s8, 11
	v_lshl_add_u64 v[248:249], v[184:185], 0, s[96:97]
	v_lshl_add_u64 v[250:251], v[186:187], 0, s[96:97]
	s_waitcnt vmcnt(8) lgkmcnt(3)
	v_mfma_f32_16x16x32_bf16 v[112:115], v[196:199], v[128:131], v[112:115]
	v_mfma_f32_16x16x32_bf16 v[120:123], v[196:199], v[132:135], v[120:123]
	v_mfma_f32_16x16x32_bf16 v[80:83], v[196:199], v[136:139], v[80:83]
	v_mfma_f32_16x16x32_bf16 v[88:91], v[196:199], v[140:143], v[88:91]
	ds_read_b128 v[196:199], v246 offset:12288
	s_waitcnt lgkmcnt(3)
	v_mfma_f32_16x16x32_bf16 v[116:119], v[200:203], v[128:131], v[116:119]
	v_mfma_f32_16x16x32_bf16 v[124:127], v[200:203], v[132:135], v[124:127]
	v_mfma_f32_16x16x32_bf16 v[84:87], v[200:203], v[136:139], v[84:87]
	v_mfma_f32_16x16x32_bf16 v[92:95], v[200:203], v[140:143], v[92:95]
	ds_read_b128 v[200:203], v162 offset:12288
	s_waitcnt lgkmcnt(3)
	v_mfma_f32_16x16x32_bf16 v[96:99], v[204:207], v[128:131], v[96:99]
	v_mfma_f32_16x16x32_bf16 v[104:107], v[204:207], v[132:135], v[104:107]
	v_mfma_f32_16x16x32_bf16 v[64:67], v[204:207], v[136:139], v[64:67]
	v_mfma_f32_16x16x32_bf16 v[72:75], v[204:207], v[140:143], v[72:75]
	ds_read_b128 v[204:207], v246 offset:14336
	s_waitcnt lgkmcnt(3)
	v_mfma_f32_16x16x32_bf16 v[100:103], v[242:245], v[128:131], v[100:103]
	v_mfma_f32_16x16x32_bf16 v[108:111], v[242:245], v[132:135], v[108:111]
	v_mfma_f32_16x16x32_bf16 v[68:71], v[242:245], v[136:139], v[68:71]
	v_mfma_f32_16x16x32_bf16 v[76:79], v[242:245], v[140:143], v[76:79]
	ds_read_b128 v[242:245], v162 offset:14336
	s_waitcnt lgkmcnt(3)
	v_mfma_f32_16x16x32_bf16 v[48:51], v[196:199], v[128:131], v[48:51]
	v_mfma_f32_16x16x32_bf16 v[56:59], v[196:199], v[132:135], v[56:59]
	v_mfma_f32_16x16x32_bf16 v[16:19], v[196:199], v[136:139], v[16:19]
	v_mfma_f32_16x16x32_bf16 v[24:27], v[196:199], v[140:143], v[24:27]
	s_waitcnt lgkmcnt(2)
	v_mfma_f32_16x16x32_bf16 v[52:55], v[200:203], v[128:131], v[52:55]
	v_mfma_f32_16x16x32_bf16 v[60:63], v[200:203], v[132:135], v[60:63]
	v_mfma_f32_16x16x32_bf16 v[20:23], v[200:203], v[136:139], v[20:23]
	v_mfma_f32_16x16x32_bf16 v[28:31], v[200:203], v[140:143], v[28:31]
	s_waitcnt lgkmcnt(1)
	v_mfma_f32_16x16x32_bf16 v[32:35], v[204:207], v[128:131], v[32:35]
	v_mfma_f32_16x16x32_bf16 v[40:43], v[204:207], v[132:135], v[40:43]
	v_mfma_f32_16x16x32_bf16 v[0:3], v[204:207], v[136:139], v[0:3]
	v_mfma_f32_16x16x32_bf16 v[8:11], v[204:207], v[140:143], v[8:11]
	s_waitcnt lgkmcnt(0)
	v_mfma_f32_16x16x32_bf16 v[36:39], v[242:245], v[128:131], v[36:39]
	v_mfma_f32_16x16x32_bf16 v[44:47], v[242:245], v[132:135], v[44:47]
	v_mfma_f32_16x16x32_bf16 v[4:7], v[242:245], v[136:139], v[4:7]
	v_mfma_f32_16x16x32_bf16 v[12:15], v[242:245], v[140:143], v[12:15]
	global_load_dwordx4 v[128:131], v[248:249], off
	global_load_dwordx4 v[132:135], v[248:249], off offset:256
	global_load_dwordx4 v[136:139], v[250:251], off
	global_load_dwordx4 v[140:143], v[250:251], off offset:256
	s_waitcnt vmcnt(10)
	s_barrier
	s_add_i32 s8, s1, 7
	s_lshl_b32 s96, s8, 13
	s_add_i32 m0, vcc_lo, 8192
	v_lshl_add_u64 v[160:161], v[188:189], 0, s[96:97]
	global_load_lds_dwordx4 v[160:161], off
	global_load_lds_dwordx4 v[160:161], off offset:1024
	ds_read_b128 v[196:199], v246 offset:16384
	ds_read_b128 v[200:203], v162 offset:16384
	ds_read_b128 v[204:207], v246 offset:18432
	ds_read_b128 v[242:245], v162 offset:18432
	s_add_i32 s8, s1, 7
	s_lshl_b32 s96, s8, 11
	v_lshl_add_u64 v[248:249], v[184:185], 0, s[96:97]
	v_lshl_add_u64 v[250:251], v[186:187], 0, s[96:97]
	s_waitcnt vmcnt(8) lgkmcnt(3)
	v_mfma_f32_16x16x32_bf16 v[112:115], v[196:199], v[144:147], v[112:115]
	v_mfma_f32_16x16x32_bf16 v[120:123], v[196:199], v[148:151], v[120:123]
	v_mfma_f32_16x16x32_bf16 v[80:83], v[196:199], v[152:155], v[80:83]
	v_mfma_f32_16x16x32_bf16 v[88:91], v[196:199], v[156:159], v[88:91]
	ds_read_b128 v[196:199], v246 offset:20480
	s_waitcnt lgkmcnt(3)
	v_mfma_f32_16x16x32_bf16 v[116:119], v[200:203], v[144:147], v[116:119]
	v_mfma_f32_16x16x32_bf16 v[124:127], v[200:203], v[148:151], v[124:127]
	v_mfma_f32_16x16x32_bf16 v[84:87], v[200:203], v[152:155], v[84:87]
	v_mfma_f32_16x16x32_bf16 v[92:95], v[200:203], v[156:159], v[92:95]
	ds_read_b128 v[200:203], v162 offset:20480
	s_waitcnt lgkmcnt(3)
	v_mfma_f32_16x16x32_bf16 v[96:99], v[204:207], v[144:147], v[96:99]
	v_mfma_f32_16x16x32_bf16 v[104:107], v[204:207], v[148:151], v[104:107]
	v_mfma_f32_16x16x32_bf16 v[64:67], v[204:207], v[152:155], v[64:67]
	v_mfma_f32_16x16x32_bf16 v[72:75], v[204:207], v[156:159], v[72:75]
	ds_read_b128 v[204:207], v246 offset:22528
	s_waitcnt lgkmcnt(3)
	v_mfma_f32_16x16x32_bf16 v[100:103], v[242:245], v[144:147], v[100:103]
	v_mfma_f32_16x16x32_bf16 v[108:111], v[242:245], v[148:151], v[108:111]
	v_mfma_f32_16x16x32_bf16 v[68:71], v[242:245], v[152:155], v[68:71]
	v_mfma_f32_16x16x32_bf16 v[76:79], v[242:245], v[156:159], v[76:79]
	ds_read_b128 v[242:245], v162 offset:22528
	s_waitcnt lgkmcnt(3)
	v_mfma_f32_16x16x32_bf16 v[48:51], v[196:199], v[144:147], v[48:51]
	v_mfma_f32_16x16x32_bf16 v[56:59], v[196:199], v[148:151], v[56:59]
	v_mfma_f32_16x16x32_bf16 v[16:19], v[196:199], v[152:155], v[16:19]
	v_mfma_f32_16x16x32_bf16 v[24:27], v[196:199], v[156:159], v[24:27]
	s_waitcnt lgkmcnt(2)
	v_mfma_f32_16x16x32_bf16 v[52:55], v[200:203], v[144:147], v[52:55]
	v_mfma_f32_16x16x32_bf16 v[60:63], v[200:203], v[148:151], v[60:63]
	v_mfma_f32_16x16x32_bf16 v[20:23], v[200:203], v[152:155], v[20:23]
	v_mfma_f32_16x16x32_bf16 v[28:31], v[200:203], v[156:159], v[28:31]
	s_waitcnt lgkmcnt(1)
	v_mfma_f32_16x16x32_bf16 v[32:35], v[204:207], v[144:147], v[32:35]
	v_mfma_f32_16x16x32_bf16 v[40:43], v[204:207], v[148:151], v[40:43]
	v_mfma_f32_16x16x32_bf16 v[0:3], v[204:207], v[152:155], v[0:3]
	v_mfma_f32_16x16x32_bf16 v[8:11], v[204:207], v[156:159], v[8:11]
	s_waitcnt lgkmcnt(0)
	v_mfma_f32_16x16x32_bf16 v[36:39], v[242:245], v[144:147], v[36:39]
	v_mfma_f32_16x16x32_bf16 v[44:47], v[242:245], v[148:151], v[44:47]
	v_mfma_f32_16x16x32_bf16 v[4:7], v[242:245], v[152:155], v[4:7]
	v_mfma_f32_16x16x32_bf16 v[12:15], v[242:245], v[156:159], v[12:15]
	global_load_dwordx4 v[144:147], v[248:249], off
	global_load_dwordx4 v[148:151], v[248:249], off offset:256
	global_load_dwordx4 v[152:155], v[250:251], off
	global_load_dwordx4 v[156:159], v[250:251], off offset:256
	s_waitcnt vmcnt(10)
	s_barrier
	s_add_i32 s1, s1, 6
	s_cmp_lt_u32 s1, 30
	s_cbranch_scc1 .Lg16_gu_k
	ds_read_b128 v[196:199], v246 offset:0
	ds_read_b128 v[200:203], v162 offset:0
	ds_read_b128 v[204:207], v246 offset:2048
	ds_read_b128 v[242:245], v162 offset:2048
	s_waitcnt vmcnt(6) lgkmcnt(3)
	v_mfma_f32_16x16x32_bf16 v[112:115], v[196:199], v[128:131], v[112:115]
	v_mfma_f32_16x16x32_bf16 v[120:123], v[196:199], v[132:135], v[120:123]
	v_mfma_f32_16x16x32_bf16 v[80:83], v[196:199], v[136:139], v[80:83]
	v_mfma_f32_16x16x32_bf16 v[88:91], v[196:199], v[140:143], v[88:91]
	ds_read_b128 v[196:199], v246 offset:4096
	s_waitcnt lgkmcnt(3)
	v_mfma_f32_16x16x32_bf16 v[116:119], v[200:203], v[128:131], v[116:119]
	v_mfma_f32_16x16x32_bf16 v[124:127], v[200:203], v[132:135], v[124:127]
	v_mfma_f32_16x16x32_bf16 v[84:87], v[200:203], v[136:139], v[84:87]
	v_mfma_f32_16x16x32_bf16 v[92:95], v[200:203], v[140:143], v[92:95]
	ds_read_b128 v[200:203], v162 offset:4096
	s_waitcnt lgkmcnt(3)
	v_mfma_f32_16x16x32_bf16 v[96:99], v[204:207], v[128:131], v[96:99]
	v_mfma_f32_16x16x32_bf16 v[104:107], v[204:207], v[132:135], v[104:107]
	v_mfma_f32_16x16x32_bf16 v[64:67], v[204:207], v[136:139], v[64:67]
	v_mfma_f32_16x16x32_bf16 v[72:75], v[204:207], v[140:143], v[72:75]
	ds_read_b128 v[204:207], v246 offset:6144
	s_waitcnt lgkmcnt(3)
	v_mfma_f32_16x16x32_bf16 v[100:103], v[242:245], v[128:131], v[100:103]
	v_mfma_f32_16x16x32_bf16 v[108:111], v[242:245], v[132:135], v[108:111]
	v_mfma_f32_16x16x32_bf16 v[68:71], v[242:245], v[136:139], v[68:71]
	v_mfma_f32_16x16x32_bf16 v[76:79], v[242:245], v[140:143], v[76:79]
	ds_read_b128 v[242:245], v162 offset:6144
	s_waitcnt lgkmcnt(3)
	v_mfma_f32_16x16x32_bf16 v[48:51], v[196:199], v[128:131], v[48:51]
	v_mfma_f32_16x16x32_bf16 v[56:59], v[196:199], v[132:135], v[56:59]
	v_mfma_f32_16x16x32_bf16 v[16:19], v[196:199], v[136:139], v[16:19]
	v_mfma_f32_16x16x32_bf16 v[24:27], v[196:199], v[140:143], v[24:27]
	s_waitcnt lgkmcnt(2)
	v_mfma_f32_16x16x32_bf16 v[52:55], v[200:203], v[128:131], v[52:55]
	v_mfma_f32_16x16x32_bf16 v[60:63], v[200:203], v[132:135], v[60:63]
	v_mfma_f32_16x16x32_bf16 v[20:23], v[200:203], v[136:139], v[20:23]
	v_mfma_f32_16x16x32_bf16 v[28:31], v[200:203], v[140:143], v[28:31]
	s_waitcnt lgkmcnt(1)
	v_mfma_f32_16x16x32_bf16 v[32:35], v[204:207], v[128:131], v[32:35]
	v_mfma_f32_16x16x32_bf16 v[40:43], v[204:207], v[132:135], v[40:43]
	v_mfma_f32_16x16x32_bf16 v[0:3], v[204:207], v[136:139], v[0:3]
	v_mfma_f32_16x16x32_bf16 v[8:11], v[204:207], v[140:143], v[8:11]
	s_waitcnt lgkmcnt(0)
	v_mfma_f32_16x16x32_bf16 v[36:39], v[242:245], v[128:131], v[36:39]
	v_mfma_f32_16x16x32_bf16 v[44:47], v[242:245], v[132:135], v[44:47]
	v_mfma_f32_16x16x32_bf16 v[4:7], v[242:245], v[136:139], v[4:7]
	v_mfma_f32_16x16x32_bf16 v[12:15], v[242:245], v[140:143], v[12:15]
	s_waitcnt vmcnt(4)
	s_barrier
	ds_read_b128 v[196:199], v246 offset:8192
	ds_read_b128 v[200:203], v162 offset:8192
	ds_read_b128 v[204:207], v246 offset:10240
	ds_read_b128 v[242:245], v162 offset:10240
	s_waitcnt vmcnt(0) lgkmcnt(3)
	v_mfma_f32_16x16x32_bf16 v[112:115], v[196:199], v[144:147], v[112:115]
	v_mfma_f32_16x16x32_bf16 v[120:123], v[196:199], v[148:151], v[120:123]
	v_mfma_f32_16x16x32_bf16 v[80:83], v[196:199], v[152:155], v[80:83]
	v_mfma_f32_16x16x32_bf16 v[88:91], v[196:199], v[156:159], v[88:91]
	ds_read_b128 v[196:199], v246 offset:12288
	s_waitcnt lgkmcnt(3)
	v_mfma_f32_16x16x32_bf16 v[116:119], v[200:203], v[144:147], v[116:119]
	v_mfma_f32_16x16x32_bf16 v[124:127], v[200:203], v[148:151], v[124:127]
	v_mfma_f32_16x16x32_bf16 v[84:87], v[200:203], v[152:155], v[84:87]
	v_mfma_f32_16x16x32_bf16 v[92:95], v[200:203], v[156:159], v[92:95]
	ds_read_b128 v[200:203], v162 offset:12288
	s_waitcnt lgkmcnt(3)
	v_mfma_f32_16x16x32_bf16 v[96:99], v[204:207], v[144:147], v[96:99]
	v_mfma_f32_16x16x32_bf16 v[104:107], v[204:207], v[148:151], v[104:107]
	v_mfma_f32_16x16x32_bf16 v[64:67], v[204:207], v[152:155], v[64:67]
	v_mfma_f32_16x16x32_bf16 v[72:75], v[204:207], v[156:159], v[72:75]
	ds_read_b128 v[204:207], v246 offset:14336
	s_waitcnt lgkmcnt(3)
	v_mfma_f32_16x16x32_bf16 v[100:103], v[242:245], v[144:147], v[100:103]
	v_mfma_f32_16x16x32_bf16 v[108:111], v[242:245], v[148:151], v[108:111]
	v_mfma_f32_16x16x32_bf16 v[68:71], v[242:245], v[152:155], v[68:71]
	v_mfma_f32_16x16x32_bf16 v[76:79], v[242:245], v[156:159], v[76:79]
	ds_read_b128 v[242:245], v162 offset:14336
	s_waitcnt lgkmcnt(3)
	v_mfma_f32_16x16x32_bf16 v[48:51], v[196:199], v[144:147], v[48:51]
	v_mfma_f32_16x16x32_bf16 v[56:59], v[196:199], v[148:151], v[56:59]
	v_mfma_f32_16x16x32_bf16 v[16:19], v[196:199], v[152:155], v[16:19]
	v_mfma_f32_16x16x32_bf16 v[24:27], v[196:199], v[156:159], v[24:27]
	s_waitcnt lgkmcnt(2)
	v_mfma_f32_16x16x32_bf16 v[52:55], v[200:203], v[144:147], v[52:55]
	v_mfma_f32_16x16x32_bf16 v[60:63], v[200:203], v[148:151], v[60:63]
	v_mfma_f32_16x16x32_bf16 v[20:23], v[200:203], v[152:155], v[20:23]
	v_mfma_f32_16x16x32_bf16 v[28:31], v[200:203], v[156:159], v[28:31]
	s_waitcnt lgkmcnt(1)
	v_mfma_f32_16x16x32_bf16 v[32:35], v[204:207], v[144:147], v[32:35]
	v_mfma_f32_16x16x32_bf16 v[40:43], v[204:207], v[148:151], v[40:43]
	v_mfma_f32_16x16x32_bf16 v[0:3], v[204:207], v[152:155], v[0:3]
	v_mfma_f32_16x16x32_bf16 v[8:11], v[204:207], v[156:159], v[8:11]
	s_waitcnt lgkmcnt(0)
	v_mfma_f32_16x16x32_bf16 v[36:39], v[242:245], v[144:147], v[36:39]
	v_mfma_f32_16x16x32_bf16 v[44:47], v[242:245], v[148:151], v[44:47]
	v_mfma_f32_16x16x32_bf16 v[4:7], v[242:245], v[152:155], v[4:7]
	v_mfma_f32_16x16x32_bf16 v[12:15], v[242:245], v[156:159], v[12:15]
	s_barrier
	s_nop 7
	s_nop 1
	s_waitcnt vmcnt(0)
	v_and_b32_e32 v128, 63, v179
	v_lshrrev_b32_e32 v129, 6, v179
	s_lshl_b32 s14, s7, 3
	s_mul_hi_u32 s15, s14, 0x2c000
	s_mul_i32 s14, s14, 0x2c000
	s_lshl_b32 s16, s0, 12
	s_add_u32 s12, s66, s14
	s_addc_u32 s13, s67, s15
	s_add_u32 s12, s12, s16
	s_addc_u32 s13, s13, 0
	v_and_b32_e32 v130, 15, v128
	v_lshlrev_b32_e32 v132, 4, v130
	v_lshrrev_b32_e32 v130, 4, v128
	v_lshl_add_u32 v132, v130, 9, v132
	v_mul_u32_u24_e32 v130, 0x58000, v129
	v_add_u32_e32 v132, v132, v130
	v_add_u32_e32 v133, 0x2c000, v132
	v_mul_f32_e32 v140, 0xbfb8aa3b, v112
	v_mul_f32_e32 v141, 0xbfb8aa3b, v113
	v_mul_f32_e32 v142, 0xbfb8aa3b, v114
	v_mul_f32_e32 v143, 0xbfb8aa3b, v115
	v_mul_f32_e32 v144, 0xbfb8aa3b, v116
	v_mul_f32_e32 v145, 0xbfb8aa3b, v117
	v_mul_f32_e32 v146, 0xbfb8aa3b, v118
	v_mul_f32_e32 v147, 0xbfb8aa3b, v119
	v_exp_f32_e32 v140, v140
	v_exp_f32_e32 v141, v141
	v_exp_f32_e32 v142, v142
	v_exp_f32_e32 v143, v143
	v_exp_f32_e32 v144, v144
	v_exp_f32_e32 v145, v145
	v_exp_f32_e32 v146, v146
	v_exp_f32_e32 v147, v147
	v_add_f32_e32 v140, 1.0, v140
	v_add_f32_e32 v141, 1.0, v141
	v_add_f32_e32 v142, 1.0, v142
	v_add_f32_e32 v143, 1.0, v143
	v_add_f32_e32 v144, 1.0, v144
	v_add_f32_e32 v145, 1.0, v145
	v_add_f32_e32 v146, 1.0, v146
	v_add_f32_e32 v147, 1.0, v147
	v_rcp_f32_e32 v140, v140
	v_rcp_f32_e32 v141, v141
	v_rcp_f32_e32 v142, v142
	v_rcp_f32_e32 v143, v143
	v_rcp_f32_e32 v144, v144
	v_rcp_f32_e32 v145, v145
	v_rcp_f32_e32 v146, v146
	v_rcp_f32_e32 v147, v147
	v_mul_f32_e32 v140, v112, v140
	v_mul_f32_e32 v141, v113, v141
	v_mul_f32_e32 v142, v114, v142
	v_mul_f32_e32 v143, v115, v143
	v_mul_f32_e32 v144, v116, v144
	v_mul_f32_e32 v145, v117, v145
	v_mul_f32_e32 v146, v118, v146
	v_mul_f32_e32 v147, v119, v147
	v_mul_f32_e32 v140, v96, v140
	v_mul_f32_e32 v141, v97, v141
	v_mul_f32_e32 v142, v98, v142
	v_mul_f32_e32 v143, v99, v143
	v_mul_f32_e32 v144, v100, v144
	v_mul_f32_e32 v145, v101, v145
	v_mul_f32_e32 v146, v102, v146
	v_mul_f32_e32 v147, v103, v147
	v_cvt_pk_bf16_f32 v148, v140, v141
	v_cvt_pk_bf16_f32 v149, v142, v143
	v_cvt_pk_bf16_f32 v150, v144, v145
	v_cvt_pk_bf16_f32 v151, v146, v147
	global_store_dwordx4 v132, v[148:151], s[12:13] sc0 sc1 nt
	v_mul_f32_e32 v140, 0xbfb8aa3b, v120
	v_mul_f32_e32 v141, 0xbfb8aa3b, v121
	v_mul_f32_e32 v142, 0xbfb8aa3b, v122
	v_mul_f32_e32 v143, 0xbfb8aa3b, v123
	v_mul_f32_e32 v144, 0xbfb8aa3b, v124
	v_mul_f32_e32 v145, 0xbfb8aa3b, v125
	v_mul_f32_e32 v146, 0xbfb8aa3b, v126
	v_mul_f32_e32 v147, 0xbfb8aa3b, v127
	v_exp_f32_e32 v140, v140
	v_exp_f32_e32 v141, v141
	v_exp_f32_e32 v142, v142
	v_exp_f32_e32 v143, v143
	v_exp_f32_e32 v144, v144
	v_exp_f32_e32 v145, v145
	v_exp_f32_e32 v146, v146
	v_exp_f32_e32 v147, v147
	v_add_f32_e32 v140, 1.0, v140
	v_add_f32_e32 v141, 1.0, v141
	v_add_f32_e32 v142, 1.0, v142
	v_add_f32_e32 v143, 1.0, v143
	v_add_f32_e32 v144, 1.0, v144
	v_add_f32_e32 v145, 1.0, v145
	v_add_f32_e32 v146, 1.0, v146
	v_add_f32_e32 v147, 1.0, v147
	v_rcp_f32_e32 v140, v140
	v_rcp_f32_e32 v141, v141
	v_rcp_f32_e32 v142, v142
	v_rcp_f32_e32 v143, v143
	v_rcp_f32_e32 v144, v144
	v_rcp_f32_e32 v145, v145
	v_rcp_f32_e32 v146, v146
	v_rcp_f32_e32 v147, v147
	v_mul_f32_e32 v140, v120, v140
	v_mul_f32_e32 v141, v121, v141
	v_mul_f32_e32 v142, v122, v142
	v_mul_f32_e32 v143, v123, v143
	v_mul_f32_e32 v144, v124, v144
	v_mul_f32_e32 v145, v125, v145
	v_mul_f32_e32 v146, v126, v146
	v_mul_f32_e32 v147, v127, v147
	v_mul_f32_e32 v140, v104, v140
	v_mul_f32_e32 v141, v105, v141
	v_mul_f32_e32 v142, v106, v142
	v_mul_f32_e32 v143, v107, v143
	v_mul_f32_e32 v144, v108, v144
	v_mul_f32_e32 v145, v109, v145
	v_mul_f32_e32 v146, v110, v146
	v_mul_f32_e32 v147, v111, v147
	v_cvt_pk_bf16_f32 v152, v140, v141
	v_cvt_pk_bf16_f32 v153, v142, v143
	v_cvt_pk_bf16_f32 v154, v144, v145
	v_cvt_pk_bf16_f32 v155, v146, v147
	global_store_dwordx4 v132, v[152:155], s[12:13] offset:256 sc0 sc1 nt
	v_mul_f32_e32 v140, 0xbfb8aa3b, v80
	v_mul_f32_e32 v141, 0xbfb8aa3b, v81
	v_mul_f32_e32 v142, 0xbfb8aa3b, v82
	v_mul_f32_e32 v143, 0xbfb8aa3b, v83
	v_mul_f32_e32 v144, 0xbfb8aa3b, v84
	v_mul_f32_e32 v145, 0xbfb8aa3b, v85
	v_mul_f32_e32 v146, 0xbfb8aa3b, v86
	v_mul_f32_e32 v147, 0xbfb8aa3b, v87
	v_exp_f32_e32 v140, v140
	v_exp_f32_e32 v141, v141
	v_exp_f32_e32 v142, v142
	v_exp_f32_e32 v143, v143
	v_exp_f32_e32 v144, v144
	v_exp_f32_e32 v145, v145
	v_exp_f32_e32 v146, v146
	v_exp_f32_e32 v147, v147
	v_add_f32_e32 v140, 1.0, v140
	v_add_f32_e32 v141, 1.0, v141
	v_add_f32_e32 v142, 1.0, v142
	v_add_f32_e32 v143, 1.0, v143
	v_add_f32_e32 v144, 1.0, v144
	v_add_f32_e32 v145, 1.0, v145
	v_add_f32_e32 v146, 1.0, v146
	v_add_f32_e32 v147, 1.0, v147
	v_rcp_f32_e32 v140, v140
	v_rcp_f32_e32 v141, v141
	v_rcp_f32_e32 v142, v142
	v_rcp_f32_e32 v143, v143
	v_rcp_f32_e32 v144, v144
	v_rcp_f32_e32 v145, v145
	v_rcp_f32_e32 v146, v146
	v_rcp_f32_e32 v147, v147
	v_mul_f32_e32 v140, v80, v140
	v_mul_f32_e32 v141, v81, v141
	v_mul_f32_e32 v142, v82, v142
	v_mul_f32_e32 v143, v83, v143
	v_mul_f32_e32 v144, v84, v144
	v_mul_f32_e32 v145, v85, v145
	v_mul_f32_e32 v146, v86, v146
	v_mul_f32_e32 v147, v87, v147
	v_mul_f32_e32 v140, v64, v140
	v_mul_f32_e32 v141, v65, v141
	v_mul_f32_e32 v142, v66, v142
	v_mul_f32_e32 v143, v67, v143
	v_mul_f32_e32 v144, v68, v144
	v_mul_f32_e32 v145, v69, v145
	v_mul_f32_e32 v146, v70, v146
	v_mul_f32_e32 v147, v71, v147
	v_cvt_pk_bf16_f32 v156, v140, v141
	v_cvt_pk_bf16_f32 v157, v142, v143
	v_cvt_pk_bf16_f32 v158, v144, v145
	v_cvt_pk_bf16_f32 v159, v146, v147
	global_store_dwordx4 v133, v[156:159], s[12:13] sc0 sc1 nt
	v_mul_f32_e32 v140, 0xbfb8aa3b, v88
	v_mul_f32_e32 v141, 0xbfb8aa3b, v89
	v_mul_f32_e32 v142, 0xbfb8aa3b, v90
	v_mul_f32_e32 v143, 0xbfb8aa3b, v91
	v_mul_f32_e32 v144, 0xbfb8aa3b, v92
	v_mul_f32_e32 v145, 0xbfb8aa3b, v93
	v_mul_f32_e32 v146, 0xbfb8aa3b, v94
	v_mul_f32_e32 v147, 0xbfb8aa3b, v95
	v_exp_f32_e32 v140, v140
	v_exp_f32_e32 v141, v141
	v_exp_f32_e32 v142, v142
	v_exp_f32_e32 v143, v143
	v_exp_f32_e32 v144, v144
	v_exp_f32_e32 v145, v145
	v_exp_f32_e32 v146, v146
	v_exp_f32_e32 v147, v147
	v_add_f32_e32 v140, 1.0, v140
	v_add_f32_e32 v141, 1.0, v141
	v_add_f32_e32 v142, 1.0, v142
	v_add_f32_e32 v143, 1.0, v143
	v_add_f32_e32 v144, 1.0, v144
	v_add_f32_e32 v145, 1.0, v145
	v_add_f32_e32 v146, 1.0, v146
	v_add_f32_e32 v147, 1.0, v147
	v_rcp_f32_e32 v140, v140
	v_rcp_f32_e32 v141, v141
	v_rcp_f32_e32 v142, v142
	v_rcp_f32_e32 v143, v143
	v_rcp_f32_e32 v144, v144
	v_rcp_f32_e32 v145, v145
	v_rcp_f32_e32 v146, v146
	v_rcp_f32_e32 v147, v147
	v_mul_f32_e32 v140, v88, v140
	v_mul_f32_e32 v141, v89, v141
	v_mul_f32_e32 v142, v90, v142
	v_mul_f32_e32 v143, v91, v143
	v_mul_f32_e32 v144, v92, v144
	v_mul_f32_e32 v145, v93, v145
	v_mul_f32_e32 v146, v94, v146
	v_mul_f32_e32 v147, v95, v147
	v_mul_f32_e32 v140, v72, v140
	v_mul_f32_e32 v141, v73, v141
	v_mul_f32_e32 v142, v74, v142
	v_mul_f32_e32 v143, v75, v143
	v_mul_f32_e32 v144, v76, v144
	v_mul_f32_e32 v145, v77, v145
	v_mul_f32_e32 v146, v78, v146
	v_mul_f32_e32 v147, v79, v147
	v_cvt_pk_bf16_f32 v160, v140, v141
	v_cvt_pk_bf16_f32 v161, v142, v143
	v_cvt_pk_bf16_f32 v162, v144, v145
	v_cvt_pk_bf16_f32 v163, v146, v147
	global_store_dwordx4 v133, v[160:163], s[12:13] offset:256 sc0 sc1 nt
	v_mul_f32_e32 v140, 0xbfb8aa3b, v48
	v_mul_f32_e32 v141, 0xbfb8aa3b, v49
	v_mul_f32_e32 v142, 0xbfb8aa3b, v50
	v_mul_f32_e32 v143, 0xbfb8aa3b, v51
	v_mul_f32_e32 v144, 0xbfb8aa3b, v52
	v_mul_f32_e32 v145, 0xbfb8aa3b, v53
	v_mul_f32_e32 v146, 0xbfb8aa3b, v54
	v_mul_f32_e32 v147, 0xbfb8aa3b, v55
	v_exp_f32_e32 v140, v140
	v_exp_f32_e32 v141, v141
	v_exp_f32_e32 v142, v142
	v_exp_f32_e32 v143, v143
	v_exp_f32_e32 v144, v144
	v_exp_f32_e32 v145, v145
	v_exp_f32_e32 v146, v146
	v_exp_f32_e32 v147, v147
	v_add_f32_e32 v140, 1.0, v140
	v_add_f32_e32 v141, 1.0, v141
	v_add_f32_e32 v142, 1.0, v142
	v_add_f32_e32 v143, 1.0, v143
	v_add_f32_e32 v144, 1.0, v144
	v_add_f32_e32 v145, 1.0, v145
	v_add_f32_e32 v146, 1.0, v146
	v_add_f32_e32 v147, 1.0, v147
	v_rcp_f32_e32 v140, v140
	v_rcp_f32_e32 v141, v141
	v_rcp_f32_e32 v142, v142
	v_rcp_f32_e32 v143, v143
	v_rcp_f32_e32 v144, v144
	v_rcp_f32_e32 v145, v145
	v_rcp_f32_e32 v146, v146
	v_rcp_f32_e32 v147, v147
	v_mul_f32_e32 v140, v48, v140
	v_mul_f32_e32 v141, v49, v141
	v_mul_f32_e32 v142, v50, v142
	v_mul_f32_e32 v143, v51, v143
	v_mul_f32_e32 v144, v52, v144
	v_mul_f32_e32 v145, v53, v145
	v_mul_f32_e32 v146, v54, v146
	v_mul_f32_e32 v147, v55, v147
	v_mul_f32_e32 v140, v32, v140
	v_mul_f32_e32 v141, v33, v141
	v_mul_f32_e32 v142, v34, v142
	v_mul_f32_e32 v143, v35, v143
	v_mul_f32_e32 v144, v36, v144
	v_mul_f32_e32 v145, v37, v145
	v_mul_f32_e32 v146, v38, v146
	v_mul_f32_e32 v147, v39, v147
	v_cvt_pk_bf16_f32 v148, v140, v141
	v_cvt_pk_bf16_f32 v149, v142, v143
	v_cvt_pk_bf16_f32 v150, v144, v145
	v_cvt_pk_bf16_f32 v151, v146, v147
	global_store_dwordx4 v132, v[148:151], s[12:13] offset:2048 sc0 sc1 nt
	v_mul_f32_e32 v140, 0xbfb8aa3b, v56
	v_mul_f32_e32 v141, 0xbfb8aa3b, v57
	v_mul_f32_e32 v142, 0xbfb8aa3b, v58
	v_mul_f32_e32 v143, 0xbfb8aa3b, v59
	v_mul_f32_e32 v144, 0xbfb8aa3b, v60
	v_mul_f32_e32 v145, 0xbfb8aa3b, v61
	v_mul_f32_e32 v146, 0xbfb8aa3b, v62
	v_mul_f32_e32 v147, 0xbfb8aa3b, v63
	v_exp_f32_e32 v140, v140
	v_exp_f32_e32 v141, v141
	v_exp_f32_e32 v142, v142
	v_exp_f32_e32 v143, v143
	v_exp_f32_e32 v144, v144
	v_exp_f32_e32 v145, v145
	v_exp_f32_e32 v146, v146
	v_exp_f32_e32 v147, v147
	v_add_f32_e32 v140, 1.0, v140
	v_add_f32_e32 v141, 1.0, v141
	v_add_f32_e32 v142, 1.0, v142
	v_add_f32_e32 v143, 1.0, v143
	v_add_f32_e32 v144, 1.0, v144
	v_add_f32_e32 v145, 1.0, v145
	v_add_f32_e32 v146, 1.0, v146
	v_add_f32_e32 v147, 1.0, v147
	v_rcp_f32_e32 v140, v140
	v_rcp_f32_e32 v141, v141
	v_rcp_f32_e32 v142, v142
	v_rcp_f32_e32 v143, v143
	v_rcp_f32_e32 v144, v144
	v_rcp_f32_e32 v145, v145
	v_rcp_f32_e32 v146, v146
	v_rcp_f32_e32 v147, v147
	v_mul_f32_e32 v140, v56, v140
	v_mul_f32_e32 v141, v57, v141
	v_mul_f32_e32 v142, v58, v142
	v_mul_f32_e32 v143, v59, v143
	v_mul_f32_e32 v144, v60, v144
	v_mul_f32_e32 v145, v61, v145
	v_mul_f32_e32 v146, v62, v146
	v_mul_f32_e32 v147, v63, v147
	v_mul_f32_e32 v140, v40, v140
	v_mul_f32_e32 v141, v41, v141
	v_mul_f32_e32 v142, v42, v142
	v_mul_f32_e32 v143, v43, v143
	v_mul_f32_e32 v144, v44, v144
	v_mul_f32_e32 v145, v45, v145
	v_mul_f32_e32 v146, v46, v146
	v_mul_f32_e32 v147, v47, v147
	v_cvt_pk_bf16_f32 v152, v140, v141
	v_cvt_pk_bf16_f32 v153, v142, v143
	v_cvt_pk_bf16_f32 v154, v144, v145
	v_cvt_pk_bf16_f32 v155, v146, v147
	global_store_dwordx4 v132, v[152:155], s[12:13] offset:2304 sc0 sc1 nt
	v_mul_f32_e32 v140, 0xbfb8aa3b, v16
	v_mul_f32_e32 v141, 0xbfb8aa3b, v17
	v_mul_f32_e32 v142, 0xbfb8aa3b, v18
	v_mul_f32_e32 v143, 0xbfb8aa3b, v19
	v_mul_f32_e32 v144, 0xbfb8aa3b, v20
	v_mul_f32_e32 v145, 0xbfb8aa3b, v21
	v_mul_f32_e32 v146, 0xbfb8aa3b, v22
	v_mul_f32_e32 v147, 0xbfb8aa3b, v23
	v_exp_f32_e32 v140, v140
	v_exp_f32_e32 v141, v141
	v_exp_f32_e32 v142, v142
	v_exp_f32_e32 v143, v143
	v_exp_f32_e32 v144, v144
	v_exp_f32_e32 v145, v145
	v_exp_f32_e32 v146, v146
	v_exp_f32_e32 v147, v147
	v_add_f32_e32 v140, 1.0, v140
	v_add_f32_e32 v141, 1.0, v141
	v_add_f32_e32 v142, 1.0, v142
	v_add_f32_e32 v143, 1.0, v143
	v_add_f32_e32 v144, 1.0, v144
	v_add_f32_e32 v145, 1.0, v145
	v_add_f32_e32 v146, 1.0, v146
	v_add_f32_e32 v147, 1.0, v147
	v_rcp_f32_e32 v140, v140
	v_rcp_f32_e32 v141, v141
	v_rcp_f32_e32 v142, v142
	v_rcp_f32_e32 v143, v143
	v_rcp_f32_e32 v144, v144
	v_rcp_f32_e32 v145, v145
	v_rcp_f32_e32 v146, v146
	v_rcp_f32_e32 v147, v147
	v_mul_f32_e32 v140, v16, v140
	v_mul_f32_e32 v141, v17, v141
	v_mul_f32_e32 v142, v18, v142
	v_mul_f32_e32 v143, v19, v143
	v_mul_f32_e32 v144, v20, v144
	v_mul_f32_e32 v145, v21, v145
	v_mul_f32_e32 v146, v22, v146
	v_mul_f32_e32 v147, v23, v147
	v_mul_f32_e32 v140, v0, v140
	v_mul_f32_e32 v141, v1, v141
	v_mul_f32_e32 v142, v2, v142
	v_mul_f32_e32 v143, v3, v143
	v_mul_f32_e32 v144, v4, v144
	v_mul_f32_e32 v145, v5, v145
	v_mul_f32_e32 v146, v6, v146
	v_mul_f32_e32 v147, v7, v147
	v_cvt_pk_bf16_f32 v156, v140, v141
	v_cvt_pk_bf16_f32 v157, v142, v143
	v_cvt_pk_bf16_f32 v158, v144, v145
	v_cvt_pk_bf16_f32 v159, v146, v147
	global_store_dwordx4 v133, v[156:159], s[12:13] offset:2048 sc0 sc1 nt
	v_mul_f32_e32 v140, 0xbfb8aa3b, v24
	v_mul_f32_e32 v141, 0xbfb8aa3b, v25
	v_mul_f32_e32 v142, 0xbfb8aa3b, v26
	v_mul_f32_e32 v143, 0xbfb8aa3b, v27
	v_mul_f32_e32 v144, 0xbfb8aa3b, v28
	v_mul_f32_e32 v145, 0xbfb8aa3b, v29
	v_mul_f32_e32 v146, 0xbfb8aa3b, v30
	v_mul_f32_e32 v147, 0xbfb8aa3b, v31
	v_exp_f32_e32 v140, v140
	v_exp_f32_e32 v141, v141
	v_exp_f32_e32 v142, v142
	v_exp_f32_e32 v143, v143
	v_exp_f32_e32 v144, v144
	v_exp_f32_e32 v145, v145
	v_exp_f32_e32 v146, v146
	v_exp_f32_e32 v147, v147
	v_add_f32_e32 v140, 1.0, v140
	v_add_f32_e32 v141, 1.0, v141
	v_add_f32_e32 v142, 1.0, v142
	v_add_f32_e32 v143, 1.0, v143
	v_add_f32_e32 v144, 1.0, v144
	v_add_f32_e32 v145, 1.0, v145
	v_add_f32_e32 v146, 1.0, v146
	v_add_f32_e32 v147, 1.0, v147
	v_rcp_f32_e32 v140, v140
	v_rcp_f32_e32 v141, v141
	v_rcp_f32_e32 v142, v142
	v_rcp_f32_e32 v143, v143
	v_rcp_f32_e32 v144, v144
	v_rcp_f32_e32 v145, v145
	v_rcp_f32_e32 v146, v146
	v_rcp_f32_e32 v147, v147
	v_mul_f32_e32 v140, v24, v140
	v_mul_f32_e32 v141, v25, v141
	v_mul_f32_e32 v142, v26, v142
	v_mul_f32_e32 v143, v27, v143
	v_mul_f32_e32 v144, v28, v144
	v_mul_f32_e32 v145, v29, v145
	v_mul_f32_e32 v146, v30, v146
	v_mul_f32_e32 v147, v31, v147
	v_mul_f32_e32 v140, v8, v140
	v_mul_f32_e32 v141, v9, v141
	v_mul_f32_e32 v142, v10, v142
	v_mul_f32_e32 v143, v11, v143
	v_mul_f32_e32 v144, v12, v144
	v_mul_f32_e32 v145, v13, v145
	v_mul_f32_e32 v146, v14, v146
	v_mul_f32_e32 v147, v15, v147
	v_cvt_pk_bf16_f32 v160, v140, v141
	v_cvt_pk_bf16_f32 v161, v142, v143
	v_cvt_pk_bf16_f32 v162, v144, v145
	v_cvt_pk_bf16_f32 v163, v146, v147
	global_store_dwordx4 v133, v[160:163], s[12:13] offset:2304 sc0 sc1 nt
	v_readlane_b32 s0, v254, 11
	s_add_i32 s2, s2, s0
	s_cmp_lt_i32 s2, s3
	s_barrier
	s_cbranch_scc1 .LBB0_1031

.Lg16_down_k:
	s_add_i32 s9, s8, 2
	s_lshl_b32 s96, s9, 13
	s_add_i32 m0, vcc_lo, 16384
	v_lshl_add_u64 v[160:161], v[188:189], 0, s[96:97]
	global_load_lds_dwordx4 v[160:161], off
	global_load_lds_dwordx4 v[160:161], off offset:1024
	ds_read_b128 v[196:199], v246 offset:0
	ds_read_b128 v[200:203], v162 offset:0
	ds_read_b128 v[204:207], v246 offset:2048
	ds_read_b128 v[242:245], v162 offset:2048
	s_add_i32 s9, s8, 2
	s_lshl_b32 s96, s9, 11
	v_lshl_add_u64 v[248:249], v[184:185], 0, s[96:97]
	v_lshl_add_u64 v[250:251], v[186:187], 0, s[96:97]
	s_waitcnt vmcnt(8) lgkmcnt(3)
	v_mfma_f32_16x16x32_bf16 v[112:115], v[196:199], v[128:131], v[112:115]
	v_mfma_f32_16x16x32_bf16 v[120:123], v[196:199], v[132:135], v[120:123]
	v_mfma_f32_16x16x32_bf16 v[48:51], v[196:199], v[136:139], v[48:51]
	v_mfma_f32_16x16x32_bf16 v[56:59], v[196:199], v[140:143], v[56:59]
	ds_read_b128 v[196:199], v246 offset:4096
	s_waitcnt lgkmcnt(3)
	v_mfma_f32_16x16x32_bf16 v[116:119], v[200:203], v[128:131], v[116:119]
	v_mfma_f32_16x16x32_bf16 v[124:127], v[200:203], v[132:135], v[124:127]
	v_mfma_f32_16x16x32_bf16 v[52:55], v[200:203], v[136:139], v[52:55]
	v_mfma_f32_16x16x32_bf16 v[60:63], v[200:203], v[140:143], v[60:63]
	ds_read_b128 v[200:203], v162 offset:4096
	s_waitcnt lgkmcnt(3)
	v_mfma_f32_16x16x32_bf16 v[96:99], v[204:207], v[128:131], v[96:99]
	v_mfma_f32_16x16x32_bf16 v[104:107], v[204:207], v[132:135], v[104:107]
	v_mfma_f32_16x16x32_bf16 v[32:35], v[204:207], v[136:139], v[32:35]
	v_mfma_f32_16x16x32_bf16 v[40:43], v[204:207], v[140:143], v[40:43]
	ds_read_b128 v[204:207], v246 offset:6144
	s_waitcnt lgkmcnt(3)
	v_mfma_f32_16x16x32_bf16 v[100:103], v[242:245], v[128:131], v[100:103]
	v_mfma_f32_16x16x32_bf16 v[108:111], v[242:245], v[132:135], v[108:111]
	v_mfma_f32_16x16x32_bf16 v[36:39], v[242:245], v[136:139], v[36:39]
	v_mfma_f32_16x16x32_bf16 v[44:47], v[242:245], v[140:143], v[44:47]
	ds_read_b128 v[242:245], v162 offset:6144
	s_waitcnt lgkmcnt(3)
	v_mfma_f32_16x16x32_bf16 v[80:83], v[196:199], v[128:131], v[80:83]
	v_mfma_f32_16x16x32_bf16 v[88:91], v[196:199], v[132:135], v[88:91]
	v_mfma_f32_16x16x32_bf16 v[16:19], v[196:199], v[136:139], v[16:19]
	v_mfma_f32_16x16x32_bf16 v[24:27], v[196:199], v[140:143], v[24:27]
	s_waitcnt lgkmcnt(2)
	v_mfma_f32_16x16x32_bf16 v[84:87], v[200:203], v[128:131], v[84:87]
	v_mfma_f32_16x16x32_bf16 v[92:95], v[200:203], v[132:135], v[92:95]
	v_mfma_f32_16x16x32_bf16 v[20:23], v[200:203], v[136:139], v[20:23]
	v_mfma_f32_16x16x32_bf16 v[28:31], v[200:203], v[140:143], v[28:31]
	s_waitcnt lgkmcnt(1)
	v_mfma_f32_16x16x32_bf16 v[64:67], v[204:207], v[128:131], v[64:67]
	v_mfma_f32_16x16x32_bf16 v[72:75], v[204:207], v[132:135], v[72:75]
	v_mfma_f32_16x16x32_bf16 v[0:3], v[204:207], v[136:139], v[0:3]
	v_mfma_f32_16x16x32_bf16 v[8:11], v[204:207], v[140:143], v[8:11]
	s_waitcnt lgkmcnt(0)
	v_mfma_f32_16x16x32_bf16 v[68:71], v[242:245], v[128:131], v[68:71]
	v_mfma_f32_16x16x32_bf16 v[76:79], v[242:245], v[132:135], v[76:79]
	v_mfma_f32_16x16x32_bf16 v[4:7], v[242:245], v[136:139], v[4:7]
	v_mfma_f32_16x16x32_bf16 v[12:15], v[242:245], v[140:143], v[12:15]
	global_load_dwordx4 v[128:131], v[248:249], off
	global_load_dwordx4 v[132:135], v[248:249], off offset:256
	global_load_dwordx4 v[136:139], v[250:251], off
	global_load_dwordx4 v[140:143], v[250:251], off offset:256
	s_waitcnt vmcnt(10)
	s_barrier
	s_add_i32 s9, s8, 3
	s_lshl_b32 s96, s9, 13
	s_mov_b32 m0, vcc_lo
	v_lshl_add_u64 v[160:161], v[188:189], 0, s[96:97]
	global_load_lds_dwordx4 v[160:161], off
	global_load_lds_dwordx4 v[160:161], off offset:1024
	ds_read_b128 v[196:199], v246 offset:8192
	ds_read_b128 v[200:203], v162 offset:8192
	ds_read_b128 v[204:207], v246 offset:10240
	ds_read_b128 v[242:245], v162 offset:10240
	s_add_i32 s9, s8, 3
	s_lshl_b32 s96, s9, 11
	v_lshl_add_u64 v[248:249], v[184:185], 0, s[96:97]
	v_lshl_add_u64 v[250:251], v[186:187], 0, s[96:97]
	s_waitcnt vmcnt(8) lgkmcnt(3)
	v_mfma_f32_16x16x32_bf16 v[112:115], v[196:199], v[144:147], v[112:115]
	v_mfma_f32_16x16x32_bf16 v[120:123], v[196:199], v[148:151], v[120:123]
	v_mfma_f32_16x16x32_bf16 v[48:51], v[196:199], v[152:155], v[48:51]
	v_mfma_f32_16x16x32_bf16 v[56:59], v[196:199], v[156:159], v[56:59]
	ds_read_b128 v[196:199], v246 offset:12288
	s_waitcnt lgkmcnt(3)
	v_mfma_f32_16x16x32_bf16 v[116:119], v[200:203], v[144:147], v[116:119]
	v_mfma_f32_16x16x32_bf16 v[124:127], v[200:203], v[148:151], v[124:127]
	v_mfma_f32_16x16x32_bf16 v[52:55], v[200:203], v[152:155], v[52:55]
	v_mfma_f32_16x16x32_bf16 v[60:63], v[200:203], v[156:159], v[60:63]
	ds_read_b128 v[200:203], v162 offset:12288
	s_waitcnt lgkmcnt(3)
	v_mfma_f32_16x16x32_bf16 v[96:99], v[204:207], v[144:147], v[96:99]
	v_mfma_f32_16x16x32_bf16 v[104:107], v[204:207], v[148:151], v[104:107]
	v_mfma_f32_16x16x32_bf16 v[32:35], v[204:207], v[152:155], v[32:35]
	v_mfma_f32_16x16x32_bf16 v[40:43], v[204:207], v[156:159], v[40:43]
	ds_read_b128 v[204:207], v246 offset:14336
	s_waitcnt lgkmcnt(3)
	v_mfma_f32_16x16x32_bf16 v[100:103], v[242:245], v[144:147], v[100:103]
	v_mfma_f32_16x16x32_bf16 v[108:111], v[242:245], v[148:151], v[108:111]
	v_mfma_f32_16x16x32_bf16 v[36:39], v[242:245], v[152:155], v[36:39]
	v_mfma_f32_16x16x32_bf16 v[44:47], v[242:245], v[156:159], v[44:47]
	ds_read_b128 v[242:245], v162 offset:14336
	s_waitcnt lgkmcnt(3)
	v_mfma_f32_16x16x32_bf16 v[80:83], v[196:199], v[144:147], v[80:83]
	v_mfma_f32_16x16x32_bf16 v[88:91], v[196:199], v[148:151], v[88:91]
	v_mfma_f32_16x16x32_bf16 v[16:19], v[196:199], v[152:155], v[16:19]
	v_mfma_f32_16x16x32_bf16 v[24:27], v[196:199], v[156:159], v[24:27]
	s_waitcnt lgkmcnt(2)
	v_mfma_f32_16x16x32_bf16 v[84:87], v[200:203], v[144:147], v[84:87]
	v_mfma_f32_16x16x32_bf16 v[92:95], v[200:203], v[148:151], v[92:95]
	v_mfma_f32_16x16x32_bf16 v[20:23], v[200:203], v[152:155], v[20:23]
	v_mfma_f32_16x16x32_bf16 v[28:31], v[200:203], v[156:159], v[28:31]
	s_waitcnt lgkmcnt(1)
	v_mfma_f32_16x16x32_bf16 v[64:67], v[204:207], v[144:147], v[64:67]
	v_mfma_f32_16x16x32_bf16 v[72:75], v[204:207], v[148:151], v[72:75]
	v_mfma_f32_16x16x32_bf16 v[0:3], v[204:207], v[152:155], v[0:3]
	v_mfma_f32_16x16x32_bf16 v[8:11], v[204:207], v[156:159], v[8:11]
	s_waitcnt lgkmcnt(0)
	v_mfma_f32_16x16x32_bf16 v[68:71], v[242:245], v[144:147], v[68:71]
	v_mfma_f32_16x16x32_bf16 v[76:79], v[242:245], v[148:151], v[76:79]
	v_mfma_f32_16x16x32_bf16 v[4:7], v[242:245], v[152:155], v[4:7]
	v_mfma_f32_16x16x32_bf16 v[12:15], v[242:245], v[156:159], v[12:15]
	global_load_dwordx4 v[144:147], v[248:249], off
	global_load_dwordx4 v[148:151], v[248:249], off offset:256
	global_load_dwordx4 v[152:155], v[250:251], off
	global_load_dwordx4 v[156:159], v[250:251], off offset:256
	s_waitcnt vmcnt(10)
	s_barrier
	s_add_i32 s9, s8, 4
	s_lshl_b32 s96, s9, 13
	s_add_i32 m0, vcc_lo, 8192
	v_lshl_add_u64 v[160:161], v[188:189], 0, s[96:97]
	global_load_lds_dwordx4 v[160:161], off
	global_load_lds_dwordx4 v[160:161], off offset:1024
	ds_read_b128 v[196:199], v246 offset:16384
	ds_read_b128 v[200:203], v162 offset:16384
	ds_read_b128 v[204:207], v246 offset:18432
	ds_read_b128 v[242:245], v162 offset:18432
	s_add_i32 s9, s8, 4
	s_lshl_b32 s96, s9, 11
	v_lshl_add_u64 v[248:249], v[184:185], 0, s[96:97]
	v_lshl_add_u64 v[250:251], v[186:187], 0, s[96:97]
	s_waitcnt vmcnt(8) lgkmcnt(3)
	v_mfma_f32_16x16x32_bf16 v[112:115], v[196:199], v[128:131], v[112:115]
	v_mfma_f32_16x16x32_bf16 v[120:123], v[196:199], v[132:135], v[120:123]
	v_mfma_f32_16x16x32_bf16 v[48:51], v[196:199], v[136:139], v[48:51]
	v_mfma_f32_16x16x32_bf16 v[56:59], v[196:199], v[140:143], v[56:59]
	ds_read_b128 v[196:199], v246 offset:20480
	s_waitcnt lgkmcnt(3)
	v_mfma_f32_16x16x32_bf16 v[116:119], v[200:203], v[128:131], v[116:119]
	v_mfma_f32_16x16x32_bf16 v[124:127], v[200:203], v[132:135], v[124:127]
	v_mfma_f32_16x16x32_bf16 v[52:55], v[200:203], v[136:139], v[52:55]
	v_mfma_f32_16x16x32_bf16 v[60:63], v[200:203], v[140:143], v[60:63]
	ds_read_b128 v[200:203], v162 offset:20480
	s_waitcnt lgkmcnt(3)
	v_mfma_f32_16x16x32_bf16 v[96:99], v[204:207], v[128:131], v[96:99]
	v_mfma_f32_16x16x32_bf16 v[104:107], v[204:207], v[132:135], v[104:107]
	v_mfma_f32_16x16x32_bf16 v[32:35], v[204:207], v[136:139], v[32:35]
	v_mfma_f32_16x16x32_bf16 v[40:43], v[204:207], v[140:143], v[40:43]
	ds_read_b128 v[204:207], v246 offset:22528
	s_waitcnt lgkmcnt(3)
	v_mfma_f32_16x16x32_bf16 v[100:103], v[242:245], v[128:131], v[100:103]
	v_mfma_f32_16x16x32_bf16 v[108:111], v[242:245], v[132:135], v[108:111]
	v_mfma_f32_16x16x32_bf16 v[36:39], v[242:245], v[136:139], v[36:39]
	v_mfma_f32_16x16x32_bf16 v[44:47], v[242:245], v[140:143], v[44:47]
	ds_read_b128 v[242:245], v162 offset:22528
	s_waitcnt lgkmcnt(3)
	v_mfma_f32_16x16x32_bf16 v[80:83], v[196:199], v[128:131], v[80:83]
	v_mfma_f32_16x16x32_bf16 v[88:91], v[196:199], v[132:135], v[88:91]
	v_mfma_f32_16x16x32_bf16 v[16:19], v[196:199], v[136:139], v[16:19]
	v_mfma_f32_16x16x32_bf16 v[24:27], v[196:199], v[140:143], v[24:27]
	s_waitcnt lgkmcnt(2)
	v_mfma_f32_16x16x32_bf16 v[84:87], v[200:203], v[128:131], v[84:87]
	v_mfma_f32_16x16x32_bf16 v[92:95], v[200:203], v[132:135], v[92:95]
	v_mfma_f32_16x16x32_bf16 v[20:23], v[200:203], v[136:139], v[20:23]
	v_mfma_f32_16x16x32_bf16 v[28:31], v[200:203], v[140:143], v[28:31]
	s_waitcnt lgkmcnt(1)
	v_mfma_f32_16x16x32_bf16 v[64:67], v[204:207], v[128:131], v[64:67]
	v_mfma_f32_16x16x32_bf16 v[72:75], v[204:207], v[132:135], v[72:75]
	v_mfma_f32_16x16x32_bf16 v[0:3], v[204:207], v[136:139], v[0:3]
	v_mfma_f32_16x16x32_bf16 v[8:11], v[204:207], v[140:143], v[8:11]
	s_waitcnt lgkmcnt(0)
	v_mfma_f32_16x16x32_bf16 v[68:71], v[242:245], v[128:131], v[68:71]
	v_mfma_f32_16x16x32_bf16 v[76:79], v[242:245], v[132:135], v[76:79]
	v_mfma_f32_16x16x32_bf16 v[4:7], v[242:245], v[136:139], v[4:7]
	v_mfma_f32_16x16x32_bf16 v[12:15], v[242:245], v[140:143], v[12:15]
	global_load_dwordx4 v[128:131], v[248:249], off
	global_load_dwordx4 v[132:135], v[248:249], off offset:256
	global_load_dwordx4 v[136:139], v[250:251], off
	global_load_dwordx4 v[140:143], v[250:251], off offset:256
	s_waitcnt vmcnt(10)
	s_barrier
	s_add_i32 s9, s8, 5
	s_lshl_b32 s96, s9, 13
	s_add_i32 m0, vcc_lo, 16384
	v_lshl_add_u64 v[160:161], v[188:189], 0, s[96:97]
	global_load_lds_dwordx4 v[160:161], off
	global_load_lds_dwordx4 v[160:161], off offset:1024
	ds_read_b128 v[196:199], v246 offset:0
	ds_read_b128 v[200:203], v162 offset:0
	ds_read_b128 v[204:207], v246 offset:2048
	ds_read_b128 v[242:245], v162 offset:2048
	s_add_i32 s9, s8, 5
	s_lshl_b32 s96, s9, 11
	v_lshl_add_u64 v[248:249], v[184:185], 0, s[96:97]
	v_lshl_add_u64 v[250:251], v[186:187], 0, s[96:97]
	s_waitcnt vmcnt(8) lgkmcnt(3)
	v_mfma_f32_16x16x32_bf16 v[112:115], v[196:199], v[144:147], v[112:115]
	v_mfma_f32_16x16x32_bf16 v[120:123], v[196:199], v[148:151], v[120:123]
	v_mfma_f32_16x16x32_bf16 v[48:51], v[196:199], v[152:155], v[48:51]
	v_mfma_f32_16x16x32_bf16 v[56:59], v[196:199], v[156:159], v[56:59]
	ds_read_b128 v[196:199], v246 offset:4096
	s_waitcnt lgkmcnt(3)
	v_mfma_f32_16x16x32_bf16 v[116:119], v[200:203], v[144:147], v[116:119]
	v_mfma_f32_16x16x32_bf16 v[124:127], v[200:203], v[148:151], v[124:127]
	v_mfma_f32_16x16x32_bf16 v[52:55], v[200:203], v[152:155], v[52:55]
	v_mfma_f32_16x16x32_bf16 v[60:63], v[200:203], v[156:159], v[60:63]
	ds_read_b128 v[200:203], v162 offset:4096
	s_waitcnt lgkmcnt(3)
	v_mfma_f32_16x16x32_bf16 v[96:99], v[204:207], v[144:147], v[96:99]
	v_mfma_f32_16x16x32_bf16 v[104:107], v[204:207], v[148:151], v[104:107]
	v_mfma_f32_16x16x32_bf16 v[32:35], v[204:207], v[152:155], v[32:35]
	v_mfma_f32_16x16x32_bf16 v[40:43], v[204:207], v[156:159], v[40:43]
	ds_read_b128 v[204:207], v246 offset:6144
	s_waitcnt lgkmcnt(3)
	v_mfma_f32_16x16x32_bf16 v[100:103], v[242:245], v[144:147], v[100:103]
	v_mfma_f32_16x16x32_bf16 v[108:111], v[242:245], v[148:151], v[108:111]
	v_mfma_f32_16x16x32_bf16 v[36:39], v[242:245], v[152:155], v[36:39]
	v_mfma_f32_16x16x32_bf16 v[44:47], v[242:245], v[156:159], v[44:47]
	ds_read_b128 v[242:245], v162 offset:6144
	s_waitcnt lgkmcnt(3)
	v_mfma_f32_16x16x32_bf16 v[80:83], v[196:199], v[144:147], v[80:83]
	v_mfma_f32_16x16x32_bf16 v[88:91], v[196:199], v[148:151], v[88:91]
	v_mfma_f32_16x16x32_bf16 v[16:19], v[196:199], v[152:155], v[16:19]
	v_mfma_f32_16x16x32_bf16 v[24:27], v[196:199], v[156:159], v[24:27]
	s_waitcnt lgkmcnt(2)
	v_mfma_f32_16x16x32_bf16 v[84:87], v[200:203], v[144:147], v[84:87]
	v_mfma_f32_16x16x32_bf16 v[92:95], v[200:203], v[148:151], v[92:95]
	v_mfma_f32_16x16x32_bf16 v[20:23], v[200:203], v[152:155], v[20:23]
	v_mfma_f32_16x16x32_bf16 v[28:31], v[200:203], v[156:159], v[28:31]
	s_waitcnt lgkmcnt(1)
	v_mfma_f32_16x16x32_bf16 v[64:67], v[204:207], v[144:147], v[64:67]
	v_mfma_f32_16x16x32_bf16 v[72:75], v[204:207], v[148:151], v[72:75]
	v_mfma_f32_16x16x32_bf16 v[0:3], v[204:207], v[152:155], v[0:3]
	v_mfma_f32_16x16x32_bf16 v[8:11], v[204:207], v[156:159], v[8:11]
	s_waitcnt lgkmcnt(0)
	v_mfma_f32_16x16x32_bf16 v[68:71], v[242:245], v[144:147], v[68:71]
	v_mfma_f32_16x16x32_bf16 v[76:79], v[242:245], v[148:151], v[76:79]
	v_mfma_f32_16x16x32_bf16 v[4:7], v[242:245], v[152:155], v[4:7]
	v_mfma_f32_16x16x32_bf16 v[12:15], v[242:245], v[156:159], v[12:15]
	global_load_dwordx4 v[144:147], v[248:249], off
	global_load_dwordx4 v[148:151], v[248:249], off offset:256
	global_load_dwordx4 v[152:155], v[250:251], off
	global_load_dwordx4 v[156:159], v[250:251], off offset:256
	s_waitcnt vmcnt(10)
	s_barrier
	s_add_i32 s9, s8, 6
	s_lshl_b32 s96, s9, 13
	s_mov_b32 m0, vcc_lo
	v_lshl_add_u64 v[160:161], v[188:189], 0, s[96:97]
	global_load_lds_dwordx4 v[160:161], off
	global_load_lds_dwordx4 v[160:161], off offset:1024
	ds_read_b128 v[196:199], v246 offset:8192
	ds_read_b128 v[200:203], v162 offset:8192
	ds_read_b128 v[204:207], v246 offset:10240
	ds_read_b128 v[242:245], v162 offset:10240
	s_add_i32 s9, s8, 6
	s_lshl_b32 s96, s9, 11
	v_lshl_add_u64 v[248:249], v[184:185], 0, s[96:97]
	v_lshl_add_u64 v[250:251], v[186:187], 0, s[96:97]
	s_waitcnt vmcnt(8) lgkmcnt(3)
	v_mfma_f32_16x16x32_bf16 v[112:115], v[196:199], v[128:131], v[112:115]
	v_mfma_f32_16x16x32_bf16 v[120:123], v[196:199], v[132:135], v[120:123]
	v_mfma_f32_16x16x32_bf16 v[48:51], v[196:199], v[136:139], v[48:51]
	v_mfma_f32_16x16x32_bf16 v[56:59], v[196:199], v[140:143], v[56:59]
	ds_read_b128 v[196:199], v246 offset:12288
	s_waitcnt lgkmcnt(3)
	v_mfma_f32_16x16x32_bf16 v[116:119], v[200:203], v[128:131], v[116:119]
	v_mfma_f32_16x16x32_bf16 v[124:127], v[200:203], v[132:135], v[124:127]
	v_mfma_f32_16x16x32_bf16 v[52:55], v[200:203], v[136:139], v[52:55]
	v_mfma_f32_16x16x32_bf16 v[60:63], v[200:203], v[140:143], v[60:63]
	ds_read_b128 v[200:203], v162 offset:12288
	s_waitcnt lgkmcnt(3)
	v_mfma_f32_16x16x32_bf16 v[96:99], v[204:207], v[128:131], v[96:99]
	v_mfma_f32_16x16x32_bf16 v[104:107], v[204:207], v[132:135], v[104:107]
	v_mfma_f32_16x16x32_bf16 v[32:35], v[204:207], v[136:139], v[32:35]
	v_mfma_f32_16x16x32_bf16 v[40:43], v[204:207], v[140:143], v[40:43]
	ds_read_b128 v[204:207], v246 offset:14336
	s_waitcnt lgkmcnt(3)
	v_mfma_f32_16x16x32_bf16 v[100:103], v[242:245], v[128:131], v[100:103]
	v_mfma_f32_16x16x32_bf16 v[108:111], v[242:245], v[132:135], v[108:111]
	v_mfma_f32_16x16x32_bf16 v[36:39], v[242:245], v[136:139], v[36:39]
	v_mfma_f32_16x16x32_bf16 v[44:47], v[242:245], v[140:143], v[44:47]
	ds_read_b128 v[242:245], v162 offset:14336
	s_waitcnt lgkmcnt(3)
	v_mfma_f32_16x16x32_bf16 v[80:83], v[196:199], v[128:131], v[80:83]
	v_mfma_f32_16x16x32_bf16 v[88:91], v[196:199], v[132:135], v[88:91]
	v_mfma_f32_16x16x32_bf16 v[16:19], v[196:199], v[136:139], v[16:19]
	v_mfma_f32_16x16x32_bf16 v[24:27], v[196:199], v[140:143], v[24:27]
	s_waitcnt lgkmcnt(2)
	v_mfma_f32_16x16x32_bf16 v[84:87], v[200:203], v[128:131], v[84:87]
	v_mfma_f32_16x16x32_bf16 v[92:95], v[200:203], v[132:135], v[92:95]
	v_mfma_f32_16x16x32_bf16 v[20:23], v[200:203], v[136:139], v[20:23]
	v_mfma_f32_16x16x32_bf16 v[28:31], v[200:203], v[140:143], v[28:31]
	s_waitcnt lgkmcnt(1)
	v_mfma_f32_16x16x32_bf16 v[64:67], v[204:207], v[128:131], v[64:67]
	v_mfma_f32_16x16x32_bf16 v[72:75], v[204:207], v[132:135], v[72:75]
	v_mfma_f32_16x16x32_bf16 v[0:3], v[204:207], v[136:139], v[0:3]
	v_mfma_f32_16x16x32_bf16 v[8:11], v[204:207], v[140:143], v[8:11]
	s_waitcnt lgkmcnt(0)
	v_mfma_f32_16x16x32_bf16 v[68:71], v[242:245], v[128:131], v[68:71]
	v_mfma_f32_16x16x32_bf16 v[76:79], v[242:245], v[132:135], v[76:79]
	v_mfma_f32_16x16x32_bf16 v[4:7], v[242:245], v[136:139], v[4:7]
	v_mfma_f32_16x16x32_bf16 v[12:15], v[242:245], v[140:143], v[12:15]
	global_load_dwordx4 v[128:131], v[248:249], off
	global_load_dwordx4 v[132:135], v[248:249], off offset:256
	global_load_dwordx4 v[136:139], v[250:251], off
	global_load_dwordx4 v[140:143], v[250:251], off offset:256
	s_waitcnt vmcnt(10)
	s_barrier
	s_add_i32 s9, s8, 7
	s_lshl_b32 s96, s9, 13
	s_add_i32 m0, vcc_lo, 8192
	v_lshl_add_u64 v[160:161], v[188:189], 0, s[96:97]
	global_load_lds_dwordx4 v[160:161], off
	global_load_lds_dwordx4 v[160:161], off offset:1024
	ds_read_b128 v[196:199], v246 offset:16384
	ds_read_b128 v[200:203], v162 offset:16384
	ds_read_b128 v[204:207], v246 offset:18432
	ds_read_b128 v[242:245], v162 offset:18432
	s_add_i32 s9, s8, 7
	s_lshl_b32 s96, s9, 11
	v_lshl_add_u64 v[248:249], v[184:185], 0, s[96:97]
	v_lshl_add_u64 v[250:251], v[186:187], 0, s[96:97]
	s_waitcnt vmcnt(8) lgkmcnt(3)
	v_mfma_f32_16x16x32_bf16 v[112:115], v[196:199], v[144:147], v[112:115]
	v_mfma_f32_16x16x32_bf16 v[120:123], v[196:199], v[148:151], v[120:123]
	v_mfma_f32_16x16x32_bf16 v[48:51], v[196:199], v[152:155], v[48:51]
	v_mfma_f32_16x16x32_bf16 v[56:59], v[196:199], v[156:159], v[56:59]
	ds_read_b128 v[196:199], v246 offset:20480
	s_waitcnt lgkmcnt(3)
	v_mfma_f32_16x16x32_bf16 v[116:119], v[200:203], v[144:147], v[116:119]
	v_mfma_f32_16x16x32_bf16 v[124:127], v[200:203], v[148:151], v[124:127]
	v_mfma_f32_16x16x32_bf16 v[52:55], v[200:203], v[152:155], v[52:55]
	v_mfma_f32_16x16x32_bf16 v[60:63], v[200:203], v[156:159], v[60:63]
	ds_read_b128 v[200:203], v162 offset:20480
	s_waitcnt lgkmcnt(3)
	v_mfma_f32_16x16x32_bf16 v[96:99], v[204:207], v[144:147], v[96:99]
	v_mfma_f32_16x16x32_bf16 v[104:107], v[204:207], v[148:151], v[104:107]
	v_mfma_f32_16x16x32_bf16 v[32:35], v[204:207], v[152:155], v[32:35]
	v_mfma_f32_16x16x32_bf16 v[40:43], v[204:207], v[156:159], v[40:43]
	ds_read_b128 v[204:207], v246 offset:22528
	s_waitcnt lgkmcnt(3)
	v_mfma_f32_16x16x32_bf16 v[100:103], v[242:245], v[144:147], v[100:103]
	v_mfma_f32_16x16x32_bf16 v[108:111], v[242:245], v[148:151], v[108:111]
	v_mfma_f32_16x16x32_bf16 v[36:39], v[242:245], v[152:155], v[36:39]
	v_mfma_f32_16x16x32_bf16 v[44:47], v[242:245], v[156:159], v[44:47]
	ds_read_b128 v[242:245], v162 offset:22528
	s_waitcnt lgkmcnt(3)
	v_mfma_f32_16x16x32_bf16 v[80:83], v[196:199], v[144:147], v[80:83]
	v_mfma_f32_16x16x32_bf16 v[88:91], v[196:199], v[148:151], v[88:91]
	v_mfma_f32_16x16x32_bf16 v[16:19], v[196:199], v[152:155], v[16:19]
	v_mfma_f32_16x16x32_bf16 v[24:27], v[196:199], v[156:159], v[24:27]
	s_waitcnt lgkmcnt(2)
	v_mfma_f32_16x16x32_bf16 v[84:87], v[200:203], v[144:147], v[84:87]
	v_mfma_f32_16x16x32_bf16 v[92:95], v[200:203], v[148:151], v[92:95]
	v_mfma_f32_16x16x32_bf16 v[20:23], v[200:203], v[152:155], v[20:23]
	v_mfma_f32_16x16x32_bf16 v[28:31], v[200:203], v[156:159], v[28:31]
	s_waitcnt lgkmcnt(1)
	v_mfma_f32_16x16x32_bf16 v[64:67], v[204:207], v[144:147], v[64:67]
	v_mfma_f32_16x16x32_bf16 v[72:75], v[204:207], v[148:151], v[72:75]
	v_mfma_f32_16x16x32_bf16 v[0:3], v[204:207], v[152:155], v[0:3]
	v_mfma_f32_16x16x32_bf16 v[8:11], v[204:207], v[156:159], v[8:11]
	s_waitcnt lgkmcnt(0)
	v_mfma_f32_16x16x32_bf16 v[68:71], v[242:245], v[144:147], v[68:71]
	v_mfma_f32_16x16x32_bf16 v[76:79], v[242:245], v[148:151], v[76:79]
	v_mfma_f32_16x16x32_bf16 v[4:7], v[242:245], v[152:155], v[4:7]
	v_mfma_f32_16x16x32_bf16 v[12:15], v[242:245], v[156:159], v[12:15]
	global_load_dwordx4 v[144:147], v[248:249], off
	global_load_dwordx4 v[148:151], v[248:249], off offset:256
	global_load_dwordx4 v[152:155], v[250:251], off
	global_load_dwordx4 v[156:159], v[250:251], off offset:256
	s_waitcnt vmcnt(10)
	s_barrier
	s_add_i32 s8, s8, 6
	s_cmp_lt_u32 s8, 84
	s_cbranch_scc1 .Lg16_down_k
	s_mov_b32 s96, 0xac000
	s_add_i32 m0, vcc_lo, 16384
	v_lshl_add_u64 v[160:161], v[188:189], 0, s[96:97]
	global_load_lds_dwordx4 v[160:161], off
	global_load_lds_dwordx4 v[160:161], off offset:1024
	ds_read_b128 v[196:199], v246 offset:0
	ds_read_b128 v[200:203], v162 offset:0
	ds_read_b128 v[204:207], v246 offset:2048
	ds_read_b128 v[242:245], v162 offset:2048
	s_mov_b32 s96, 0x2b000
	v_lshl_add_u64 v[248:249], v[184:185], 0, s[96:97]
	v_lshl_add_u64 v[250:251], v[186:187], 0, s[96:97]
	s_waitcnt vmcnt(8) lgkmcnt(3)
	v_mfma_f32_16x16x32_bf16 v[112:115], v[196:199], v[128:131], v[112:115]
	v_mfma_f32_16x16x32_bf16 v[120:123], v[196:199], v[132:135], v[120:123]
	v_mfma_f32_16x16x32_bf16 v[48:51], v[196:199], v[136:139], v[48:51]
	v_mfma_f32_16x16x32_bf16 v[56:59], v[196:199], v[140:143], v[56:59]
	ds_read_b128 v[196:199], v246 offset:4096
	s_waitcnt lgkmcnt(3)
	v_mfma_f32_16x16x32_bf16 v[116:119], v[200:203], v[128:131], v[116:119]
	v_mfma_f32_16x16x32_bf16 v[124:127], v[200:203], v[132:135], v[124:127]
	v_mfma_f32_16x16x32_bf16 v[52:55], v[200:203], v[136:139], v[52:55]
	v_mfma_f32_16x16x32_bf16 v[60:63], v[200:203], v[140:143], v[60:63]
	ds_read_b128 v[200:203], v162 offset:4096
	s_waitcnt lgkmcnt(3)
	v_mfma_f32_16x16x32_bf16 v[96:99], v[204:207], v[128:131], v[96:99]
	v_mfma_f32_16x16x32_bf16 v[104:107], v[204:207], v[132:135], v[104:107]
	v_mfma_f32_16x16x32_bf16 v[32:35], v[204:207], v[136:139], v[32:35]
	v_mfma_f32_16x16x32_bf16 v[40:43], v[204:207], v[140:143], v[40:43]
	ds_read_b128 v[204:207], v246 offset:6144
	s_waitcnt lgkmcnt(3)
	v_mfma_f32_16x16x32_bf16 v[100:103], v[242:245], v[128:131], v[100:103]
	v_mfma_f32_16x16x32_bf16 v[108:111], v[242:245], v[132:135], v[108:111]
	v_mfma_f32_16x16x32_bf16 v[36:39], v[242:245], v[136:139], v[36:39]
	v_mfma_f32_16x16x32_bf16 v[44:47], v[242:245], v[140:143], v[44:47]
	ds_read_b128 v[242:245], v162 offset:6144
	s_waitcnt lgkmcnt(3)
	v_mfma_f32_16x16x32_bf16 v[80:83], v[196:199], v[128:131], v[80:83]
	v_mfma_f32_16x16x32_bf16 v[88:91], v[196:199], v[132:135], v[88:91]
	v_mfma_f32_16x16x32_bf16 v[16:19], v[196:199], v[136:139], v[16:19]
	v_mfma_f32_16x16x32_bf16 v[24:27], v[196:199], v[140:143], v[24:27]
	s_waitcnt lgkmcnt(2)
	v_mfma_f32_16x16x32_bf16 v[84:87], v[200:203], v[128:131], v[84:87]
	v_mfma_f32_16x16x32_bf16 v[92:95], v[200:203], v[132:135], v[92:95]
	v_mfma_f32_16x16x32_bf16 v[20:23], v[200:203], v[136:139], v[20:23]
	v_mfma_f32_16x16x32_bf16 v[28:31], v[200:203], v[140:143], v[28:31]
	s_waitcnt lgkmcnt(1)
	v_mfma_f32_16x16x32_bf16 v[64:67], v[204:207], v[128:131], v[64:67]
	v_mfma_f32_16x16x32_bf16 v[72:75], v[204:207], v[132:135], v[72:75]
	v_mfma_f32_16x16x32_bf16 v[0:3], v[204:207], v[136:139], v[0:3]
	v_mfma_f32_16x16x32_bf16 v[8:11], v[204:207], v[140:143], v[8:11]
	s_waitcnt lgkmcnt(0)
	v_mfma_f32_16x16x32_bf16 v[68:71], v[242:245], v[128:131], v[68:71]
	v_mfma_f32_16x16x32_bf16 v[76:79], v[242:245], v[132:135], v[76:79]
	v_mfma_f32_16x16x32_bf16 v[4:7], v[242:245], v[136:139], v[4:7]
	v_mfma_f32_16x16x32_bf16 v[12:15], v[242:245], v[140:143], v[12:15]
	global_load_dwordx4 v[128:131], v[248:249], off
	global_load_dwordx4 v[132:135], v[248:249], off offset:256
	global_load_dwordx4 v[136:139], v[250:251], off
	global_load_dwordx4 v[140:143], v[250:251], off offset:256
	s_waitcnt vmcnt(10)
	s_barrier
	s_mov_b32 s96, 0xae000
	s_mov_b32 m0, vcc_lo
	v_lshl_add_u64 v[160:161], v[188:189], 0, s[96:97]
	global_load_lds_dwordx4 v[160:161], off
	global_load_lds_dwordx4 v[160:161], off offset:1024
	ds_read_b128 v[196:199], v246 offset:8192
	ds_read_b128 v[200:203], v162 offset:8192
	ds_read_b128 v[204:207], v246 offset:10240
	ds_read_b128 v[242:245], v162 offset:10240
	s_mov_b32 s96, 0x2b800
	v_lshl_add_u64 v[248:249], v[184:185], 0, s[96:97]
	v_lshl_add_u64 v[250:251], v[186:187], 0, s[96:97]
	s_waitcnt vmcnt(8) lgkmcnt(3)
	v_mfma_f32_16x16x32_bf16 v[112:115], v[196:199], v[144:147], v[112:115]
	v_mfma_f32_16x16x32_bf16 v[120:123], v[196:199], v[148:151], v[120:123]
	v_mfma_f32_16x16x32_bf16 v[48:51], v[196:199], v[152:155], v[48:51]
	v_mfma_f32_16x16x32_bf16 v[56:59], v[196:199], v[156:159], v[56:59]
	ds_read_b128 v[196:199], v246 offset:12288
	s_waitcnt lgkmcnt(3)
	v_mfma_f32_16x16x32_bf16 v[116:119], v[200:203], v[144:147], v[116:119]
	v_mfma_f32_16x16x32_bf16 v[124:127], v[200:203], v[148:151], v[124:127]
	v_mfma_f32_16x16x32_bf16 v[52:55], v[200:203], v[152:155], v[52:55]
	v_mfma_f32_16x16x32_bf16 v[60:63], v[200:203], v[156:159], v[60:63]
	ds_read_b128 v[200:203], v162 offset:12288
	s_waitcnt lgkmcnt(3)
	v_mfma_f32_16x16x32_bf16 v[96:99], v[204:207], v[144:147], v[96:99]
	v_mfma_f32_16x16x32_bf16 v[104:107], v[204:207], v[148:151], v[104:107]
	v_mfma_f32_16x16x32_bf16 v[32:35], v[204:207], v[152:155], v[32:35]
	v_mfma_f32_16x16x32_bf16 v[40:43], v[204:207], v[156:159], v[40:43]
	ds_read_b128 v[204:207], v246 offset:14336
	s_waitcnt lgkmcnt(3)
	v_mfma_f32_16x16x32_bf16 v[100:103], v[242:245], v[144:147], v[100:103]
	v_mfma_f32_16x16x32_bf16 v[108:111], v[242:245], v[148:151], v[108:111]
	v_mfma_f32_16x16x32_bf16 v[36:39], v[242:245], v[152:155], v[36:39]
	v_mfma_f32_16x16x32_bf16 v[44:47], v[242:245], v[156:159], v[44:47]
	ds_read_b128 v[242:245], v162 offset:14336
	s_waitcnt lgkmcnt(3)
	v_mfma_f32_16x16x32_bf16 v[80:83], v[196:199], v[144:147], v[80:83]
	v_mfma_f32_16x16x32_bf16 v[88:91], v[196:199], v[148:151], v[88:91]
	v_mfma_f32_16x16x32_bf16 v[16:19], v[196:199], v[152:155], v[16:19]
	v_mfma_f32_16x16x32_bf16 v[24:27], v[196:199], v[156:159], v[24:27]
	s_waitcnt lgkmcnt(2)
	v_mfma_f32_16x16x32_bf16 v[84:87], v[200:203], v[144:147], v[84:87]
	v_mfma_f32_16x16x32_bf16 v[92:95], v[200:203], v[148:151], v[92:95]
	v_mfma_f32_16x16x32_bf16 v[20:23], v[200:203], v[152:155], v[20:23]
	v_mfma_f32_16x16x32_bf16 v[28:31], v[200:203], v[156:159], v[28:31]
	s_waitcnt lgkmcnt(1)
	v_mfma_f32_16x16x32_bf16 v[64:67], v[204:207], v[144:147], v[64:67]
	v_mfma_f32_16x16x32_bf16 v[72:75], v[204:207], v[148:151], v[72:75]
	v_mfma_f32_16x16x32_bf16 v[0:3], v[204:207], v[152:155], v[0:3]
	v_mfma_f32_16x16x32_bf16 v[8:11], v[204:207], v[156:159], v[8:11]
	s_waitcnt lgkmcnt(0)
	v_mfma_f32_16x16x32_bf16 v[68:71], v[242:245], v[144:147], v[68:71]
	v_mfma_f32_16x16x32_bf16 v[76:79], v[242:245], v[148:151], v[76:79]
	v_mfma_f32_16x16x32_bf16 v[4:7], v[242:245], v[152:155], v[4:7]
	v_mfma_f32_16x16x32_bf16 v[12:15], v[242:245], v[156:159], v[12:15]
	global_load_dwordx4 v[144:147], v[248:249], off
	global_load_dwordx4 v[148:151], v[248:249], off offset:256
	global_load_dwordx4 v[152:155], v[250:251], off
	global_load_dwordx4 v[156:159], v[250:251], off offset:256
	s_waitcnt vmcnt(10)
	s_barrier
	ds_read_b128 v[196:199], v246 offset:16384
	ds_read_b128 v[200:203], v162 offset:16384
	ds_read_b128 v[204:207], v246 offset:18432
	ds_read_b128 v[242:245], v162 offset:18432
	s_waitcnt vmcnt(6) lgkmcnt(3)
	v_mfma_f32_16x16x32_bf16 v[112:115], v[196:199], v[128:131], v[112:115]
	v_mfma_f32_16x16x32_bf16 v[120:123], v[196:199], v[132:135], v[120:123]
	v_mfma_f32_16x16x32_bf16 v[48:51], v[196:199], v[136:139], v[48:51]
	v_mfma_f32_16x16x32_bf16 v[56:59], v[196:199], v[140:143], v[56:59]
	ds_read_b128 v[196:199], v246 offset:20480
	s_waitcnt lgkmcnt(3)
	v_mfma_f32_16x16x32_bf16 v[116:119], v[200:203], v[128:131], v[116:119]
	v_mfma_f32_16x16x32_bf16 v[124:127], v[200:203], v[132:135], v[124:127]
	v_mfma_f32_16x16x32_bf16 v[52:55], v[200:203], v[136:139], v[52:55]
	v_mfma_f32_16x16x32_bf16 v[60:63], v[200:203], v[140:143], v[60:63]
	ds_read_b128 v[200:203], v162 offset:20480
	s_waitcnt lgkmcnt(3)
	v_mfma_f32_16x16x32_bf16 v[96:99], v[204:207], v[128:131], v[96:99]
	v_mfma_f32_16x16x32_bf16 v[104:107], v[204:207], v[132:135], v[104:107]
	v_mfma_f32_16x16x32_bf16 v[32:35], v[204:207], v[136:139], v[32:35]
	v_mfma_f32_16x16x32_bf16 v[40:43], v[204:207], v[140:143], v[40:43]
	ds_read_b128 v[204:207], v246 offset:22528
	s_waitcnt lgkmcnt(3)
	v_mfma_f32_16x16x32_bf16 v[100:103], v[242:245], v[128:131], v[100:103]
	v_mfma_f32_16x16x32_bf16 v[108:111], v[242:245], v[132:135], v[108:111]
	v_mfma_f32_16x16x32_bf16 v[36:39], v[242:245], v[136:139], v[36:39]
	v_mfma_f32_16x16x32_bf16 v[44:47], v[242:245], v[140:143], v[44:47]
	ds_read_b128 v[242:245], v162 offset:22528
	s_waitcnt lgkmcnt(3)
	v_mfma_f32_16x16x32_bf16 v[80:83], v[196:199], v[128:131], v[80:83]
	v_mfma_f32_16x16x32_bf16 v[88:91], v[196:199], v[132:135], v[88:91]
	v_mfma_f32_16x16x32_bf16 v[16:19], v[196:199], v[136:139], v[16:19]
	v_mfma_f32_16x16x32_bf16 v[24:27], v[196:199], v[140:143], v[24:27]
	s_waitcnt lgkmcnt(2)
	v_mfma_f32_16x16x32_bf16 v[84:87], v[200:203], v[128:131], v[84:87]
	v_mfma_f32_16x16x32_bf16 v[92:95], v[200:203], v[132:135], v[92:95]
	v_mfma_f32_16x16x32_bf16 v[20:23], v[200:203], v[136:139], v[20:23]
	v_mfma_f32_16x16x32_bf16 v[28:31], v[200:203], v[140:143], v[28:31]
	s_waitcnt lgkmcnt(1)
	v_mfma_f32_16x16x32_bf16 v[64:67], v[204:207], v[128:131], v[64:67]
	v_mfma_f32_16x16x32_bf16 v[72:75], v[204:207], v[132:135], v[72:75]
	v_mfma_f32_16x16x32_bf16 v[0:3], v[204:207], v[136:139], v[0:3]
	v_mfma_f32_16x16x32_bf16 v[8:11], v[204:207], v[140:143], v[8:11]
	s_waitcnt lgkmcnt(0)
	v_mfma_f32_16x16x32_bf16 v[68:71], v[242:245], v[128:131], v[68:71]
	v_mfma_f32_16x16x32_bf16 v[76:79], v[242:245], v[132:135], v[76:79]
	v_mfma_f32_16x16x32_bf16 v[4:7], v[242:245], v[136:139], v[4:7]
	v_mfma_f32_16x16x32_bf16 v[12:15], v[242:245], v[140:143], v[12:15]
	s_waitcnt vmcnt(4)
	s_barrier
	ds_read_b128 v[196:199], v246 offset:0
	ds_read_b128 v[200:203], v162 offset:0
	ds_read_b128 v[204:207], v246 offset:2048
	ds_read_b128 v[242:245], v162 offset:2048
	s_waitcnt vmcnt(0) lgkmcnt(3)
	v_mfma_f32_16x16x32_bf16 v[112:115], v[196:199], v[144:147], v[112:115]
	v_mfma_f32_16x16x32_bf16 v[120:123], v[196:199], v[148:151], v[120:123]
	v_mfma_f32_16x16x32_bf16 v[48:51], v[196:199], v[152:155], v[48:51]
	v_mfma_f32_16x16x32_bf16 v[56:59], v[196:199], v[156:159], v[56:59]
	ds_read_b128 v[196:199], v246 offset:4096
	s_waitcnt lgkmcnt(3)
	v_mfma_f32_16x16x32_bf16 v[116:119], v[200:203], v[144:147], v[116:119]
	v_mfma_f32_16x16x32_bf16 v[124:127], v[200:203], v[148:151], v[124:127]
	v_mfma_f32_16x16x32_bf16 v[52:55], v[200:203], v[152:155], v[52:55]
	v_mfma_f32_16x16x32_bf16 v[60:63], v[200:203], v[156:159], v[60:63]
	ds_read_b128 v[200:203], v162 offset:4096
	s_waitcnt lgkmcnt(3)
	v_mfma_f32_16x16x32_bf16 v[96:99], v[204:207], v[144:147], v[96:99]
	v_mfma_f32_16x16x32_bf16 v[104:107], v[204:207], v[148:151], v[104:107]
	v_mfma_f32_16x16x32_bf16 v[32:35], v[204:207], v[152:155], v[32:35]
	v_mfma_f32_16x16x32_bf16 v[40:43], v[204:207], v[156:159], v[40:43]
	ds_read_b128 v[204:207], v246 offset:6144
	s_waitcnt lgkmcnt(3)
	v_mfma_f32_16x16x32_bf16 v[100:103], v[242:245], v[144:147], v[100:103]
	v_mfma_f32_16x16x32_bf16 v[108:111], v[242:245], v[148:151], v[108:111]
	v_mfma_f32_16x16x32_bf16 v[36:39], v[242:245], v[152:155], v[36:39]
	v_mfma_f32_16x16x32_bf16 v[44:47], v[242:245], v[156:159], v[44:47]
	ds_read_b128 v[242:245], v162 offset:6144
	s_waitcnt lgkmcnt(3)
	v_mfma_f32_16x16x32_bf16 v[80:83], v[196:199], v[144:147], v[80:83]
	v_mfma_f32_16x16x32_bf16 v[88:91], v[196:199], v[148:151], v[88:91]
	v_mfma_f32_16x16x32_bf16 v[16:19], v[196:199], v[152:155], v[16:19]
	v_mfma_f32_16x16x32_bf16 v[24:27], v[196:199], v[156:159], v[24:27]
	s_waitcnt lgkmcnt(2)
	v_mfma_f32_16x16x32_bf16 v[84:87], v[200:203], v[144:147], v[84:87]
	v_mfma_f32_16x16x32_bf16 v[92:95], v[200:203], v[148:151], v[92:95]
	v_mfma_f32_16x16x32_bf16 v[20:23], v[200:203], v[152:155], v[20:23]
	v_mfma_f32_16x16x32_bf16 v[28:31], v[200:203], v[156:159], v[28:31]
	s_waitcnt lgkmcnt(1)
	v_mfma_f32_16x16x32_bf16 v[64:67], v[204:207], v[144:147], v[64:67]
	v_mfma_f32_16x16x32_bf16 v[72:75], v[204:207], v[148:151], v[72:75]
	v_mfma_f32_16x16x32_bf16 v[0:3], v[204:207], v[152:155], v[0:3]
	v_mfma_f32_16x16x32_bf16 v[8:11], v[204:207], v[156:159], v[8:11]
	s_waitcnt lgkmcnt(0)
	v_mfma_f32_16x16x32_bf16 v[68:71], v[242:245], v[144:147], v[68:71]
	v_mfma_f32_16x16x32_bf16 v[76:79], v[242:245], v[148:151], v[76:79]
	v_mfma_f32_16x16x32_bf16 v[4:7], v[242:245], v[152:155], v[4:7]
	v_mfma_f32_16x16x32_bf16 v[12:15], v[242:245], v[156:159], v[12:15]
	s_barrier
	s_nop 7
	s_nop 1
	s_waitcnt vmcnt(0)
	s_waitcnt vmcnt(0)
	v_and_b32_e32 v188, 63, v179
	v_lshrrev_b32_e32 v189, 6, v179
	v_mul_u32_u24_e32 v249, 0x2400, v189
	v_mov_b32_e32 v250, v249
	v_and_b32_e32 v251, 15, v188
	v_mul_u32_u24_e32 v251, 0x110, v251
	v_add_u32_e32 v249, v249, v251
	v_lshrrev_b32_e32 v251, 4, v188
	v_lshl_add_u32 v249, v251, 5, v249
	v_lshrrev_b32_e32 v237, 4, v188
	v_mul_u32_u24_e32 v251, 0x110, v237
	v_add_u32_e32 v250, v250, v251
	v_and_b32_e32 v251, 15, v188
	v_lshlrev_b32_e32 v251, 4, v251
	v_add_u32_e32 v250, v250, v251
	v_lshl_add_u32 v237, v189, 6, v237
	v_lshl_add_u32 v237, v237, 12, v251
	v_add_u32_e32 v238, 16384, v237
	v_add_u32_e32 v239, 32768, v237
	v_add_u32_e32 v240, 49152, v237
	v_add_u32_e32 v241, 65536, v237
	v_add_u32_e32 v242, 81920, v237
	v_add_u32_e32 v243, 98304, v237
	v_add_u32_e32 v248, 114688, v237
	s_lshl_b32 s16, s7, 8
	s_lshl_b32 s18, s6, 9
	s_lshr_b32 s19, s7, 4
	v_readlane_b32 s12, v253, 46
	v_readlane_b32 s13, v253, 47
	v_readlane_b32 s14, v253, 46
	v_readlane_b32 s15, v253, 47
	s_add_i32 s17, s16, 0xffff8000
	s_cmpk_lt_u32 s7, 0x80
	s_cselect_b32 s12, s12, s62
	s_cselect_b32 s13, s13, s63
	s_cselect_b32 s14, s14, s62
	s_cselect_b32 s15, s15, s63
	s_cselect_b32 s19, s19, 8
	s_cselect_b32 s16, s16, s17
	s_mov_b32 s17, 0
	s_lshl_b64 s[16:17], s[16:17], 12
	s_add_u32 s16, s16, s18
	s_addc_u32 s17, s17, 0
	s_add_u32 s12, s12, s16
	s_addc_u32 s13, s13, s17
	s_add_u32 s14, s14, s16
	s_addc_u32 s15, s15, s17
	s_mul_i32 s19, s19, 0x6000
	s_add_u32 s20, s0, s19
	s_addc_u32 s21, s1, 0
	s_add_u32 s20, s20, s18
	s_addc_u32 s21, s21, 0
	global_load_dwordx4 v[244:247], v251, s[20:21]
	global_load_dwordx4 v[160:163], v237, s[12:13]
	global_load_dwordx4 v[164:167], v238, s[12:13]
	global_load_dwordx4 v[168:171], v239, s[12:13]
	global_load_dwordx4 v[172:175], v240, s[12:13]
	global_load_dwordx4 v[196:199], v241, s[12:13]
	global_load_dwordx4 v[200:203], v242, s[12:13]
	global_load_dwordx4 v[204:207], v243, s[12:13]
	global_load_dwordx4 v[184:187], v248, s[12:13]
	ds_write_b128 v249, v[112:115]
	ds_write_b128 v249, v[116:119] offset:16
	ds_write_b128 v249, v[96:99] offset:128
	ds_write_b128 v249, v[100:103] offset:144
	ds_write_b128 v249, v[120:123] offset:4352
	ds_write_b128 v249, v[124:127] offset:4368
	ds_write_b128 v249, v[104:107] offset:4480
	ds_write_b128 v249, v[108:111] offset:4496
	s_waitcnt lgkmcnt(0)
	ds_read_b128 v[128:131], v250
	ds_read_b128 v[132:135], v250 offset:1088
	ds_read_b128 v[136:139], v250 offset:2176
	ds_read_b128 v[140:143], v250 offset:3264
	ds_read_b128 v[144:147], v250 offset:4352
	ds_read_b128 v[148:151], v250 offset:5440
	ds_read_b128 v[152:155], v250 offset:6528
	ds_read_b128 v[156:159], v250 offset:7616
	s_waitcnt vmcnt(7) lgkmcnt(7)
	v_fma_f32 v128, v244, v128, v160
	v_fma_f32 v129, v245, v129, v161
	v_fma_f32 v130, v246, v130, v162
	v_fma_f32 v131, v247, v131, v163
	global_store_dwordx4 v237, v[128:131], s[14:15] sc0 sc1 nt
	s_waitcnt vmcnt(7) lgkmcnt(6)
	v_fma_f32 v132, v244, v132, v164
	v_fma_f32 v133, v245, v133, v165
	v_fma_f32 v134, v246, v134, v166
	v_fma_f32 v135, v247, v135, v167
	global_store_dwordx4 v238, v[132:135], s[14:15] sc0 sc1 nt
	s_waitcnt vmcnt(7) lgkmcnt(5)
	v_fma_f32 v136, v244, v136, v168
	v_fma_f32 v137, v245, v137, v169
	v_fma_f32 v138, v246, v138, v170
	v_fma_f32 v139, v247, v139, v171
	global_store_dwordx4 v239, v[136:139], s[14:15] sc0 sc1 nt
	s_waitcnt vmcnt(7) lgkmcnt(4)
	v_fma_f32 v140, v244, v140, v172
	v_fma_f32 v141, v245, v141, v173
	v_fma_f32 v142, v246, v142, v174
	v_fma_f32 v143, v247, v143, v175
	global_store_dwordx4 v240, v[140:143], s[14:15] sc0 sc1 nt
	s_waitcnt vmcnt(7) lgkmcnt(3)
	v_fma_f32 v144, v244, v144, v196
	v_fma_f32 v145, v245, v145, v197
	v_fma_f32 v146, v246, v146, v198
	v_fma_f32 v147, v247, v147, v199
	global_store_dwordx4 v241, v[144:147], s[14:15] sc0 sc1 nt
	s_waitcnt vmcnt(7) lgkmcnt(2)
	v_fma_f32 v148, v244, v148, v200
	v_fma_f32 v149, v245, v149, v201
	v_fma_f32 v150, v246, v150, v202
	v_fma_f32 v151, v247, v151, v203
	global_store_dwordx4 v242, v[148:151], s[14:15] sc0 sc1 nt
	s_waitcnt vmcnt(7) lgkmcnt(1)
	v_fma_f32 v152, v244, v152, v204
	v_fma_f32 v153, v245, v153, v205
	v_fma_f32 v154, v246, v154, v206
	v_fma_f32 v155, v247, v155, v207
	global_store_dwordx4 v243, v[152:155], s[14:15] sc0 sc1 nt
	s_waitcnt vmcnt(7) lgkmcnt(0)
	v_fma_f32 v156, v244, v156, v184
	v_fma_f32 v157, v245, v157, v185
	v_fma_f32 v158, v246, v158, v186
	v_fma_f32 v159, v247, v159, v187
	global_store_dwordx4 v248, v[156:159], s[14:15] sc0 sc1 nt
	global_load_dwordx4 v[244:247], v251, s[20:21] offset:256
	global_load_dwordx4 v[160:163], v237, s[12:13] offset:256
	global_load_dwordx4 v[164:167], v238, s[12:13] offset:256
	global_load_dwordx4 v[168:171], v239, s[12:13] offset:256
	global_load_dwordx4 v[172:175], v240, s[12:13] offset:256
	global_load_dwordx4 v[196:199], v241, s[12:13] offset:256
	global_load_dwordx4 v[200:203], v242, s[12:13] offset:256
	global_load_dwordx4 v[204:207], v243, s[12:13] offset:256
	global_load_dwordx4 v[184:187], v248, s[12:13] offset:256
	ds_write_b128 v249, v[80:83]
	ds_write_b128 v249, v[84:87] offset:16
	ds_write_b128 v249, v[64:67] offset:128
	ds_write_b128 v249, v[68:71] offset:144
	ds_write_b128 v249, v[88:91] offset:4352
	ds_write_b128 v249, v[92:95] offset:4368
	ds_write_b128 v249, v[72:75] offset:4480
	ds_write_b128 v249, v[76:79] offset:4496
	s_waitcnt lgkmcnt(0)
	ds_read_b128 v[128:131], v250
	ds_read_b128 v[132:135], v250 offset:1088
	ds_read_b128 v[136:139], v250 offset:2176
	ds_read_b128 v[140:143], v250 offset:3264
	ds_read_b128 v[144:147], v250 offset:4352
	ds_read_b128 v[148:151], v250 offset:5440
	ds_read_b128 v[152:155], v250 offset:6528
	ds_read_b128 v[156:159], v250 offset:7616
	s_waitcnt vmcnt(7) lgkmcnt(7)
	v_fma_f32 v128, v244, v128, v160
	v_fma_f32 v129, v245, v129, v161
	v_fma_f32 v130, v246, v130, v162
	v_fma_f32 v131, v247, v131, v163
	global_store_dwordx4 v237, v[128:131], s[14:15] offset:256 sc0 sc1 nt
	s_waitcnt vmcnt(7) lgkmcnt(6)
	v_fma_f32 v132, v244, v132, v164
	v_fma_f32 v133, v245, v133, v165
	v_fma_f32 v134, v246, v134, v166
	v_fma_f32 v135, v247, v135, v167
	global_store_dwordx4 v238, v[132:135], s[14:15] offset:256 sc0 sc1 nt
	s_waitcnt vmcnt(7) lgkmcnt(5)
	v_fma_f32 v136, v244, v136, v168
	v_fma_f32 v137, v245, v137, v169
	v_fma_f32 v138, v246, v138, v170
	v_fma_f32 v139, v247, v139, v171
	global_store_dwordx4 v239, v[136:139], s[14:15] offset:256 sc0 sc1 nt
	s_waitcnt vmcnt(7) lgkmcnt(4)
	v_fma_f32 v140, v244, v140, v172
	v_fma_f32 v141, v245, v141, v173
	v_fma_f32 v142, v246, v142, v174
	v_fma_f32 v143, v247, v143, v175
	global_store_dwordx4 v240, v[140:143], s[14:15] offset:256 sc0 sc1 nt
	s_waitcnt vmcnt(7) lgkmcnt(3)
	v_fma_f32 v144, v244, v144, v196
	v_fma_f32 v145, v245, v145, v197
	v_fma_f32 v146, v246, v146, v198
	v_fma_f32 v147, v247, v147, v199
	global_store_dwordx4 v241, v[144:147], s[14:15] offset:256 sc0 sc1 nt
	s_waitcnt vmcnt(7) lgkmcnt(2)
	v_fma_f32 v148, v244, v148, v200
	v_fma_f32 v149, v245, v149, v201
	v_fma_f32 v150, v246, v150, v202
	v_fma_f32 v151, v247, v151, v203
	global_store_dwordx4 v242, v[148:151], s[14:15] offset:256 sc0 sc1 nt
	s_waitcnt vmcnt(7) lgkmcnt(1)
	v_fma_f32 v152, v244, v152, v204
	v_fma_f32 v153, v245, v153, v205
	v_fma_f32 v154, v246, v154, v206
	v_fma_f32 v155, v247, v155, v207
	global_store_dwordx4 v243, v[152:155], s[14:15] offset:256 sc0 sc1 nt
	s_waitcnt vmcnt(7) lgkmcnt(0)
	v_fma_f32 v156, v244, v156, v184
	v_fma_f32 v157, v245, v157, v185
	v_fma_f32 v158, v246, v158, v186
	v_fma_f32 v159, v247, v159, v187
	global_store_dwordx4 v248, v[156:159], s[14:15] offset:256 sc0 sc1 nt
	s_add_u32 s12, s12, 0x20000
	s_addc_u32 s13, s13, 0
	s_add_u32 s14, s14, 0x20000
	s_addc_u32 s15, s15, 0
	global_load_dwordx4 v[244:247], v251, s[20:21]
	global_load_dwordx4 v[160:163], v237, s[12:13]
	global_load_dwordx4 v[164:167], v238, s[12:13]
	global_load_dwordx4 v[168:171], v239, s[12:13]
	global_load_dwordx4 v[172:175], v240, s[12:13]
	global_load_dwordx4 v[196:199], v241, s[12:13]
	global_load_dwordx4 v[200:203], v242, s[12:13]
	global_load_dwordx4 v[204:207], v243, s[12:13]
	global_load_dwordx4 v[184:187], v248, s[12:13]
	ds_write_b128 v249, v[48:51]
	ds_write_b128 v249, v[52:55] offset:16
	ds_write_b128 v249, v[32:35] offset:128
	ds_write_b128 v249, v[36:39] offset:144
	ds_write_b128 v249, v[56:59] offset:4352
	ds_write_b128 v249, v[60:63] offset:4368
	ds_write_b128 v249, v[40:43] offset:4480
	ds_write_b128 v249, v[44:47] offset:4496
	s_waitcnt lgkmcnt(0)
	ds_read_b128 v[128:131], v250
	ds_read_b128 v[132:135], v250 offset:1088
	ds_read_b128 v[136:139], v250 offset:2176
	ds_read_b128 v[140:143], v250 offset:3264
	ds_read_b128 v[144:147], v250 offset:4352
	ds_read_b128 v[148:151], v250 offset:5440
	ds_read_b128 v[152:155], v250 offset:6528
	ds_read_b128 v[156:159], v250 offset:7616
	s_waitcnt vmcnt(7) lgkmcnt(7)
	v_fma_f32 v128, v244, v128, v160
	v_fma_f32 v129, v245, v129, v161
	v_fma_f32 v130, v246, v130, v162
	v_fma_f32 v131, v247, v131, v163
	global_store_dwordx4 v237, v[128:131], s[14:15] sc0 sc1 nt
	s_waitcnt vmcnt(7) lgkmcnt(6)
	v_fma_f32 v132, v244, v132, v164
	v_fma_f32 v133, v245, v133, v165
	v_fma_f32 v134, v246, v134, v166
	v_fma_f32 v135, v247, v135, v167
	global_store_dwordx4 v238, v[132:135], s[14:15] sc0 sc1 nt
	s_waitcnt vmcnt(7) lgkmcnt(5)
	v_fma_f32 v136, v244, v136, v168
	v_fma_f32 v137, v245, v137, v169
	v_fma_f32 v138, v246, v138, v170
	v_fma_f32 v139, v247, v139, v171
	global_store_dwordx4 v239, v[136:139], s[14:15] sc0 sc1 nt
	s_waitcnt vmcnt(7) lgkmcnt(4)
	v_fma_f32 v140, v244, v140, v172
	v_fma_f32 v141, v245, v141, v173
	v_fma_f32 v142, v246, v142, v174
	v_fma_f32 v143, v247, v143, v175
	global_store_dwordx4 v240, v[140:143], s[14:15] sc0 sc1 nt
	s_waitcnt vmcnt(7) lgkmcnt(3)
	v_fma_f32 v144, v244, v144, v196
	v_fma_f32 v145, v245, v145, v197
	v_fma_f32 v146, v246, v146, v198
	v_fma_f32 v147, v247, v147, v199
	global_store_dwordx4 v241, v[144:147], s[14:15] sc0 sc1 nt
	s_waitcnt vmcnt(7) lgkmcnt(2)
	v_fma_f32 v148, v244, v148, v200
	v_fma_f32 v149, v245, v149, v201
	v_fma_f32 v150, v246, v150, v202
	v_fma_f32 v151, v247, v151, v203
	global_store_dwordx4 v242, v[148:151], s[14:15] sc0 sc1 nt
	s_waitcnt vmcnt(7) lgkmcnt(1)
	v_fma_f32 v152, v244, v152, v204
	v_fma_f32 v153, v245, v153, v205
	v_fma_f32 v154, v246, v154, v206
	v_fma_f32 v155, v247, v155, v207
	global_store_dwordx4 v243, v[152:155], s[14:15] sc0 sc1 nt
	s_waitcnt vmcnt(7) lgkmcnt(0)
	v_fma_f32 v156, v244, v156, v184
	v_fma_f32 v157, v245, v157, v185
	v_fma_f32 v158, v246, v158, v186
	v_fma_f32 v159, v247, v159, v187
	global_store_dwordx4 v248, v[156:159], s[14:15] sc0 sc1 nt
	global_load_dwordx4 v[244:247], v251, s[20:21] offset:256
	global_load_dwordx4 v[160:163], v237, s[12:13] offset:256
	global_load_dwordx4 v[164:167], v238, s[12:13] offset:256
	global_load_dwordx4 v[168:171], v239, s[12:13] offset:256
	global_load_dwordx4 v[172:175], v240, s[12:13] offset:256
	global_load_dwordx4 v[196:199], v241, s[12:13] offset:256
	global_load_dwordx4 v[200:203], v242, s[12:13] offset:256
	global_load_dwordx4 v[204:207], v243, s[12:13] offset:256
	global_load_dwordx4 v[184:187], v248, s[12:13] offset:256
	ds_write_b128 v249, v[16:19]
	ds_write_b128 v249, v[20:23] offset:16
	ds_write_b128 v249, v[0:3] offset:128
	ds_write_b128 v249, v[4:7] offset:144
	ds_write_b128 v249, v[24:27] offset:4352
	ds_write_b128 v249, v[28:31] offset:4368
	ds_write_b128 v249, v[8:11] offset:4480
	ds_write_b128 v249, v[12:15] offset:4496
	s_waitcnt lgkmcnt(0)
	ds_read_b128 v[128:131], v250
	ds_read_b128 v[132:135], v250 offset:1088
	ds_read_b128 v[136:139], v250 offset:2176
	ds_read_b128 v[140:143], v250 offset:3264
	ds_read_b128 v[144:147], v250 offset:4352
	ds_read_b128 v[148:151], v250 offset:5440
	ds_read_b128 v[152:155], v250 offset:6528
	ds_read_b128 v[156:159], v250 offset:7616
	s_waitcnt vmcnt(7) lgkmcnt(7)
	v_fma_f32 v128, v244, v128, v160
	v_fma_f32 v129, v245, v129, v161
	v_fma_f32 v130, v246, v130, v162
	v_fma_f32 v131, v247, v131, v163
	global_store_dwordx4 v237, v[128:131], s[14:15] offset:256 sc0 sc1 nt
	s_waitcnt vmcnt(7) lgkmcnt(6)
	v_fma_f32 v132, v244, v132, v164
	v_fma_f32 v133, v245, v133, v165
	v_fma_f32 v134, v246, v134, v166
	v_fma_f32 v135, v247, v135, v167
	global_store_dwordx4 v238, v[132:135], s[14:15] offset:256 sc0 sc1 nt
	s_waitcnt vmcnt(7) lgkmcnt(5)
	v_fma_f32 v136, v244, v136, v168
	v_fma_f32 v137, v245, v137, v169
	v_fma_f32 v138, v246, v138, v170
	v_fma_f32 v139, v247, v139, v171
	global_store_dwordx4 v239, v[136:139], s[14:15] offset:256 sc0 sc1 nt
	s_waitcnt vmcnt(7) lgkmcnt(4)
	v_fma_f32 v140, v244, v140, v172
	v_fma_f32 v141, v245, v141, v173
	v_fma_f32 v142, v246, v142, v174
	v_fma_f32 v143, v247, v143, v175
	global_store_dwordx4 v240, v[140:143], s[14:15] offset:256 sc0 sc1 nt
	s_waitcnt vmcnt(7) lgkmcnt(3)
	v_fma_f32 v144, v244, v144, v196
	v_fma_f32 v145, v245, v145, v197
	v_fma_f32 v146, v246, v146, v198
	v_fma_f32 v147, v247, v147, v199
	global_store_dwordx4 v241, v[144:147], s[14:15] offset:256 sc0 sc1 nt
	s_waitcnt vmcnt(7) lgkmcnt(2)
	v_fma_f32 v148, v244, v148, v200
	v_fma_f32 v149, v245, v149, v201
	v_fma_f32 v150, v246, v150, v202
	v_fma_f32 v151, v247, v151, v203
	global_store_dwordx4 v242, v[148:151], s[14:15] offset:256 sc0 sc1 nt
	s_waitcnt vmcnt(7) lgkmcnt(1)
	v_fma_f32 v152, v244, v152, v204
	v_fma_f32 v153, v245, v153, v205
	v_fma_f32 v154, v246, v154, v206
	v_fma_f32 v155, v247, v155, v207
	global_store_dwordx4 v243, v[152:155], s[14:15] offset:256 sc0 sc1 nt
	s_waitcnt vmcnt(7) lgkmcnt(0)
	v_fma_f32 v156, v244, v156, v184
	v_fma_f32 v157, v245, v157, v185
	v_fma_f32 v158, v246, v158, v186
	v_fma_f32 v159, v247, v159, v187
	global_store_dwordx4 v248, v[156:159], s[14:15] offset:256 sc0 sc1 nt
	s_waitcnt lgkmcnt(0)
	v_readlane_b32 s16, v254, 11
	s_andn2_b32 s17, s26, 63
	s_add_i32 s2, s2, s16
	s_cmp_lt_i32 s2, s17
	s_cbranch_scc0 .Lhx_down_left
	s_barrier
	s_branch .LBB0_1086
